# out-proj/down residual epilogues: hi-part stores re-paired with permlane16/32 swaps so each store instruction writes 64 contiguous bytes per row; on top of v18
# speedup vs baseline: 1.0058x; 1.0058x over previous
; __device__ __forceinline__ u32x4 pack8(f32x4 a, f32x4 b) { u32x4 w; w.x = cvt_pk_bf16(a[0], a[1]); w.y = cvt_pk_bf16(a[2], a[3]); w.z = cvt_pk_bf16(b[0], b[1]); w.w = cvt_pk_bf16(b[2], b[3]); return w; }
;     __device__ __forceinline__ void operator()(const f32x4 (&acc)[2][2][4][2], const Unit& u, int wr, int wc, int fr_, int fq_) const {
;     ...
;         const size_t off0 = (size_t)(u.pm * 256 + wr * 64 + fr) * 1024 + 256 * u.pn + 64 * wc + 16 * fq;
;         u32x4 h0[2][2], h1[2][2], lw[2][2];
; #pragma unroll
;         for (int k = 0; k < 6; ++k) {
;             if (k >= 2) {
; #pragma unroll
;                 for (int j = 0; j < 2; ++j) {
;                     const int kb = k - 2, ai = kb >> 1, m = (kb & 1) * 2 + j;
;                     const size_t off = off0 + (size_t)(ai * 128 + m * 16) * 1024;
;                     u32x4 lo_out; float ss = 0.f;
; #pragma unroll
;                     for (int bj = 0; bj < 2; ++bj) {
;                         f32x4 a, b; unpack8(bj ? h1[k & 1][j] : h0[k & 1][j], a, b);
; #pragma unroll
;                         for (int i = 0; i < 4; ++i) { a[i] += lo_dec(lw[k & 1][j][2 * bj], i); b[i] += lo_dec(lw[k & 1][j][2 * bj + 1], i); }
;                         a = a + acc[ai][bj][m][0]; b = b + acc[ai][bj][m][1];
;                         const u32x4 hw = pack8(a, b);
;                         *(u32x4*)(XH + off + 8 * bj) = hw;
;                         f32x4 ra, rb; unpack8(hw, ra, rb);
;                         lo_out[2 * bj] = lo_enc(a - ra); lo_out[2 * bj + 1] = lo_enc(b - rb);
;                         ss += ((a[0] * a[0] + a[1] * a[1]) + (a[2] * a[2] + a[3] * a[3])) + ((b[0] * b[0] + b[1] * b[1]) + (b[2] * b[2] + b[3] * b[3]));
;                     }
;                     *(u32x4*)(XL + off) = lo_out;
;                     ss += __shfl_xor(ss, 16); ss += __shfl_xor(ss, 32);
;                     if (fq == 0) SSo[(size_t)(u.pm * 256 + ai * 128 + wr * 64 + m * 16 + fr) * 16 + 4 * u.pn + wc] = ss;
;                 }
;             }
;             if (k < 4) {
; #pragma unroll
;                 for (int j = 0; j < 2; ++j) {
;                     const int ai = k >> 1, m = (k & 1) * 2 + j;
;                     const size_t off = off0 + (size_t)(ai * 128 + m * 16) * 1024;
;                     h0[k & 1][j] = *(const u32x4*)(XH + off); h1[k & 1][j] = *(const u32x4*)(XH + off + 8); lw[k & 1][j] = *(const u32x4*)(XL + off);
.LBB0_80:
	v_lshlrev_b32_e32 v232, 4, v185
	v_sub_u32_e32 v232, 0, v232
	v_ashrrev_i32_e32 v233, 31, v232
	s_lshl_b32 s2, s40, 8
	v_mov_b32_e32 v98, v184
	v_mov_b32_e32 v106, v185
	s_add_i32 s2, s2, s73
	s_lshl_b32 s30, s36, 8
	s_ashr_i32 s31, s30, 31
	v_add_u32_e32 v172, s2, v98
	v_lshlrev_b32_e32 v100, 4, v106
	v_ashrrev_i32_e32 v173, 31, v172
	v_ashrrev_i32_e32 v101, 31, v100
	s_or_b64 s[30:31], s[30:31], s[52:53]
	v_lshlrev_b64 v[98:99], 10, v[172:173]
	v_lshl_add_u64 v[100:101], s[30:31], 0, v[100:101]
	v_readlane_b32 s30, v253, 11
	v_lshl_add_u64 v[98:99], v[100:101], 0, v[98:99]
	v_readlane_b32 s31, v253, 12
	s_mov_b32 s23, 0x8000
	s_movk_i32 s2, 0x4000
	v_lshl_add_u64 v[174:175], s[30:31], 0, v[98:99]
	v_readlane_b32 s30, v253, 9
	v_readlane_b32 s31, v253, 10
	global_load_dwordx4 v[188:191], v[174:175], off
	v_cmp_eq_u32_e64 s[40:41], 0, v106
	v_lshl_add_u64 v[176:177], v[98:99], 1, s[30:31]
	global_load_dwordx4 v[192:195], v[176:177], off
	global_load_dwordx4 v[196:199], v[176:177], off offset:16
	v_add_co_u32_e32 v98, vcc, s23, v176
	s_mov_b64 s[30:31], 0x8000
	s_nop 0
	v_addc_co_u32_e32 v99, vcc, 0, v177, vcc
	v_add_co_u32_e32 v100, vcc, s2, v174
	s_mov_b32 s2, 0x10000
	s_nop 0
	v_addc_co_u32_e32 v101, vcc, 0, v175, vcc
	v_add_co_u32_e32 v106, vcc, s2, v176
	s_mov_b32 s2, 0x18000
	s_nop 0
	v_addc_co_u32_e32 v107, vcc, 0, v177, vcc
	v_add_co_u32_e32 v108, vcc, s23, v174
	v_lshl_add_u64 v[182:183], v[176:177], 0, s[30:31]
	s_nop 0
	v_addc_co_u32_e32 v109, vcc, 0, v175, vcc
	v_add_co_u32_e32 v114, vcc, s2, v176
	s_mov_b32 s2, 0xc000
	s_nop 0
	v_addc_co_u32_e32 v115, vcc, 0, v177, vcc
	s_mov_b64 s[30:31], 0x18000
	v_add_co_u32_e32 v200, vcc, s2, v174
	v_lshl_add_u64 v[180:181], v[176:177], 0, s[28:29]
	v_lshl_add_u64 v[178:179], v[176:177], 0, s[30:31]
	v_addc_co_u32_e32 v201, vcc, 0, v175, vcc
	global_load_dwordx4 v[154:157], v[182:183], off offset:16
	global_load_dwordx4 v[162:165], v[98:99], off
	global_load_dwordx4 v[158:161], v[100:101], off
	global_load_dwordx4 v[142:145], v[106:107], off
	global_load_dwordx4 v[126:129], v[108:109], off
	global_load_dwordx4 v[130:133], v[180:181], off offset:16
	s_nop 0
	global_load_dwordx4 v[98:101], v[178:179], off offset:16
	s_nop 0
	global_load_dwordx4 v[114:117], v[114:115], off
	s_nop 0
	global_load_dwordx4 v[106:109], v[200:201], off
	s_lshl_b32 s62, s36, 2
	s_ashr_i32 s63, s62, 31
	s_waitcnt vmcnt(0)
	v_cvt_f32_fp8_e32 v200, v188
	v_cvt_f32_fp8_e32 v204, v189
	v_cvt_f32_fp8_sdwa v201, v188 src0_sel:BYTE_1
	v_cvt_f32_fp8_sdwa v205, v189 src0_sel:BYTE_1
	v_lshlrev_b32_e32 v208, 16, v192
	v_and_b32_e32 v209, 0xffff0000, v192
	v_cvt_f32_fp8_sdwa v212, v188 src0_sel:BYTE_2
	v_cvt_f32_fp8_sdwa v192, v189 src0_sel:BYTE_2
	v_cvt_f32_fp8_sdwa v213, v188 src0_sel:BYTE_3
	v_lshlrev_b32_e32 v214, 16, v193
	v_and_b32_e32 v215, 0xffff0000, v193
	v_cvt_f32_fp8_sdwa v193, v189 src0_sel:BYTE_3
	v_lshlrev_b32_e32 v210, 16, v194
	v_and_b32_e32 v211, 0xffff0000, v194
	v_lshlrev_b32_e32 v188, 16, v195
	v_and_b32_e32 v189, 0xffff0000, v195
	v_pk_fma_f32 v[194:195], v[200:201], s[22:23], v[208:209] op_sel_hi:[1,0,1]
	v_pk_fma_f32 v[200:201], v[204:205], s[22:23], v[210:211] op_sel_hi:[1,0,1]
	v_pk_fma_f32 v[204:205], v[212:213], s[22:23], v[214:215] op_sel_hi:[1,0,1]
	v_pk_fma_f32 v[188:189], v[192:193], s[22:23], v[188:189] op_sel_hi:[1,0,1]
	v_pk_add_f32 v[150:151], v[150:151], v[194:195]
	v_pk_add_f32 v[192:193], v[146:147], v[200:201]
	v_cvt_pk_bf16_f32 v146, v150, v151
	v_pk_add_f32 v[152:153], v[152:153], v[204:205]
	v_pk_add_f32 v[188:189], v[148:149], v[188:189]
	v_cvt_pk_bf16_f32 v147, v152, v153
	v_cvt_pk_bf16_f32 v148, v192, v193
	v_lshlrev_b32_e32 v194, 16, v146
	v_cvt_pk_bf16_f32 v149, v188, v189
	v_mov_b32_e32 v222, v146
	v_mov_b32_e32 v223, v147
	v_mov_b32_e32 v224, v148
	v_mov_b32_e32 v225, v149
	v_sub_f32_e32 v194, v150, v194
	v_mul_f32_e32 v194, 0x45800000, v194
	v_and_b32_e32 v146, 0xffff0000, v146
	v_sub_f32_e32 v146, v151, v146
	v_mul_f32_e32 v146, 0x45800000, v146
	v_med3_f32 v194, v194, s3, v206
	v_med3_f32 v204, v146, s3, v206
	v_mov_b32_e32 v146, v1
	v_lshlrev_b32_e32 v195, 16, v147
	v_and_b32_e32 v147, 0xffff0000, v147
	v_cvt_pk_fp8_f32 v146, v194, v204
	v_sub_f32_e32 v147, v153, v147
	v_sub_f32_e32 v195, v152, v195
	v_mul_f32_e32 v195, 0x45800000, v195
	v_mul_f32_e32 v147, 0x45800000, v147
	v_lshlrev_b32_e32 v200, 16, v148
	v_and_b32_e32 v148, 0xffff0000, v148
	v_med3_f32 v194, v195, s3, v206
	v_med3_f32 v147, v147, s3, v206
	v_lshlrev_b32_e32 v201, 16, v149
	v_cvt_pk_fp8_f32 v146, v194, v147 op_sel:[0,0,1]
	v_sub_f32_e32 v148, v193, v148
	v_sub_f32_e32 v194, v192, v200
	v_sub_f32_e32 v147, v188, v201
	v_mul_f32_e32 v194, 0x45800000, v194
	v_mul_f32_e32 v148, 0x45800000, v148
	v_med3_f32 v194, v194, s3, v206
	v_med3_f32 v148, v148, s3, v206
	v_mul_f32_e32 v195, 0x45800000, v147
	v_mov_b32_e32 v147, v1
	v_and_b32_e32 v149, 0xffff0000, v149
	v_cvt_pk_fp8_f32 v147, v194, v148
	v_sub_f32_e32 v149, v189, v149
	v_mul_f32_e32 v149, 0x45800000, v149
	v_med3_f32 v148, v195, s3, v206
	v_med3_f32 v149, v149, s3, v206
	v_cvt_pk_fp8_f32 v147, v148, v149 op_sel:[0,0,1]
	v_mul_f32_e32 v148, v151, v151
	v_mul_f32_e32 v149, v153, v153
	v_fmac_f32_e32 v148, v150, v150
	v_fmac_f32_e32 v149, v152, v152
	v_add_f32_e32 v148, v148, v149
	v_mul_f32_e32 v149, v193, v193
	v_mul_f32_e32 v150, v189, v189
	v_fmac_f32_e32 v149, v192, v192
	v_fmac_f32_e32 v150, v188, v188
	v_add_f32_e32 v149, v149, v150
	v_add_f32_e32 v194, v148, v149
	v_cvt_f32_fp8_e32 v148, v190
	v_cvt_f32_fp8_sdwa v149, v190 src0_sel:BYTE_1
	v_cvt_f32_fp8_e32 v150, v191
	v_cvt_f32_fp8_sdwa v151, v191 src0_sel:BYTE_1
	v_lshlrev_b32_e32 v152, 16, v196
; __device__ __forceinline__ u32x4 pack8(f32x4 a, f32x4 b) { u32x4 w; w.x = cvt_pk_bf16(a[0], a[1]); w.y = cvt_pk_bf16(a[2], a[3]); w.z = cvt_pk_bf16(b[0], b[1]); w.w = cvt_pk_bf16(b[2], b[3]); return w; }
; __device__ __forceinline__ void unpack8(u32x4 w, f32x4& a, f32x4& b) { a = (f32x4){bf_lo(w.x), bf_hi(w.x), bf_lo(w.y), bf_hi(w.y)}; b = (f32x4){bf_lo(w.z), bf_hi(w.z), bf_lo(w.w), bf_hi(w.w)}; }
; __device__ __forceinline__ float lo_dec(unsigned w, int i) { return (i == 0 ? __builtin_amdgcn_cvt_f32_fp8(w, 0) : i == 1 ? __builtin_amdgcn_cvt_f32_fp8(w, 1) : i == 2 ? __builtin_amdgcn_cvt_f32_fp8(w, 2) : __builtin_amdgcn_cvt_f32_fp8(w, 3)) * (1.0f / 4096.0f); }
;     __device__ __forceinline__ void operator()(const f32x4 (&acc)[2][2][4][2], const Unit& u, int wr, int wc, int fr_, int fq_) const {
;     ...
;                     u32x4 lo_out; float ss = 0.f;
; #pragma unroll
;                     for (int bj = 0; bj < 2; ++bj) {
;                         f32x4 a, b; unpack8(bj ? h1[k & 1][j] : h0[k & 1][j], a, b);
; #pragma unroll
;                         for (int i = 0; i < 4; ++i) { a[i] += lo_dec(lw[k & 1][j][2 * bj], i); b[i] += lo_dec(lw[k & 1][j][2 * bj + 1], i); }
;                         a = a + acc[ai][bj][m][0]; b = b + acc[ai][bj][m][1];
;                         const u32x4 hw = pack8(a, b);
;                         *(u32x4*)(XH + off + 8 * bj) = hw;
;                         f32x4 ra, rb; unpack8(hw, ra, rb);
;                         lo_out[2 * bj] = lo_enc(a - ra); lo_out[2 * bj + 1] = lo_enc(b - rb);
;                         ss += ((a[0] * a[0] + a[1] * a[1]) + (a[2] * a[2] + a[3] * a[3])) + ((b[0] * b[0] + b[1] * b[1]) + (b[2] * b[2] + b[3] * b[3]));
;                     }
;                     *(u32x4*)(XL + off) = lo_out;
;                     ss += __shfl_xor(ss, 16); ss += __shfl_xor(ss, 32);
;                     if (fq == 0) SSo[(size_t)(u.pm * 256 + ai * 128 + wr * 64 + m * 16 + fr) * 16 + 4 * u.pn + wc] = ss;
	v_and_b32_e32 v153, 0xffff0000, v196
	v_pk_fma_f32 v[148:149], v[148:149], s[22:23], v[152:153] op_sel_hi:[1,0,1]
	v_lshlrev_b32_e32 v152, 16, v198
	v_and_b32_e32 v153, 0xffff0000, v198
	v_pk_fma_f32 v[150:151], v[150:151], s[22:23], v[152:153] op_sel_hi:[1,0,1]
	v_cvt_f32_fp8_sdwa v152, v190 src0_sel:BYTE_2
	v_cvt_f32_fp8_sdwa v188, v191 src0_sel:BYTE_2
	v_cvt_f32_fp8_sdwa v153, v190 src0_sel:BYTE_3
	v_cvt_f32_fp8_sdwa v189, v191 src0_sel:BYTE_3
	v_lshlrev_b32_e32 v192, 16, v197
	v_and_b32_e32 v193, 0xffff0000, v197
	v_lshlrev_b32_e32 v190, 16, v199
	v_and_b32_e32 v191, 0xffff0000, v199
	v_pk_fma_f32 v[152:153], v[152:153], s[22:23], v[192:193] op_sel_hi:[1,0,1]
	v_pk_fma_f32 v[188:189], v[188:189], s[22:23], v[190:191] op_sel_hi:[1,0,1]
	v_pk_add_f32 v[140:141], v[140:141], v[152:153]
	v_pk_add_f32 v[152:153], v[138:139], v[148:149]
	v_pk_add_f32 v[188:189], v[136:137], v[188:189]
	v_cvt_pk_bf16_f32 v136, v152, v153
	v_pk_add_f32 v[134:135], v[134:135], v[150:151]
	v_lshlrev_b32_e32 v148, 16, v136
	v_and_b32_e32 v149, 0xffff0000, v136
	v_sub_f32_e32 v148, v152, v148
	v_sub_f32_e32 v149, v153, v149
	v_mul_f32_e32 v148, 0x45800000, v148
	v_med3_f32 v195, v148, s3, v206
	v_mul_f32_e32 v148, 0x45800000, v149
	v_cvt_pk_bf16_f32 v137, v140, v141
	v_med3_f32 v149, v148, s3, v206
	v_lshlrev_b32_e32 v150, 16, v137
	v_mov_b32_e32 v148, v1
	v_and_b32_e32 v151, 0xffff0000, v137
	v_sub_f32_e32 v150, v140, v150
	v_cvt_pk_fp8_f32 v148, v195, v149
	v_sub_f32_e32 v151, v141, v151
	v_mul_f32_e32 v150, 0x45800000, v150
	v_med3_f32 v149, v150, s3, v206
	v_mul_f32_e32 v150, 0x45800000, v151
	v_cvt_pk_bf16_f32 v138, v134, v135
	v_med3_f32 v150, v150, s3, v206
	v_lshlrev_b32_e32 v190, 16, v138
	v_and_b32_e32 v191, 0xffff0000, v138
	v_cvt_pk_bf16_f32 v139, v188, v189
	v_cvt_pk_fp8_f32 v148, v149, v150 op_sel:[0,0,1]
	v_lshlrev_b32_e32 v192, 16, v139
	v_sub_f32_e32 v150, v135, v191
	v_sub_f32_e32 v190, v134, v190
	v_sub_f32_e32 v149, v188, v192
	v_mul_f32_e32 v190, 0x45800000, v190
	v_mul_f32_e32 v150, 0x45800000, v150
	v_med3_f32 v190, v190, s3, v206
	v_med3_f32 v150, v150, s3, v206
	v_mul_f32_e32 v191, 0x45800000, v149
	v_mov_b32_e32 v149, v1
	v_mul_f32_e32 v135, v135, v135
	v_cvt_pk_fp8_f32 v149, v190, v150
	v_mul_f32_e32 v150, v153, v153
	v_mul_f32_e32 v141, v141, v141
	v_fmac_f32_e32 v135, v134, v134
	v_mul_f32_e32 v134, v189, v189
	v_fmac_f32_e32 v150, v152, v152
	v_fmac_f32_e32 v141, v140, v140
	v_fmac_f32_e32 v134, v188, v188
	v_add_f32_e32 v140, v150, v141
	v_add_f32_e32 v134, v135, v134
	v_add_f32_e32 v134, v140, v134
	v_and_b32_e32 v140, 64, v203
	v_xor_b32_e32 v135, 16, v203
	v_add_u32_e32 v140, 64, v140
	v_cmp_lt_i32_e32 vcc, v135, v140
	v_add_f32_e32 v134, v194, v134
	v_and_b32_e32 v193, 0xffff0000, v139
	v_cndmask_b32_e32 v135, v203, v135, vcc
	v_lshlrev_b32_e32 v150, 2, v135
	ds_bpermute_b32 v135, v150, v134
	v_sub_f32_e32 v151, v189, v193
	v_mul_f32_e32 v151, 0x45800000, v151
	v_med3_f32 v141, v191, s3, v206
	v_med3_f32 v151, v151, s3, v206
	s_waitcnt lgkmcnt(0)
	v_add_f32_e32 v134, v134, v135
	v_xor_b32_e32 v135, 32, v203
	v_cmp_lt_i32_e32 vcc, v135, v140
	v_cvt_pk_fp8_f32 v149, v141, v151 op_sel:[0,0,1]
	v_mov_b32_e32 v226, v136
	v_mov_b32_e32 v227, v137
	v_mov_b32_e32 v228, v138
	v_mov_b32_e32 v229, v139
	s_nop 1
	v_permlane16_swap_b32_e32 v222, v226
	v_permlane16_swap_b32_e32 v223, v227
	v_permlane16_swap_b32_e32 v224, v228
	v_permlane16_swap_b32_e32 v225, v229
	v_permlane32_swap_b32_e32 v222, v226
	v_permlane32_swap_b32_e32 v223, v227
	v_permlane32_swap_b32_e32 v224, v228
	v_permlane32_swap_b32_e32 v225, v229
	v_lshl_add_u64 v[230:231], v[176:177], 0, v[232:233]
	global_store_dwordx4 v[230:231], v[222:225], off
	global_store_dwordx4 v[230:231], v[226:229], off offset:64
	global_store_dwordx4 v[174:175], v[146:149], off
	v_cndmask_b32_e32 v135, v203, v135, vcc
	v_lshlrev_b32_e32 v151, 2, v135
	ds_bpermute_b32 v135, v151, v134
	s_and_saveexec_b64 s[36:37], s[40:41]
	s_cbranch_execz .LBB0_82
	v_lshlrev_b64 v[136:137], 6, v[172:173]
	v_lshl_add_u64 v[136:137], s[46:47], 0, v[136:137]
	v_lshl_add_u64 v[136:137], s[62:63], 2, v[136:137]
	s_lshl_b32 s24, s72, 2
	v_lshl_add_u64 v[136:137], v[136:137], 0, s[24:25]
	s_waitcnt lgkmcnt(0)
	v_add_f32_e32 v134, v134, v135
	global_store_dword v[136:137], v134, off
; __device__ __forceinline__ u32x4 pack8(f32x4 a, f32x4 b) { u32x4 w; w.x = cvt_pk_bf16(a[0], a[1]); w.y = cvt_pk_bf16(a[2], a[3]); w.z = cvt_pk_bf16(b[0], b[1]); w.w = cvt_pk_bf16(b[2], b[3]); return w; }
; __device__ __forceinline__ void unpack8(u32x4 w, f32x4& a, f32x4& b) { a = (f32x4){bf_lo(w.x), bf_hi(w.x), bf_lo(w.y), bf_hi(w.y)}; b = (f32x4){bf_lo(w.z), bf_hi(w.z), bf_lo(w.w), bf_hi(w.w)}; }
; __device__ __forceinline__ float lo_dec(unsigned w, int i) { return (i == 0 ? __builtin_amdgcn_cvt_f32_fp8(w, 0) : i == 1 ? __builtin_amdgcn_cvt_f32_fp8(w, 1) : i == 2 ? __builtin_amdgcn_cvt_f32_fp8(w, 2) : __builtin_amdgcn_cvt_f32_fp8(w, 3)) * (1.0f / 4096.0f); }
;     __device__ __forceinline__ void operator()(const f32x4 (&acc)[2][2][4][2], const Unit& u, int wr, int wc, int fr_, int fq_) const {
;     ...
;                     u32x4 lo_out; float ss = 0.f;
; #pragma unroll
;                     for (int bj = 0; bj < 2; ++bj) {
;                         f32x4 a, b; unpack8(bj ? h1[k & 1][j] : h0[k & 1][j], a, b);
; #pragma unroll
;                         for (int i = 0; i < 4; ++i) { a[i] += lo_dec(lw[k & 1][j][2 * bj], i); b[i] += lo_dec(lw[k & 1][j][2 * bj + 1], i); }
;                         a = a + acc[ai][bj][m][0]; b = b + acc[ai][bj][m][1];
;                         const u32x4 hw = pack8(a, b);
;                         *(u32x4*)(XH + off + 8 * bj) = hw;
;                         f32x4 ra, rb; unpack8(hw, ra, rb);
;                         lo_out[2 * bj] = lo_enc(a - ra); lo_out[2 * bj + 1] = lo_enc(b - rb);
;                         ss += ((a[0] * a[0] + a[1] * a[1]) + (a[2] * a[2] + a[3] * a[3])) + ((b[0] * b[0] + b[1] * b[1]) + (b[2] * b[2] + b[3] * b[3]));
;                     }
;                     *(u32x4*)(XL + off) = lo_out;
;                     ss += __shfl_xor(ss, 16); ss += __shfl_xor(ss, 32);
;                     if (fq == 0) SSo[(size_t)(u.pm * 256 + ai * 128 + wr * 64 + m * 16 + fr) * 16 + 4 * u.pn + wc] = ss;
.LBB0_82:
	s_or_b64 exec, exec, s[36:37]
	v_cvt_f32_fp8_e32 v134, v158
	s_waitcnt lgkmcnt(0)
	v_cvt_f32_fp8_sdwa v135, v158 src0_sel:BYTE_1
	v_cvt_f32_fp8_e32 v136, v159
	v_cvt_f32_fp8_sdwa v137, v159 src0_sel:BYTE_1
	v_lshlrev_b32_e32 v138, 16, v162
	v_and_b32_e32 v139, 0xffff0000, v162
	v_pk_fma_f32 v[134:135], v[134:135], s[22:23], v[138:139] op_sel_hi:[1,0,1]
	v_lshlrev_b32_e32 v138, 16, v164
	v_and_b32_e32 v139, 0xffff0000, v164
	v_pk_fma_f32 v[136:137], v[136:137], s[22:23], v[138:139] op_sel_hi:[1,0,1]
	v_cvt_f32_fp8_sdwa v138, v158 src0_sel:BYTE_2
	v_cvt_f32_fp8_sdwa v139, v158 src0_sel:BYTE_3
	v_cvt_f32_fp8_sdwa v140, v159 src0_sel:BYTE_2
	v_cvt_f32_fp8_sdwa v141, v159 src0_sel:BYTE_3
	v_lshlrev_b32_e32 v146, 16, v163
	v_and_b32_e32 v147, 0xffff0000, v163
	v_pk_fma_f32 v[138:139], v[138:139], s[22:23], v[146:147] op_sel_hi:[1,0,1]
	v_lshlrev_b32_e32 v146, 16, v165
	v_and_b32_e32 v147, 0xffff0000, v165
	v_pk_fma_f32 v[140:141], v[140:141], s[22:23], v[146:147] op_sel_hi:[1,0,1]
	v_pk_add_f32 v[122:123], v[122:123], v[134:135]
	v_pk_add_f32 v[136:137], v[118:119], v[136:137]
	v_cvt_pk_bf16_f32 v118, v122, v123
	v_pk_add_f32 v[124:125], v[124:125], v[138:139]
	v_pk_add_f32 v[134:135], v[120:121], v[140:141]
	v_cvt_pk_bf16_f32 v119, v124, v125
	v_cvt_pk_bf16_f32 v120, v136, v137
	v_lshlrev_b32_e32 v138, 16, v118
	v_cvt_pk_bf16_f32 v121, v134, v135
	v_mov_b32_e32 v222, v118
	v_mov_b32_e32 v223, v119
	v_mov_b32_e32 v224, v120
	v_mov_b32_e32 v225, v121
	v_sub_f32_e32 v138, v122, v138
	v_mul_f32_e32 v138, 0x45800000, v138
	v_and_b32_e32 v118, 0xffff0000, v118
	v_sub_f32_e32 v118, v123, v118
	v_mul_f32_e32 v118, 0x45800000, v118
	v_med3_f32 v138, v138, s3, v206
	v_med3_f32 v146, v118, s3, v206
	v_mov_b32_e32 v118, v1
	v_lshlrev_b32_e32 v139, 16, v119
	v_and_b32_e32 v119, 0xffff0000, v119
	v_cvt_pk_fp8_f32 v118, v138, v146
	v_sub_f32_e32 v119, v125, v119
	v_sub_f32_e32 v139, v124, v139
	v_mul_f32_e32 v139, 0x45800000, v139
	v_mul_f32_e32 v119, 0x45800000, v119
	v_lshlrev_b32_e32 v140, 16, v120
	v_and_b32_e32 v120, 0xffff0000, v120
	v_med3_f32 v138, v139, s3, v206
	v_med3_f32 v119, v119, s3, v206
	v_lshlrev_b32_e32 v141, 16, v121
	v_cvt_pk_fp8_f32 v118, v138, v119 op_sel:[0,0,1]
	v_sub_f32_e32 v120, v137, v120
	v_sub_f32_e32 v138, v136, v140
	v_sub_f32_e32 v119, v134, v141
	v_mul_f32_e32 v138, 0x45800000, v138
	v_mul_f32_e32 v120, 0x45800000, v120
	v_med3_f32 v138, v138, s3, v206
	v_med3_f32 v120, v120, s3, v206
	v_mul_f32_e32 v139, 0x45800000, v119
	v_mov_b32_e32 v119, v1
	v_and_b32_e32 v121, 0xffff0000, v121
	v_cvt_pk_fp8_f32 v119, v138, v120
	v_sub_f32_e32 v121, v135, v121
	v_mul_f32_e32 v121, 0x45800000, v121
	v_med3_f32 v120, v139, s3, v206
	v_med3_f32 v121, v121, s3, v206
	v_cvt_pk_fp8_f32 v119, v120, v121 op_sel:[0,0,1]
	v_mul_f32_e32 v120, v123, v123
	v_mul_f32_e32 v121, v125, v125
	v_fmac_f32_e32 v120, v122, v122
	v_fmac_f32_e32 v121, v124, v124
	v_add_f32_e32 v120, v120, v121
	v_mul_f32_e32 v121, v137, v137
	v_mul_f32_e32 v122, v135, v135
	v_fmac_f32_e32 v121, v136, v136
	v_fmac_f32_e32 v122, v134, v134
	v_add_f32_e32 v121, v121, v122
	v_add_f32_e32 v138, v120, v121
	v_cvt_f32_fp8_e32 v120, v160
	v_cvt_f32_fp8_sdwa v121, v160 src0_sel:BYTE_1
	v_cvt_f32_fp8_e32 v122, v161
	v_cvt_f32_fp8_sdwa v123, v161 src0_sel:BYTE_1
	v_lshlrev_b32_e32 v124, 16, v154
	v_and_b32_e32 v125, 0xffff0000, v154
	v_pk_fma_f32 v[120:121], v[120:121], s[22:23], v[124:125] op_sel_hi:[1,0,1]
	v_lshlrev_b32_e32 v124, 16, v156
	v_and_b32_e32 v125, 0xffff0000, v156
	v_pk_fma_f32 v[122:123], v[122:123], s[22:23], v[124:125] op_sel_hi:[1,0,1]
	v_cvt_f32_fp8_sdwa v124, v160 src0_sel:BYTE_2
	v_cvt_f32_fp8_sdwa v125, v160 src0_sel:BYTE_3
	v_cvt_f32_fp8_sdwa v134, v161 src0_sel:BYTE_2
	v_cvt_f32_fp8_sdwa v135, v161 src0_sel:BYTE_3
	v_lshlrev_b32_e32 v136, 16, v155
	v_and_b32_e32 v137, 0xffff0000, v155
	v_pk_fma_f32 v[124:125], v[124:125], s[22:23], v[136:137] op_sel_hi:[1,0,1]
	v_lshlrev_b32_e32 v136, 16, v157
	v_and_b32_e32 v137, 0xffff0000, v157
	v_pk_fma_f32 v[134:135], v[134:135], s[22:23], v[136:137] op_sel_hi:[1,0,1]
	v_pk_add_f32 v[136:137], v[110:111], v[120:121]
	v_pk_add_f32 v[124:125], v[112:113], v[124:125]
	v_cvt_pk_bf16_f32 v110, v136, v137
	v_pk_add_f32 v[102:103], v[102:103], v[122:123]
	v_lshlrev_b32_e32 v120, 16, v110
	v_and_b32_e32 v121, 0xffff0000, v110
	v_sub_f32_e32 v120, v136, v120
	v_sub_f32_e32 v121, v137, v121
	v_mul_f32_e32 v120, 0x45800000, v120
	v_med3_f32 v141, v120, s3, v206
	v_mul_f32_e32 v120, 0x45800000, v121
	v_cvt_pk_bf16_f32 v111, v124, v125
	v_med3_f32 v121, v120, s3, v206
	v_lshlrev_b32_e32 v122, 16, v111
	v_mov_b32_e32 v120, v1
	v_and_b32_e32 v123, 0xffff0000, v111
	v_sub_f32_e32 v122, v124, v122
	v_cvt_pk_fp8_f32 v120, v141, v121
	v_sub_f32_e32 v123, v125, v123
	v_mul_f32_e32 v122, 0x45800000, v122
	v_pk_add_f32 v[104:105], v[104:105], v[134:135]
	v_cvt_pk_bf16_f32 v112, v102, v103
	v_med3_f32 v121, v122, s3, v206
	v_lshlrev_b32_e32 v134, 16, v112
	v_and_b32_e32 v135, 0xffff0000, v112
	v_mul_f32_e32 v122, 0x45800000, v123
	v_cvt_pk_bf16_f32 v113, v104, v105
	v_med3_f32 v122, v122, s3, v206
	v_lshlrev_b32_e32 v139, 16, v113
	v_sub_f32_e32 v123, v103, v135
	v_sub_f32_e32 v134, v102, v134
	v_cvt_pk_fp8_f32 v120, v121, v122 op_sel:[0,0,1]
	v_sub_f32_e32 v121, v104, v139
	v_mul_f32_e32 v134, 0x45800000, v134
	v_mul_f32_e32 v123, 0x45800000, v123
	v_med3_f32 v134, v134, s3, v206
	v_med3_f32 v123, v123, s3, v206
	v_mul_f32_e32 v135, 0x45800000, v121
	v_mov_b32_e32 v121, v1
	v_mul_f32_e32 v103, v103, v103
	v_cvt_pk_fp8_f32 v121, v134, v123
	v_mul_f32_e32 v123, v137, v137
	v_mul_f32_e32 v125, v125, v125
	v_fmac_f32_e32 v103, v102, v102
	v_mul_f32_e32 v102, v105, v105
	v_fmac_f32_e32 v123, v136, v136
	v_fmac_f32_e32 v125, v124, v124
	v_fmac_f32_e32 v102, v104, v104
	v_add_f32_e32 v123, v123, v125
	v_add_f32_e32 v102, v103, v102
	v_add_f32_e32 v102, v123, v102
	v_add_f32_e32 v102, v138, v102
	ds_bpermute_b32 v103, v150, v102
	v_and_b32_e32 v140, 0xffff0000, v113
	v_sub_f32_e32 v122, v105, v140
	v_mul_f32_e32 v105, 0x45800000, v122
	v_med3_f32 v104, v135, s3, v206
	s_waitcnt lgkmcnt(0)
	v_add_f32_e32 v102, v102, v103
	ds_bpermute_b32 v103, v151, v102
	v_med3_f32 v105, v105, s3, v206
	v_cvt_pk_fp8_f32 v121, v104, v105 op_sel:[0,0,1]
	s_mov_b64 s[30:31], 0x4000
	v_lshl_add_u64 v[104:105], v[174:175], 0, s[30:31]
	v_mov_b32_e32 v226, v110
	v_mov_b32_e32 v227, v111
	v_mov_b32_e32 v228, v112
	v_mov_b32_e32 v229, v113
	s_nop 1
	v_permlane16_swap_b32_e32 v222, v226
	v_permlane16_swap_b32_e32 v223, v227
	v_permlane16_swap_b32_e32 v224, v228
	v_permlane16_swap_b32_e32 v225, v229
	v_permlane32_swap_b32_e32 v222, v226
	v_permlane32_swap_b32_e32 v223, v227
	v_permlane32_swap_b32_e32 v224, v228
	v_permlane32_swap_b32_e32 v225, v229
	v_lshl_add_u64 v[230:231], v[182:183], 0, v[232:233]
	global_store_dwordx4 v[230:231], v[222:225], off
	global_store_dwordx4 v[230:231], v[226:229], off offset:64
	global_store_dwordx4 v[104:105], v[118:121], off
	s_and_saveexec_b64 s[36:37], s[40:41]
	s_cbranch_execz .LBB0_84
; __device__ __forceinline__ u32x4 pack8(f32x4 a, f32x4 b) { u32x4 w; w.x = cvt_pk_bf16(a[0], a[1]); w.y = cvt_pk_bf16(a[2], a[3]); w.z = cvt_pk_bf16(b[0], b[1]); w.w = cvt_pk_bf16(b[2], b[3]); return w; }
; __device__ __forceinline__ void unpack8(u32x4 w, f32x4& a, f32x4& b) { a = (f32x4){bf_lo(w.x), bf_hi(w.x), bf_lo(w.y), bf_hi(w.y)}; b = (f32x4){bf_lo(w.z), bf_hi(w.z), bf_lo(w.w), bf_hi(w.w)}; }
; __device__ __forceinline__ float lo_dec(unsigned w, int i) { return (i == 0 ? __builtin_amdgcn_cvt_f32_fp8(w, 0) : i == 1 ? __builtin_amdgcn_cvt_f32_fp8(w, 1) : i == 2 ? __builtin_amdgcn_cvt_f32_fp8(w, 2) : __builtin_amdgcn_cvt_f32_fp8(w, 3)) * (1.0f / 4096.0f); }
;     __device__ __forceinline__ void operator()(const f32x4 (&acc)[2][2][4][2], const Unit& u, int wr, int wc, int fr_, int fq_) const {
;     ...
;                     u32x4 lo_out; float ss = 0.f;
; #pragma unroll
;                     for (int bj = 0; bj < 2; ++bj) {
;                         f32x4 a, b; unpack8(bj ? h1[k & 1][j] : h0[k & 1][j], a, b);
; #pragma unroll
;                         for (int i = 0; i < 4; ++i) { a[i] += lo_dec(lw[k & 1][j][2 * bj], i); b[i] += lo_dec(lw[k & 1][j][2 * bj + 1], i); }
;                         a = a + acc[ai][bj][m][0]; b = b + acc[ai][bj][m][1];
;                         const u32x4 hw = pack8(a, b);
;                         *(u32x4*)(XH + off + 8 * bj) = hw;
;                         f32x4 ra, rb; unpack8(hw, ra, rb);
;                         lo_out[2 * bj] = lo_enc(a - ra); lo_out[2 * bj + 1] = lo_enc(b - rb);
;                         ss += ((a[0] * a[0] + a[1] * a[1]) + (a[2] * a[2] + a[3] * a[3])) + ((b[0] * b[0] + b[1] * b[1]) + (b[2] * b[2] + b[3] * b[3]));
;                     }
;                     *(u32x4*)(XL + off) = lo_out;
;                     ss += __shfl_xor(ss, 16); ss += __shfl_xor(ss, 32);
;                     if (fq == 0) SSo[(size_t)(u.pm * 256 + ai * 128 + wr * 64 + m * 16 + fr) * 16 + 4 * u.pn + wc] = ss;
;                 }
;             }
;             if (k < 4) {
; #pragma unroll
;                 for (int j = 0; j < 2; ++j) {
;                     const int ai = k >> 1, m = (k & 1) * 2 + j;
;                     const size_t off = off0 + (size_t)(ai * 128 + m * 16) * 1024;
;                     h0[k & 1][j] = *(const u32x4*)(XH + off); h1[k & 1][j] = *(const u32x4*)(XH + off + 8); lw[k & 1][j] = *(const u32x4*)(XL + off);
	s_waitcnt lgkmcnt(0)
	v_add_f32_e32 v104, v102, v103
	v_add_u32_e32 v102, 16, v172
	v_ashrrev_i32_e32 v103, 31, v102
	v_lshlrev_b64 v[102:103], 6, v[102:103]
	v_lshl_add_u64 v[102:103], s[46:47], 0, v[102:103]
	v_lshl_add_u64 v[102:103], s[62:63], 2, v[102:103]
	s_lshl_b32 s24, s72, 2
	v_lshl_add_u64 v[102:103], v[102:103], 0, s[24:25]
	global_store_dword v[102:103], v104, off
.LBB0_84:
	s_or_b64 exec, exec, s[36:37]
	v_add_co_u32_e32 v102, vcc, 0x40000, v176
	s_mov_b64 s[30:31], 0x40000
	s_waitcnt lgkmcnt(0)
	v_addc_co_u32_e32 v103, vcc, 0, v177, vcc
	v_add_co_u32_e32 v104, vcc, 0x20000, v174
	v_lshl_add_u64 v[148:149], v[176:177], 0, s[30:31]
	s_nop 0
	v_addc_co_u32_e32 v105, vcc, 0, v175, vcc
	v_add_co_u32_e32 v110, vcc, 0x48000, v176
	s_mov_b64 s[30:31], 0x48000
	s_nop 0
	v_addc_co_u32_e32 v111, vcc, 0, v177, vcc
	v_add_co_u32_e32 v112, vcc, 0x24000, v174
	global_load_dwordx4 v[138:141], v[102:103], off
	global_load_dwordx4 v[122:125], v[104:105], off
	v_addc_co_u32_e32 v113, vcc, 0, v175, vcc
	v_lshl_add_u64 v[146:147], v[176:177], 0, s[30:31]
	global_load_dwordx4 v[134:137], v[148:149], off offset:16
	global_load_dwordx4 v[102:105], v[146:147], off offset:16
	global_load_dwordx4 v[118:121], v[110:111], off
	s_nop 0
	global_load_dwordx4 v[110:113], v[112:113], off
	v_cvt_f32_fp8_e32 v152, v126
	v_cvt_f32_fp8_sdwa v153, v126 src0_sel:BYTE_1
	v_cvt_f32_fp8_e32 v154, v127
	v_cvt_f32_fp8_sdwa v155, v127 src0_sel:BYTE_1
	v_lshlrev_b32_e32 v156, 16, v142
	v_and_b32_e32 v157, 0xffff0000, v142
	v_pk_fma_f32 v[152:153], v[152:153], s[22:23], v[156:157] op_sel_hi:[1,0,1]
	v_lshlrev_b32_e32 v156, 16, v144
	v_and_b32_e32 v157, 0xffff0000, v144
	v_pk_fma_f32 v[154:155], v[154:155], s[22:23], v[156:157] op_sel_hi:[1,0,1]
	v_cvt_f32_fp8_sdwa v156, v126 src0_sel:BYTE_2
	v_cvt_f32_fp8_sdwa v142, v127 src0_sel:BYTE_2
	v_cvt_f32_fp8_sdwa v157, v126 src0_sel:BYTE_3
	v_lshlrev_b32_e32 v158, 16, v143
	v_and_b32_e32 v159, 0xffff0000, v143
	v_cvt_f32_fp8_sdwa v143, v127 src0_sel:BYTE_3
	v_lshlrev_b32_e32 v144, 16, v145
	v_and_b32_e32 v145, 0xffff0000, v145
	v_pk_fma_f32 v[126:127], v[156:157], s[22:23], v[158:159] op_sel_hi:[1,0,1]
	v_pk_fma_f32 v[142:143], v[142:143], s[22:23], v[144:145] op_sel_hi:[1,0,1]
	v_pk_add_f32 v[96:97], v[96:97], v[126:127]
	v_pk_add_f32 v[94:95], v[94:95], v[152:153]
	v_pk_add_f32 v[126:127], v[92:93], v[142:143]
	v_pk_add_f32 v[142:143], v[90:91], v[154:155]
	v_cvt_pk_bf16_f32 v90, v94, v95
	v_cvt_pk_bf16_f32 v91, v96, v97
	s_mov_b64 s[30:31], 0x8000
	v_cvt_pk_bf16_f32 v92, v142, v143
	v_cvt_pk_bf16_f32 v93, v126, v127
	v_mov_b32_e32 v222, v90
	v_mov_b32_e32 v223, v91
	v_mov_b32_e32 v224, v92
	v_mov_b32_e32 v225, v93
	v_lshlrev_b32_e32 v144, 16, v90
	v_sub_f32_e32 v144, v94, v144
	v_and_b32_e32 v90, 0xffff0000, v90
	v_sub_f32_e32 v90, v95, v90
	v_mul_f32_e32 v144, 0x45800000, v144
	v_mul_f32_e32 v90, 0x45800000, v90
	v_med3_f32 v144, v144, s3, v206
	v_med3_f32 v154, v90, s3, v206
	v_mov_b32_e32 v90, v1
	v_lshlrev_b32_e32 v145, 16, v91
	v_and_b32_e32 v91, 0xffff0000, v91
	v_cvt_pk_fp8_f32 v90, v144, v154
	v_sub_f32_e32 v91, v97, v91
	v_sub_f32_e32 v145, v96, v145
	v_mul_f32_e32 v145, 0x45800000, v145
	v_mul_f32_e32 v91, 0x45800000, v91
	v_lshlrev_b32_e32 v152, 16, v92
	v_and_b32_e32 v92, 0xffff0000, v92
	v_med3_f32 v144, v145, s3, v206
	v_med3_f32 v91, v91, s3, v206
	v_lshlrev_b32_e32 v153, 16, v93
	v_cvt_pk_fp8_f32 v90, v144, v91 op_sel:[0,0,1]
	v_sub_f32_e32 v92, v143, v92
	v_sub_f32_e32 v144, v142, v152
	v_sub_f32_e32 v91, v126, v153
	v_mul_f32_e32 v144, 0x45800000, v144
	v_mul_f32_e32 v92, 0x45800000, v92
	v_med3_f32 v144, v144, s3, v206
	v_med3_f32 v92, v92, s3, v206
	v_mul_f32_e32 v145, 0x45800000, v91
	v_mov_b32_e32 v91, v1
	v_and_b32_e32 v93, 0xffff0000, v93
	v_cvt_pk_fp8_f32 v91, v144, v92
	v_sub_f32_e32 v93, v127, v93
	v_mul_f32_e32 v93, 0x45800000, v93
	v_med3_f32 v92, v145, s3, v206
	v_med3_f32 v93, v93, s3, v206
	v_cvt_pk_fp8_f32 v91, v92, v93 op_sel:[0,0,1]
	v_mul_f32_e32 v92, v95, v95
	v_mul_f32_e32 v93, v97, v97
	v_fmac_f32_e32 v92, v94, v94
	v_fmac_f32_e32 v93, v96, v96
	v_add_f32_e32 v92, v92, v93
	v_mul_f32_e32 v93, v143, v143
	v_mul_f32_e32 v94, v127, v127
	v_fmac_f32_e32 v93, v142, v142
	v_fmac_f32_e32 v94, v126, v126
	v_add_f32_e32 v93, v93, v94
	v_add_f32_e32 v142, v92, v93
	v_cvt_f32_fp8_e32 v92, v128
	v_cvt_f32_fp8_sdwa v93, v128 src0_sel:BYTE_1
	v_cvt_f32_fp8_e32 v94, v129
	v_cvt_f32_fp8_sdwa v95, v129 src0_sel:BYTE_1
	v_lshlrev_b32_e32 v96, 16, v130
	v_and_b32_e32 v97, 0xffff0000, v130
	v_pk_fma_f32 v[92:93], v[92:93], s[22:23], v[96:97] op_sel_hi:[1,0,1]
	v_lshlrev_b32_e32 v96, 16, v132
	v_and_b32_e32 v97, 0xffff0000, v132
	v_pk_fma_f32 v[94:95], v[94:95], s[22:23], v[96:97] op_sel_hi:[1,0,1]
	v_cvt_f32_fp8_sdwa v96, v128 src0_sel:BYTE_2
	v_cvt_f32_fp8_sdwa v126, v129 src0_sel:BYTE_2
	v_cvt_f32_fp8_sdwa v97, v128 src0_sel:BYTE_3
	v_cvt_f32_fp8_sdwa v127, v129 src0_sel:BYTE_3
	v_lshlrev_b32_e32 v130, 16, v131
	v_and_b32_e32 v131, 0xffff0000, v131
	v_lshlrev_b32_e32 v128, 16, v133
	v_and_b32_e32 v129, 0xffff0000, v133
	v_pk_fma_f32 v[96:97], v[96:97], s[22:23], v[130:131] op_sel_hi:[1,0,1]
	v_pk_fma_f32 v[126:127], v[126:127], s[22:23], v[128:129] op_sel_hi:[1,0,1]
	v_pk_add_f32 v[88:89], v[88:89], v[96:97]
	v_pk_add_f32 v[96:97], v[86:87], v[92:93]
	v_pk_add_f32 v[126:127], v[84:85], v[126:127]
	v_cvt_pk_bf16_f32 v84, v96, v97
	v_pk_add_f32 v[82:83], v[82:83], v[94:95]
	v_lshlrev_b32_e32 v92, 16, v84
	v_and_b32_e32 v93, 0xffff0000, v84
	v_sub_f32_e32 v92, v96, v92
	v_sub_f32_e32 v93, v97, v93
	v_mul_f32_e32 v92, 0x45800000, v92
	v_med3_f32 v132, v92, s3, v206
	v_mul_f32_e32 v92, 0x45800000, v93
; __device__ __forceinline__ u32x4 pack8(f32x4 a, f32x4 b) { u32x4 w; w.x = cvt_pk_bf16(a[0], a[1]); w.y = cvt_pk_bf16(a[2], a[3]); w.z = cvt_pk_bf16(b[0], b[1]); w.w = cvt_pk_bf16(b[2], b[3]); return w; }
; __device__ __forceinline__ void unpack8(u32x4 w, f32x4& a, f32x4& b) { a = (f32x4){bf_lo(w.x), bf_hi(w.x), bf_lo(w.y), bf_hi(w.y)}; b = (f32x4){bf_lo(w.z), bf_hi(w.z), bf_lo(w.w), bf_hi(w.w)}; }
; __device__ __forceinline__ float lo_dec(unsigned w, int i) { return (i == 0 ? __builtin_amdgcn_cvt_f32_fp8(w, 0) : i == 1 ? __builtin_amdgcn_cvt_f32_fp8(w, 1) : i == 2 ? __builtin_amdgcn_cvt_f32_fp8(w, 2) : __builtin_amdgcn_cvt_f32_fp8(w, 3)) * (1.0f / 4096.0f); }
;     __device__ __forceinline__ void operator()(const f32x4 (&acc)[2][2][4][2], const Unit& u, int wr, int wc, int fr_, int fq_) const {
;     ...
;                     u32x4 lo_out; float ss = 0.f;
; #pragma unroll
;                     for (int bj = 0; bj < 2; ++bj) {
;                         f32x4 a, b; unpack8(bj ? h1[k & 1][j] : h0[k & 1][j], a, b);
; #pragma unroll
;                         for (int i = 0; i < 4; ++i) { a[i] += lo_dec(lw[k & 1][j][2 * bj], i); b[i] += lo_dec(lw[k & 1][j][2 * bj + 1], i); }
;                         a = a + acc[ai][bj][m][0]; b = b + acc[ai][bj][m][1];
;                         const u32x4 hw = pack8(a, b);
;                         *(u32x4*)(XH + off + 8 * bj) = hw;
;                         f32x4 ra, rb; unpack8(hw, ra, rb);
;                         lo_out[2 * bj] = lo_enc(a - ra); lo_out[2 * bj + 1] = lo_enc(b - rb);
;                         ss += ((a[0] * a[0] + a[1] * a[1]) + (a[2] * a[2] + a[3] * a[3])) + ((b[0] * b[0] + b[1] * b[1]) + (b[2] * b[2] + b[3] * b[3]));
;                     }
;                     *(u32x4*)(XL + off) = lo_out;
;                     ss += __shfl_xor(ss, 16); ss += __shfl_xor(ss, 32);
;                     if (fq == 0) SSo[(size_t)(u.pm * 256 + ai * 128 + wr * 64 + m * 16 + fr) * 16 + 4 * u.pn + wc] = ss;
	v_cvt_pk_bf16_f32 v85, v88, v89
	v_med3_f32 v93, v92, s3, v206
	v_lshlrev_b32_e32 v94, 16, v85
	v_mov_b32_e32 v92, v1
	v_and_b32_e32 v95, 0xffff0000, v85
	v_sub_f32_e32 v94, v88, v94
	v_cvt_pk_fp8_f32 v92, v132, v93
	v_sub_f32_e32 v95, v89, v95
	v_mul_f32_e32 v94, 0x45800000, v94
	v_cvt_pk_bf16_f32 v86, v82, v83
	v_med3_f32 v93, v94, s3, v206
	v_lshlrev_b32_e32 v128, 16, v86
	v_and_b32_e32 v129, 0xffff0000, v86
	v_mul_f32_e32 v94, 0x45800000, v95
	v_cvt_pk_bf16_f32 v87, v126, v127
	v_med3_f32 v94, v94, s3, v206
	v_lshlrev_b32_e32 v130, 16, v87
	v_sub_f32_e32 v95, v83, v129
	v_sub_f32_e32 v128, v82, v128
	v_cvt_pk_fp8_f32 v92, v93, v94 op_sel:[0,0,1]
	v_sub_f32_e32 v93, v126, v130
	v_mul_f32_e32 v128, 0x45800000, v128
	v_mul_f32_e32 v95, 0x45800000, v95
	v_med3_f32 v128, v128, s3, v206
	v_med3_f32 v95, v95, s3, v206
	v_mul_f32_e32 v129, 0x45800000, v93
	v_mov_b32_e32 v93, v1
	v_mul_f32_e32 v83, v83, v83
	v_cvt_pk_fp8_f32 v93, v128, v95
	v_mul_f32_e32 v95, v97, v97
	v_mul_f32_e32 v89, v89, v89
	v_fmac_f32_e32 v83, v82, v82
	v_mul_f32_e32 v82, v127, v127
	v_fmac_f32_e32 v95, v96, v96
	v_fmac_f32_e32 v89, v88, v88
	v_fmac_f32_e32 v82, v126, v126
	v_add_f32_e32 v88, v95, v89
	v_add_f32_e32 v82, v83, v82
	v_add_f32_e32 v82, v88, v82
	v_add_f32_e32 v82, v142, v82
	ds_bpermute_b32 v83, v150, v82
	v_and_b32_e32 v131, 0xffff0000, v87
	v_sub_f32_e32 v94, v127, v131
	v_mul_f32_e32 v89, 0x45800000, v94
	v_med3_f32 v88, v129, s3, v206
	s_waitcnt lgkmcnt(0)
	v_add_f32_e32 v82, v82, v83
	ds_bpermute_b32 v83, v151, v82
	v_med3_f32 v89, v89, s3, v206
	v_cvt_pk_fp8_f32 v93, v88, v89 op_sel:[0,0,1]
	v_lshl_add_u64 v[88:89], v[174:175], 0, s[30:31]
	v_mov_b32_e32 v226, v84
	v_mov_b32_e32 v227, v85
	v_mov_b32_e32 v228, v86
	v_mov_b32_e32 v229, v87
	s_nop 1
	v_permlane16_swap_b32_e32 v222, v226
	v_permlane16_swap_b32_e32 v223, v227
	v_permlane16_swap_b32_e32 v224, v228
	v_permlane16_swap_b32_e32 v225, v229
	v_permlane32_swap_b32_e32 v222, v226
	v_permlane32_swap_b32_e32 v223, v227
	v_permlane32_swap_b32_e32 v224, v228
	v_permlane32_swap_b32_e32 v225, v229
	v_lshl_add_u64 v[230:231], v[180:181], 0, v[232:233]
	global_store_dwordx4 v[230:231], v[222:225], off
	global_store_dwordx4 v[230:231], v[226:229], off offset:64
	global_store_dwordx4 v[88:89], v[90:93], off
	s_and_saveexec_b64 s[36:37], s[40:41]
	s_cbranch_execz .LBB0_86
	s_waitcnt lgkmcnt(0)
	v_add_f32_e32 v84, v82, v83
	v_add_u32_e32 v82, 32, v172
	v_ashrrev_i32_e32 v83, 31, v82
	v_lshlrev_b64 v[82:83], 6, v[82:83]
	v_lshl_add_u64 v[82:83], s[46:47], 0, v[82:83]
	v_lshl_add_u64 v[82:83], s[62:63], 2, v[82:83]
	s_lshl_b32 s24, s72, 2
	v_lshl_add_u64 v[82:83], v[82:83], 0, s[24:25]
	global_store_dword v[82:83], v84, off
.LBB0_86:
	s_or_b64 exec, exec, s[36:37]
	v_cvt_f32_fp8_e32 v82, v106
	s_waitcnt lgkmcnt(0)
	v_cvt_f32_fp8_sdwa v83, v106 src0_sel:BYTE_1
	v_cvt_f32_fp8_e32 v84, v107
	v_cvt_f32_fp8_sdwa v85, v107 src0_sel:BYTE_1
	v_lshlrev_b32_e32 v86, 16, v114
	v_and_b32_e32 v87, 0xffff0000, v114
	v_pk_fma_f32 v[82:83], v[82:83], s[22:23], v[86:87] op_sel_hi:[1,0,1]
	v_lshlrev_b32_e32 v86, 16, v116
	v_and_b32_e32 v87, 0xffff0000, v116
	v_pk_fma_f32 v[84:85], v[84:85], s[22:23], v[86:87] op_sel_hi:[1,0,1]
	v_cvt_f32_fp8_sdwa v86, v106 src0_sel:BYTE_2
	v_cvt_f32_fp8_sdwa v87, v106 src0_sel:BYTE_3
	v_cvt_f32_fp8_sdwa v88, v107 src0_sel:BYTE_2
	v_cvt_f32_fp8_sdwa v89, v107 src0_sel:BYTE_3
	v_lshlrev_b32_e32 v90, 16, v115
	v_and_b32_e32 v91, 0xffff0000, v115
	v_pk_fma_f32 v[86:87], v[86:87], s[22:23], v[90:91] op_sel_hi:[1,0,1]
	v_lshlrev_b32_e32 v90, 16, v117
	v_and_b32_e32 v91, 0xffff0000, v117
	v_pk_fma_f32 v[88:89], v[88:89], s[22:23], v[90:91] op_sel_hi:[1,0,1]
	v_pk_add_f32 v[78:79], v[78:79], v[82:83]
	v_pk_add_f32 v[84:85], v[74:75], v[84:85]
	v_cvt_pk_bf16_f32 v74, v78, v79
	v_pk_add_f32 v[80:81], v[80:81], v[86:87]
	v_pk_add_f32 v[82:83], v[76:77], v[88:89]
	v_cvt_pk_bf16_f32 v75, v80, v81
	v_cvt_pk_bf16_f32 v76, v84, v85
	v_lshlrev_b32_e32 v86, 16, v74
	v_cvt_pk_bf16_f32 v77, v82, v83
	v_mov_b32_e32 v222, v74
	v_mov_b32_e32 v223, v75
	v_mov_b32_e32 v224, v76
	v_mov_b32_e32 v225, v77
	v_sub_f32_e32 v86, v78, v86
	v_mul_f32_e32 v86, 0x45800000, v86
	v_and_b32_e32 v74, 0xffff0000, v74
	v_sub_f32_e32 v74, v79, v74
	v_mul_f32_e32 v74, 0x45800000, v74
	v_med3_f32 v86, v86, s3, v206
	v_med3_f32 v90, v74, s3, v206
	v_mov_b32_e32 v74, v1
	v_lshlrev_b32_e32 v87, 16, v75
	v_and_b32_e32 v75, 0xffff0000, v75
	v_cvt_pk_fp8_f32 v74, v86, v90
	v_sub_f32_e32 v75, v81, v75
	v_sub_f32_e32 v87, v80, v87
	v_mul_f32_e32 v87, 0x45800000, v87
	v_mul_f32_e32 v75, 0x45800000, v75
	v_lshlrev_b32_e32 v88, 16, v76
	v_and_b32_e32 v76, 0xffff0000, v76
	v_med3_f32 v86, v87, s3, v206
	v_med3_f32 v75, v75, s3, v206
	v_lshlrev_b32_e32 v89, 16, v77
	v_cvt_pk_fp8_f32 v74, v86, v75 op_sel:[0,0,1]
	v_sub_f32_e32 v76, v85, v76
	v_sub_f32_e32 v86, v84, v88
	v_sub_f32_e32 v75, v82, v89
	v_mul_f32_e32 v86, 0x45800000, v86
	v_mul_f32_e32 v76, 0x45800000, v76
	v_med3_f32 v86, v86, s3, v206
	v_med3_f32 v76, v76, s3, v206
	v_mul_f32_e32 v87, 0x45800000, v75
	v_mov_b32_e32 v75, v1
	v_and_b32_e32 v77, 0xffff0000, v77
	v_cvt_pk_fp8_f32 v75, v86, v76
	v_sub_f32_e32 v77, v83, v77
	v_mul_f32_e32 v77, 0x45800000, v77
	v_med3_f32 v76, v87, s3, v206
	v_med3_f32 v77, v77, s3, v206
	v_cvt_pk_fp8_f32 v75, v76, v77 op_sel:[0,0,1]
	v_mul_f32_e32 v76, v79, v79
	v_mul_f32_e32 v77, v81, v81
	v_fmac_f32_e32 v76, v78, v78
	v_fmac_f32_e32 v77, v80, v80
	v_add_f32_e32 v76, v76, v77
	v_mul_f32_e32 v77, v85, v85
	v_mul_f32_e32 v78, v83, v83
	v_fmac_f32_e32 v77, v84, v84
	v_fmac_f32_e32 v78, v82, v82
	v_add_f32_e32 v77, v77, v78
	v_add_f32_e32 v86, v76, v77
; __device__ __forceinline__ u32x4 pack8(f32x4 a, f32x4 b) { u32x4 w; w.x = cvt_pk_bf16(a[0], a[1]); w.y = cvt_pk_bf16(a[2], a[3]); w.z = cvt_pk_bf16(b[0], b[1]); w.w = cvt_pk_bf16(b[2], b[3]); return w; }
; __device__ __forceinline__ void unpack8(u32x4 w, f32x4& a, f32x4& b) { a = (f32x4){bf_lo(w.x), bf_hi(w.x), bf_lo(w.y), bf_hi(w.y)}; b = (f32x4){bf_lo(w.z), bf_hi(w.z), bf_lo(w.w), bf_hi(w.w)}; }
; __device__ __forceinline__ float lo_dec(unsigned w, int i) { return (i == 0 ? __builtin_amdgcn_cvt_f32_fp8(w, 0) : i == 1 ? __builtin_amdgcn_cvt_f32_fp8(w, 1) : i == 2 ? __builtin_amdgcn_cvt_f32_fp8(w, 2) : __builtin_amdgcn_cvt_f32_fp8(w, 3)) * (1.0f / 4096.0f); }
;     __device__ __forceinline__ void operator()(const f32x4 (&acc)[2][2][4][2], const Unit& u, int wr, int wc, int fr_, int fq_) const {
;     ...
;                     u32x4 lo_out; float ss = 0.f;
; #pragma unroll
;                     for (int bj = 0; bj < 2; ++bj) {
;                         f32x4 a, b; unpack8(bj ? h1[k & 1][j] : h0[k & 1][j], a, b);
; #pragma unroll
;                         for (int i = 0; i < 4; ++i) { a[i] += lo_dec(lw[k & 1][j][2 * bj], i); b[i] += lo_dec(lw[k & 1][j][2 * bj + 1], i); }
;                         a = a + acc[ai][bj][m][0]; b = b + acc[ai][bj][m][1];
;                         const u32x4 hw = pack8(a, b);
;                         *(u32x4*)(XH + off + 8 * bj) = hw;
;                         f32x4 ra, rb; unpack8(hw, ra, rb);
;                         lo_out[2 * bj] = lo_enc(a - ra); lo_out[2 * bj + 1] = lo_enc(b - rb);
;                         ss += ((a[0] * a[0] + a[1] * a[1]) + (a[2] * a[2] + a[3] * a[3])) + ((b[0] * b[0] + b[1] * b[1]) + (b[2] * b[2] + b[3] * b[3]));
;                     }
;                     *(u32x4*)(XL + off) = lo_out;
;                     ss += __shfl_xor(ss, 16); ss += __shfl_xor(ss, 32);
;                     if (fq == 0) SSo[(size_t)(u.pm * 256 + ai * 128 + wr * 64 + m * 16 + fr) * 16 + 4 * u.pn + wc] = ss;
;                 }
;             }
;             if (k < 4) {
; #pragma unroll
;                 for (int j = 0; j < 2; ++j) {
;                     const int ai = k >> 1, m = (k & 1) * 2 + j;
;                     const size_t off = off0 + (size_t)(ai * 128 + m * 16) * 1024;
;                     h0[k & 1][j] = *(const u32x4*)(XH + off); h1[k & 1][j] = *(const u32x4*)(XH + off + 8); lw[k & 1][j] = *(const u32x4*)(XL + off);
	v_cvt_f32_fp8_e32 v76, v108
	v_cvt_f32_fp8_sdwa v77, v108 src0_sel:BYTE_1
	v_cvt_f32_fp8_e32 v78, v109
	v_cvt_f32_fp8_sdwa v79, v109 src0_sel:BYTE_1
	v_lshlrev_b32_e32 v80, 16, v98
	v_and_b32_e32 v81, 0xffff0000, v98
	v_pk_fma_f32 v[76:77], v[76:77], s[22:23], v[80:81] op_sel_hi:[1,0,1]
	v_lshlrev_b32_e32 v80, 16, v100
	v_and_b32_e32 v81, 0xffff0000, v100
	v_pk_fma_f32 v[78:79], v[78:79], s[22:23], v[80:81] op_sel_hi:[1,0,1]
	v_cvt_f32_fp8_sdwa v80, v108 src0_sel:BYTE_2
	v_cvt_f32_fp8_sdwa v81, v108 src0_sel:BYTE_3
	v_cvt_f32_fp8_sdwa v82, v109 src0_sel:BYTE_2
	v_cvt_f32_fp8_sdwa v83, v109 src0_sel:BYTE_3
	v_lshlrev_b32_e32 v84, 16, v99
	v_and_b32_e32 v85, 0xffff0000, v99
	v_pk_fma_f32 v[80:81], v[80:81], s[22:23], v[84:85] op_sel_hi:[1,0,1]
	v_lshlrev_b32_e32 v84, 16, v101
	v_and_b32_e32 v85, 0xffff0000, v101
	v_pk_fma_f32 v[82:83], v[82:83], s[22:23], v[84:85] op_sel_hi:[1,0,1]
	v_pk_add_f32 v[72:73], v[72:73], v[80:81]
	v_pk_add_f32 v[80:81], v[70:71], v[76:77]
	v_pk_add_f32 v[82:83], v[68:69], v[82:83]
	v_cvt_pk_bf16_f32 v68, v80, v81
	v_pk_add_f32 v[66:67], v[66:67], v[78:79]
	v_lshlrev_b32_e32 v76, 16, v68
	v_and_b32_e32 v77, 0xffff0000, v68
	v_sub_f32_e32 v76, v80, v76
	v_sub_f32_e32 v77, v81, v77
	v_mul_f32_e32 v76, 0x45800000, v76
	v_med3_f32 v89, v76, s3, v206
	v_mul_f32_e32 v76, 0x45800000, v77
	v_cvt_pk_bf16_f32 v69, v72, v73
	v_med3_f32 v77, v76, s3, v206
	v_lshlrev_b32_e32 v78, 16, v69
	v_mov_b32_e32 v76, v1
	v_and_b32_e32 v79, 0xffff0000, v69
	v_sub_f32_e32 v78, v72, v78
	v_cvt_pk_fp8_f32 v76, v89, v77
	v_sub_f32_e32 v79, v73, v79
	v_mul_f32_e32 v78, 0x45800000, v78
	v_cvt_pk_bf16_f32 v70, v66, v67
	v_med3_f32 v77, v78, s3, v206
	v_lshlrev_b32_e32 v84, 16, v70
	v_and_b32_e32 v85, 0xffff0000, v70
	v_mul_f32_e32 v78, 0x45800000, v79
	v_cvt_pk_bf16_f32 v71, v82, v83
	v_med3_f32 v78, v78, s3, v206
	v_lshlrev_b32_e32 v87, 16, v71
	v_sub_f32_e32 v79, v67, v85
	v_sub_f32_e32 v84, v66, v84
	v_cvt_pk_fp8_f32 v76, v77, v78 op_sel:[0,0,1]
	v_sub_f32_e32 v77, v82, v87
	v_mul_f32_e32 v84, 0x45800000, v84
	v_mul_f32_e32 v79, 0x45800000, v79
	v_med3_f32 v84, v84, s3, v206
	v_med3_f32 v79, v79, s3, v206
	v_mul_f32_e32 v85, 0x45800000, v77
	v_mov_b32_e32 v77, v1
	v_mul_f32_e32 v67, v67, v67
	v_cvt_pk_fp8_f32 v77, v84, v79
	v_mul_f32_e32 v79, v81, v81
	v_mul_f32_e32 v73, v73, v73
	v_fmac_f32_e32 v67, v66, v66
	v_mul_f32_e32 v66, v83, v83
	v_fmac_f32_e32 v79, v80, v80
	v_fmac_f32_e32 v73, v72, v72
	v_fmac_f32_e32 v66, v82, v82
	v_add_f32_e32 v72, v79, v73
	v_add_f32_e32 v66, v67, v66
	v_add_f32_e32 v66, v72, v66
	v_add_f32_e32 v66, v86, v66
	ds_bpermute_b32 v67, v150, v66
	v_and_b32_e32 v88, 0xffff0000, v71
	v_sub_f32_e32 v78, v83, v88
	v_mul_f32_e32 v73, 0x45800000, v78
	v_med3_f32 v72, v85, s3, v206
	s_waitcnt lgkmcnt(0)
	v_add_f32_e32 v66, v66, v67
	ds_bpermute_b32 v67, v151, v66
	v_med3_f32 v73, v73, s3, v206
	v_cvt_pk_fp8_f32 v77, v72, v73 op_sel:[0,0,1]
	s_mov_b64 s[30:31], 0xc000
	v_lshl_add_u64 v[72:73], v[174:175], 0, s[30:31]
	v_mov_b32_e32 v226, v68
	v_mov_b32_e32 v227, v69
	v_mov_b32_e32 v228, v70
	v_mov_b32_e32 v229, v71
	s_nop 1
	v_permlane16_swap_b32_e32 v222, v226
	v_permlane16_swap_b32_e32 v223, v227
	v_permlane16_swap_b32_e32 v224, v228
	v_permlane16_swap_b32_e32 v225, v229
	v_permlane32_swap_b32_e32 v222, v226
	v_permlane32_swap_b32_e32 v223, v227
	v_permlane32_swap_b32_e32 v224, v228
	v_permlane32_swap_b32_e32 v225, v229
	v_lshl_add_u64 v[230:231], v[178:179], 0, v[232:233]
	global_store_dwordx4 v[230:231], v[222:225], off
	global_store_dwordx4 v[230:231], v[226:229], off offset:64
	global_store_dwordx4 v[72:73], v[74:77], off
	s_and_saveexec_b64 s[36:37], s[40:41]
	s_cbranch_execz .LBB0_88
	s_waitcnt lgkmcnt(0)
	v_add_f32_e32 v68, v66, v67
	v_add_u32_e32 v66, 48, v172
	v_ashrrev_i32_e32 v67, 31, v66
	v_lshlrev_b64 v[66:67], 6, v[66:67]
	v_lshl_add_u64 v[66:67], s[46:47], 0, v[66:67]
	v_lshl_add_u64 v[66:67], s[62:63], 2, v[66:67]
	s_lshl_b32 s24, s72, 2
	v_lshl_add_u64 v[66:67], v[66:67], 0, s[24:25]
	global_store_dword v[66:67], v68, off
.LBB0_88:
	s_or_b64 exec, exec, s[36:37]
	v_add_co_u32_e32 v66, vcc, 0x50000, v176
	s_mov_b64 s[30:31], 0x50000
	s_waitcnt lgkmcnt(0)
	v_addc_co_u32_e32 v67, vcc, 0, v177, vcc
	v_add_co_u32_e32 v68, vcc, 0x28000, v174
	v_lshl_add_u64 v[92:93], v[176:177], 0, s[30:31]
	s_nop 0
	v_addc_co_u32_e32 v69, vcc, 0, v175, vcc
	v_add_co_u32_e32 v70, vcc, 0x58000, v176
	s_mov_b64 s[30:31], 0x58000
	s_nop 0
	v_addc_co_u32_e32 v71, vcc, 0, v177, vcc
	v_add_co_u32_e32 v72, vcc, 0x2c000, v174
	global_load_dwordx4 v[86:89], v[66:67], off
	global_load_dwordx4 v[78:81], v[68:69], off
	v_addc_co_u32_e32 v73, vcc, 0, v175, vcc
	v_lshl_add_u64 v[90:91], v[176:177], 0, s[30:31]
	global_load_dwordx4 v[82:85], v[92:93], off offset:16
	global_load_dwordx4 v[66:69], v[90:91], off offset:16
	global_load_dwordx4 v[74:77], v[70:71], off
	s_nop 0
	global_load_dwordx4 v[70:73], v[72:73], off
	s_waitcnt vmcnt(16)
; __device__ __forceinline__ u32x4 pack8(f32x4 a, f32x4 b) { u32x4 w; w.x = cvt_pk_bf16(a[0], a[1]); w.y = cvt_pk_bf16(a[2], a[3]); w.z = cvt_pk_bf16(b[0], b[1]); w.w = cvt_pk_bf16(b[2], b[3]); return w; }
; __device__ __forceinline__ void unpack8(u32x4 w, f32x4& a, f32x4& b) { a = (f32x4){bf_lo(w.x), bf_hi(w.x), bf_lo(w.y), bf_hi(w.y)}; b = (f32x4){bf_lo(w.z), bf_hi(w.z), bf_lo(w.w), bf_hi(w.w)}; }
; __device__ __forceinline__ float lo_dec(unsigned w, int i) { return (i == 0 ? __builtin_amdgcn_cvt_f32_fp8(w, 0) : i == 1 ? __builtin_amdgcn_cvt_f32_fp8(w, 1) : i == 2 ? __builtin_amdgcn_cvt_f32_fp8(w, 2) : __builtin_amdgcn_cvt_f32_fp8(w, 3)) * (1.0f / 4096.0f); }
;     __device__ __forceinline__ void operator()(const f32x4 (&acc)[2][2][4][2], const Unit& u, int wr, int wc, int fr_, int fq_) const {
;     ...
;                     u32x4 lo_out; float ss = 0.f;
; #pragma unroll
;                     for (int bj = 0; bj < 2; ++bj) {
;                         f32x4 a, b; unpack8(bj ? h1[k & 1][j] : h0[k & 1][j], a, b);
; #pragma unroll
;                         for (int i = 0; i < 4; ++i) { a[i] += lo_dec(lw[k & 1][j][2 * bj], i); b[i] += lo_dec(lw[k & 1][j][2 * bj + 1], i); }
;                         a = a + acc[ai][bj][m][0]; b = b + acc[ai][bj][m][1];
;                         const u32x4 hw = pack8(a, b);
;                         *(u32x4*)(XH + off + 8 * bj) = hw;
;                         f32x4 ra, rb; unpack8(hw, ra, rb);
;                         lo_out[2 * bj] = lo_enc(a - ra); lo_out[2 * bj + 1] = lo_enc(b - rb);
;                         ss += ((a[0] * a[0] + a[1] * a[1]) + (a[2] * a[2] + a[3] * a[3])) + ((b[0] * b[0] + b[1] * b[1]) + (b[2] * b[2] + b[3] * b[3]));
;                     }
;                     *(u32x4*)(XL + off) = lo_out;
;                     ss += __shfl_xor(ss, 16); ss += __shfl_xor(ss, 32);
;                     if (fq == 0) SSo[(size_t)(u.pm * 256 + ai * 128 + wr * 64 + m * 16 + fr) * 16 + 4 * u.pn + wc] = ss;
	v_cvt_f32_fp8_e32 v94, v122
	v_cvt_f32_fp8_sdwa v95, v122 src0_sel:BYTE_1
	v_cvt_f32_fp8_e32 v96, v123
	v_cvt_f32_fp8_sdwa v97, v123 src0_sel:BYTE_1
	v_lshlrev_b32_e32 v98, 16, v138
	v_and_b32_e32 v99, 0xffff0000, v138
	v_pk_fma_f32 v[94:95], v[94:95], s[22:23], v[98:99] op_sel_hi:[1,0,1]
	v_lshlrev_b32_e32 v98, 16, v140
	v_and_b32_e32 v99, 0xffff0000, v140
	v_pk_fma_f32 v[96:97], v[96:97], s[22:23], v[98:99] op_sel_hi:[1,0,1]
	v_cvt_f32_fp8_sdwa v98, v122 src0_sel:BYTE_2
	v_cvt_f32_fp8_sdwa v99, v122 src0_sel:BYTE_3
	v_cvt_f32_fp8_sdwa v100, v123 src0_sel:BYTE_2
	v_cvt_f32_fp8_sdwa v101, v123 src0_sel:BYTE_3
	v_lshlrev_b32_e32 v106, 16, v139
	v_and_b32_e32 v107, 0xffff0000, v139
	v_pk_fma_f32 v[98:99], v[98:99], s[22:23], v[106:107] op_sel_hi:[1,0,1]
	v_lshlrev_b32_e32 v106, 16, v141
	v_and_b32_e32 v107, 0xffff0000, v141
	v_pk_fma_f32 v[100:101], v[100:101], s[22:23], v[106:107] op_sel_hi:[1,0,1]
	v_pk_add_f32 v[62:63], v[62:63], v[94:95]
	v_pk_add_f32 v[96:97], v[58:59], v[96:97]
	v_cvt_pk_bf16_f32 v58, v62, v63
	v_pk_add_f32 v[64:65], v[64:65], v[98:99]
	v_pk_add_f32 v[94:95], v[60:61], v[100:101]
	v_cvt_pk_bf16_f32 v59, v64, v65
	v_cvt_pk_bf16_f32 v60, v96, v97
	v_lshlrev_b32_e32 v98, 16, v58
	v_cvt_pk_bf16_f32 v61, v94, v95
	v_mov_b32_e32 v222, v58
	v_mov_b32_e32 v223, v59
	v_mov_b32_e32 v224, v60
	v_mov_b32_e32 v225, v61
	v_sub_f32_e32 v98, v62, v98
	v_mul_f32_e32 v98, 0x45800000, v98
	v_and_b32_e32 v58, 0xffff0000, v58
	v_sub_f32_e32 v58, v63, v58
	v_mul_f32_e32 v58, 0x45800000, v58
	v_med3_f32 v98, v98, s3, v206
	v_med3_f32 v106, v58, s3, v206
	v_mov_b32_e32 v58, v1
	v_lshlrev_b32_e32 v99, 16, v59
	v_and_b32_e32 v59, 0xffff0000, v59
	v_cvt_pk_fp8_f32 v58, v98, v106
	v_sub_f32_e32 v59, v65, v59
	v_sub_f32_e32 v99, v64, v99
	v_mul_f32_e32 v99, 0x45800000, v99
	v_mul_f32_e32 v59, 0x45800000, v59
	v_lshlrev_b32_e32 v100, 16, v60
	v_and_b32_e32 v60, 0xffff0000, v60
	v_med3_f32 v98, v99, s3, v206
	v_med3_f32 v59, v59, s3, v206
	v_lshlrev_b32_e32 v101, 16, v61
	v_cvt_pk_fp8_f32 v58, v98, v59 op_sel:[0,0,1]
	v_sub_f32_e32 v60, v97, v60
	v_sub_f32_e32 v98, v96, v100
	v_sub_f32_e32 v59, v94, v101
	v_mul_f32_e32 v98, 0x45800000, v98
	v_mul_f32_e32 v60, 0x45800000, v60
	v_med3_f32 v98, v98, s3, v206
	v_med3_f32 v60, v60, s3, v206
	v_mul_f32_e32 v99, 0x45800000, v59
	v_mov_b32_e32 v59, v1
	v_and_b32_e32 v61, 0xffff0000, v61
	v_cvt_pk_fp8_f32 v59, v98, v60
	v_sub_f32_e32 v61, v95, v61
	v_mul_f32_e32 v61, 0x45800000, v61
	v_med3_f32 v60, v99, s3, v206
	v_med3_f32 v61, v61, s3, v206
	v_cvt_pk_fp8_f32 v59, v60, v61 op_sel:[0,0,1]
	v_mul_f32_e32 v60, v63, v63
	v_mul_f32_e32 v61, v65, v65
	v_fmac_f32_e32 v60, v62, v62
	v_fmac_f32_e32 v61, v64, v64
	v_add_f32_e32 v60, v60, v61
	v_mul_f32_e32 v61, v97, v97
	v_mul_f32_e32 v62, v95, v95
	v_fmac_f32_e32 v61, v96, v96
	v_fmac_f32_e32 v62, v94, v94
	v_add_f32_e32 v61, v61, v62
	v_add_f32_e32 v98, v60, v61
	v_cvt_f32_fp8_e32 v60, v124
	v_cvt_f32_fp8_sdwa v61, v124 src0_sel:BYTE_1
	v_cvt_f32_fp8_e32 v62, v125
	v_cvt_f32_fp8_sdwa v63, v125 src0_sel:BYTE_1
	s_waitcnt vmcnt(15)
	v_lshlrev_b32_e32 v64, 16, v134
	v_and_b32_e32 v65, 0xffff0000, v134
	v_pk_fma_f32 v[60:61], v[60:61], s[22:23], v[64:65] op_sel_hi:[1,0,1]
	v_lshlrev_b32_e32 v64, 16, v136
	v_and_b32_e32 v65, 0xffff0000, v136
	v_pk_fma_f32 v[62:63], v[62:63], s[22:23], v[64:65] op_sel_hi:[1,0,1]
	v_cvt_f32_fp8_sdwa v64, v124 src0_sel:BYTE_2
	v_cvt_f32_fp8_sdwa v65, v124 src0_sel:BYTE_3
	v_cvt_f32_fp8_sdwa v94, v125 src0_sel:BYTE_2
	v_cvt_f32_fp8_sdwa v95, v125 src0_sel:BYTE_3
	v_lshlrev_b32_e32 v96, 16, v135
	v_and_b32_e32 v97, 0xffff0000, v135
	v_pk_fma_f32 v[64:65], v[64:65], s[22:23], v[96:97] op_sel_hi:[1,0,1]
	v_lshlrev_b32_e32 v96, 16, v137
	v_and_b32_e32 v97, 0xffff0000, v137
	v_pk_fma_f32 v[94:95], v[94:95], s[22:23], v[96:97] op_sel_hi:[1,0,1]
	v_pk_add_f32 v[56:57], v[56:57], v[64:65]
	v_pk_add_f32 v[64:65], v[54:55], v[60:61]
	v_pk_add_f32 v[94:95], v[52:53], v[94:95]
	v_cvt_pk_bf16_f32 v52, v64, v65
	v_pk_add_f32 v[50:51], v[50:51], v[62:63]
	v_lshlrev_b32_e32 v60, 16, v52
	v_and_b32_e32 v61, 0xffff0000, v52
	v_sub_f32_e32 v60, v64, v60
	v_sub_f32_e32 v61, v65, v61
	v_mul_f32_e32 v60, 0x45800000, v60
	v_med3_f32 v101, v60, s3, v206
	v_mul_f32_e32 v60, 0x45800000, v61
	v_cvt_pk_bf16_f32 v53, v56, v57
	v_med3_f32 v61, v60, s3, v206
	v_lshlrev_b32_e32 v62, 16, v53
	v_mov_b32_e32 v60, v1
	v_and_b32_e32 v63, 0xffff0000, v53
	v_sub_f32_e32 v62, v56, v62
	v_cvt_pk_fp8_f32 v60, v101, v61
	v_sub_f32_e32 v63, v57, v63
	v_mul_f32_e32 v62, 0x45800000, v62
	v_cvt_pk_bf16_f32 v54, v50, v51
	v_med3_f32 v61, v62, s3, v206
	v_lshlrev_b32_e32 v96, 16, v54
	v_and_b32_e32 v97, 0xffff0000, v54
	v_mul_f32_e32 v62, 0x45800000, v63
	v_cvt_pk_bf16_f32 v55, v94, v95
	v_med3_f32 v62, v62, s3, v206
	v_lshlrev_b32_e32 v99, 16, v55
	v_sub_f32_e32 v63, v51, v97
	v_sub_f32_e32 v96, v50, v96
	v_cvt_pk_fp8_f32 v60, v61, v62 op_sel:[0,0,1]
	v_sub_f32_e32 v61, v94, v99
	v_mul_f32_e32 v96, 0x45800000, v96
	v_mul_f32_e32 v63, 0x45800000, v63
	v_med3_f32 v96, v96, s3, v206
	v_med3_f32 v63, v63, s3, v206
	v_mul_f32_e32 v97, 0x45800000, v61
	v_mov_b32_e32 v61, v1
	v_mul_f32_e32 v51, v51, v51
	v_cvt_pk_fp8_f32 v61, v96, v63
	v_mul_f32_e32 v63, v65, v65
	v_mul_f32_e32 v57, v57, v57
	v_fmac_f32_e32 v51, v50, v50
	v_mul_f32_e32 v50, v95, v95
	v_fmac_f32_e32 v63, v64, v64
	v_fmac_f32_e32 v57, v56, v56
	v_fmac_f32_e32 v50, v94, v94
	v_add_f32_e32 v56, v63, v57
	v_add_f32_e32 v50, v51, v50
	v_add_f32_e32 v50, v56, v50
	v_add_f32_e32 v50, v98, v50
	ds_bpermute_b32 v51, v150, v50
	v_and_b32_e32 v100, 0xffff0000, v55
	v_sub_f32_e32 v62, v95, v100
	v_mul_f32_e32 v57, 0x45800000, v62
	v_med3_f32 v56, v97, s3, v206
	s_waitcnt lgkmcnt(0)
	v_add_f32_e32 v50, v50, v51
	ds_bpermute_b32 v51, v151, v50
	v_med3_f32 v57, v57, s3, v206
	v_cvt_pk_fp8_f32 v61, v56, v57 op_sel:[0,0,1]
	s_mov_b64 s[30:31], 0x20000
	v_lshl_add_u64 v[56:57], v[174:175], 0, s[30:31]
	v_mov_b32_e32 v226, v52
	v_mov_b32_e32 v227, v53
	v_mov_b32_e32 v228, v54
	v_mov_b32_e32 v229, v55
	s_nop 1
	v_permlane16_swap_b32_e32 v222, v226
	v_permlane16_swap_b32_e32 v223, v227
	v_permlane16_swap_b32_e32 v224, v228
	v_permlane16_swap_b32_e32 v225, v229
	v_permlane32_swap_b32_e32 v222, v226
	v_permlane32_swap_b32_e32 v223, v227
	v_permlane32_swap_b32_e32 v224, v228
	v_permlane32_swap_b32_e32 v225, v229
	v_lshl_add_u64 v[230:231], v[148:149], 0, v[232:233]
	global_store_dwordx4 v[230:231], v[222:225], off
	global_store_dwordx4 v[230:231], v[226:229], off offset:64
	global_store_dwordx4 v[56:57], v[58:61], off
	s_and_saveexec_b64 s[36:37], s[40:41]
	s_cbranch_execz .LBB0_90
	v_add_u32_e32 v52, 0x80, v172
	v_ashrrev_i32_e32 v53, 31, v52
	s_waitcnt lgkmcnt(0)
	v_add_f32_e32 v54, v50, v51
	v_lshlrev_b64 v[50:51], 6, v[52:53]
	v_lshl_add_u64 v[50:51], s[46:47], 0, v[50:51]
	v_lshl_add_u64 v[50:51], s[62:63], 2, v[50:51]
	s_lshl_b32 s24, s72, 2
	v_lshl_add_u64 v[50:51], v[50:51], 0, s[24:25]
	global_store_dword v[50:51], v54, off
; __device__ __forceinline__ u32x4 pack8(f32x4 a, f32x4 b) { u32x4 w; w.x = cvt_pk_bf16(a[0], a[1]); w.y = cvt_pk_bf16(a[2], a[3]); w.z = cvt_pk_bf16(b[0], b[1]); w.w = cvt_pk_bf16(b[2], b[3]); return w; }
; __device__ __forceinline__ void unpack8(u32x4 w, f32x4& a, f32x4& b) { a = (f32x4){bf_lo(w.x), bf_hi(w.x), bf_lo(w.y), bf_hi(w.y)}; b = (f32x4){bf_lo(w.z), bf_hi(w.z), bf_lo(w.w), bf_hi(w.w)}; }
; __device__ __forceinline__ float lo_dec(unsigned w, int i) { return (i == 0 ? __builtin_amdgcn_cvt_f32_fp8(w, 0) : i == 1 ? __builtin_amdgcn_cvt_f32_fp8(w, 1) : i == 2 ? __builtin_amdgcn_cvt_f32_fp8(w, 2) : __builtin_amdgcn_cvt_f32_fp8(w, 3)) * (1.0f / 4096.0f); }
;     __device__ __forceinline__ void operator()(const f32x4 (&acc)[2][2][4][2], const Unit& u, int wr, int wc, int fr_, int fq_) const {
;     ...
;                     u32x4 lo_out; float ss = 0.f;
; #pragma unroll
;                     for (int bj = 0; bj < 2; ++bj) {
;                         f32x4 a, b; unpack8(bj ? h1[k & 1][j] : h0[k & 1][j], a, b);
; #pragma unroll
;                         for (int i = 0; i < 4; ++i) { a[i] += lo_dec(lw[k & 1][j][2 * bj], i); b[i] += lo_dec(lw[k & 1][j][2 * bj + 1], i); }
;                         a = a + acc[ai][bj][m][0]; b = b + acc[ai][bj][m][1];
;                         const u32x4 hw = pack8(a, b);
;                         *(u32x4*)(XH + off + 8 * bj) = hw;
;                         f32x4 ra, rb; unpack8(hw, ra, rb);
;                         lo_out[2 * bj] = lo_enc(a - ra); lo_out[2 * bj + 1] = lo_enc(b - rb);
;                         ss += ((a[0] * a[0] + a[1] * a[1]) + (a[2] * a[2] + a[3] * a[3])) + ((b[0] * b[0] + b[1] * b[1]) + (b[2] * b[2] + b[3] * b[3]));
;                     }
;                     *(u32x4*)(XL + off) = lo_out;
;                     ss += __shfl_xor(ss, 16); ss += __shfl_xor(ss, 32);
;                     if (fq == 0) SSo[(size_t)(u.pm * 256 + ai * 128 + wr * 64 + m * 16 + fr) * 16 + 4 * u.pn + wc] = ss;
.LBB0_90:
	s_or_b64 exec, exec, s[36:37]
	s_waitcnt vmcnt(15)
	v_cvt_f32_fp8_e32 v50, v110
	s_waitcnt lgkmcnt(0)
	v_cvt_f32_fp8_sdwa v51, v110 src0_sel:BYTE_1
	v_cvt_f32_fp8_e32 v52, v111
	v_cvt_f32_fp8_sdwa v53, v111 src0_sel:BYTE_1
	v_lshlrev_b32_e32 v54, 16, v118
	v_and_b32_e32 v55, 0xffff0000, v118
	v_pk_fma_f32 v[50:51], v[50:51], s[22:23], v[54:55] op_sel_hi:[1,0,1]
	v_lshlrev_b32_e32 v54, 16, v120
	v_and_b32_e32 v55, 0xffff0000, v120
	v_pk_fma_f32 v[52:53], v[52:53], s[22:23], v[54:55] op_sel_hi:[1,0,1]
	v_cvt_f32_fp8_sdwa v54, v110 src0_sel:BYTE_2
	v_cvt_f32_fp8_sdwa v55, v110 src0_sel:BYTE_3
	v_cvt_f32_fp8_sdwa v56, v111 src0_sel:BYTE_2
	v_cvt_f32_fp8_sdwa v57, v111 src0_sel:BYTE_3
	v_lshlrev_b32_e32 v58, 16, v119
	v_and_b32_e32 v59, 0xffff0000, v119
	v_pk_fma_f32 v[54:55], v[54:55], s[22:23], v[58:59] op_sel_hi:[1,0,1]
	v_lshlrev_b32_e32 v58, 16, v121
	v_and_b32_e32 v59, 0xffff0000, v121
	v_pk_fma_f32 v[56:57], v[56:57], s[22:23], v[58:59] op_sel_hi:[1,0,1]
	v_pk_add_f32 v[46:47], v[46:47], v[50:51]
	v_pk_add_f32 v[52:53], v[42:43], v[52:53]
	v_cvt_pk_bf16_f32 v42, v46, v47
	v_pk_add_f32 v[48:49], v[48:49], v[54:55]
	v_pk_add_f32 v[50:51], v[44:45], v[56:57]
	v_cvt_pk_bf16_f32 v43, v48, v49
	v_cvt_pk_bf16_f32 v44, v52, v53
	v_lshlrev_b32_e32 v54, 16, v42
	v_cvt_pk_bf16_f32 v45, v50, v51
	v_mov_b32_e32 v222, v42
	v_mov_b32_e32 v223, v43
	v_mov_b32_e32 v224, v44
	v_mov_b32_e32 v225, v45
	v_sub_f32_e32 v54, v46, v54
	v_mul_f32_e32 v54, 0x45800000, v54
	v_and_b32_e32 v42, 0xffff0000, v42
	v_sub_f32_e32 v42, v47, v42
	v_mul_f32_e32 v42, 0x45800000, v42
	v_med3_f32 v54, v54, s3, v206
	v_med3_f32 v58, v42, s3, v206
	v_mov_b32_e32 v42, v1
	v_lshlrev_b32_e32 v55, 16, v43
	v_and_b32_e32 v43, 0xffff0000, v43
	v_cvt_pk_fp8_f32 v42, v54, v58
	v_sub_f32_e32 v43, v49, v43
	v_sub_f32_e32 v55, v48, v55
	v_mul_f32_e32 v55, 0x45800000, v55
	v_mul_f32_e32 v43, 0x45800000, v43
	v_lshlrev_b32_e32 v56, 16, v44
	v_and_b32_e32 v44, 0xffff0000, v44
	v_med3_f32 v54, v55, s3, v206
	v_med3_f32 v43, v43, s3, v206
	v_lshlrev_b32_e32 v57, 16, v45
	v_cvt_pk_fp8_f32 v42, v54, v43 op_sel:[0,0,1]
	v_sub_f32_e32 v44, v53, v44
	v_sub_f32_e32 v54, v52, v56
	v_sub_f32_e32 v43, v50, v57
	v_mul_f32_e32 v54, 0x45800000, v54
	v_mul_f32_e32 v44, 0x45800000, v44
	v_med3_f32 v54, v54, s3, v206
	v_med3_f32 v44, v44, s3, v206
	v_mul_f32_e32 v55, 0x45800000, v43
	v_mov_b32_e32 v43, v1
	v_and_b32_e32 v45, 0xffff0000, v45
	v_cvt_pk_fp8_f32 v43, v54, v44
	v_sub_f32_e32 v45, v51, v45
	v_mul_f32_e32 v45, 0x45800000, v45
	v_med3_f32 v44, v55, s3, v206
	v_med3_f32 v45, v45, s3, v206
	v_cvt_pk_fp8_f32 v43, v44, v45 op_sel:[0,0,1]
	v_mul_f32_e32 v44, v47, v47
	v_mul_f32_e32 v45, v49, v49
	v_fmac_f32_e32 v44, v46, v46
	v_fmac_f32_e32 v45, v48, v48
	v_add_f32_e32 v44, v44, v45
	v_mul_f32_e32 v45, v53, v53
	v_mul_f32_e32 v46, v51, v51
	v_fmac_f32_e32 v45, v52, v52
	v_fmac_f32_e32 v46, v50, v50
	v_add_f32_e32 v45, v45, v46
	v_add_f32_e32 v54, v44, v45
	v_cvt_f32_fp8_e32 v44, v112
	v_cvt_f32_fp8_sdwa v45, v112 src0_sel:BYTE_1
	v_cvt_f32_fp8_e32 v46, v113
	v_cvt_f32_fp8_sdwa v47, v113 src0_sel:BYTE_1
	v_lshlrev_b32_e32 v48, 16, v102
	v_and_b32_e32 v49, 0xffff0000, v102
	v_pk_fma_f32 v[44:45], v[44:45], s[22:23], v[48:49] op_sel_hi:[1,0,1]
	v_lshlrev_b32_e32 v48, 16, v104
	v_and_b32_e32 v49, 0xffff0000, v104
	v_pk_fma_f32 v[46:47], v[46:47], s[22:23], v[48:49] op_sel_hi:[1,0,1]
	v_cvt_f32_fp8_sdwa v48, v112 src0_sel:BYTE_2
	v_cvt_f32_fp8_sdwa v49, v112 src0_sel:BYTE_3
	v_cvt_f32_fp8_sdwa v50, v113 src0_sel:BYTE_2
	v_cvt_f32_fp8_sdwa v51, v113 src0_sel:BYTE_3
	v_lshlrev_b32_e32 v52, 16, v103
	v_and_b32_e32 v53, 0xffff0000, v103
	v_pk_fma_f32 v[48:49], v[48:49], s[22:23], v[52:53] op_sel_hi:[1,0,1]
	v_lshlrev_b32_e32 v52, 16, v105
	v_and_b32_e32 v53, 0xffff0000, v105
	v_pk_fma_f32 v[50:51], v[50:51], s[22:23], v[52:53] op_sel_hi:[1,0,1]
	v_pk_add_f32 v[40:41], v[40:41], v[48:49]
	v_pk_add_f32 v[48:49], v[38:39], v[44:45]
	v_pk_add_f32 v[50:51], v[36:37], v[50:51]
	v_cvt_pk_bf16_f32 v36, v48, v49
	v_pk_add_f32 v[34:35], v[34:35], v[46:47]
	v_lshlrev_b32_e32 v44, 16, v36
	v_and_b32_e32 v45, 0xffff0000, v36
	v_sub_f32_e32 v44, v48, v44
	v_sub_f32_e32 v45, v49, v45
	v_mul_f32_e32 v44, 0x45800000, v44
	v_med3_f32 v57, v44, s3, v206
	v_mul_f32_e32 v44, 0x45800000, v45
	v_cvt_pk_bf16_f32 v37, v40, v41
	v_med3_f32 v45, v44, s3, v206
	v_lshlrev_b32_e32 v46, 16, v37
	v_mov_b32_e32 v44, v1
	v_and_b32_e32 v47, 0xffff0000, v37
	v_sub_f32_e32 v46, v40, v46
	v_cvt_pk_fp8_f32 v44, v57, v45
	v_sub_f32_e32 v47, v41, v47
	v_mul_f32_e32 v46, 0x45800000, v46
	v_cvt_pk_bf16_f32 v38, v34, v35
	v_med3_f32 v45, v46, s3, v206
	v_lshlrev_b32_e32 v52, 16, v38
	v_and_b32_e32 v53, 0xffff0000, v38
	v_mul_f32_e32 v46, 0x45800000, v47
	v_cvt_pk_bf16_f32 v39, v50, v51
	v_med3_f32 v46, v46, s3, v206
	v_lshlrev_b32_e32 v55, 16, v39
	v_sub_f32_e32 v47, v35, v53
	v_sub_f32_e32 v52, v34, v52
	v_cvt_pk_fp8_f32 v44, v45, v46 op_sel:[0,0,1]
	v_sub_f32_e32 v45, v50, v55
	v_mul_f32_e32 v52, 0x45800000, v52
	v_mul_f32_e32 v47, 0x45800000, v47
	v_med3_f32 v52, v52, s3, v206
	v_med3_f32 v47, v47, s3, v206
	v_mul_f32_e32 v53, 0x45800000, v45
	v_mov_b32_e32 v45, v1
	v_mul_f32_e32 v35, v35, v35
	v_cvt_pk_fp8_f32 v45, v52, v47
	v_mul_f32_e32 v47, v49, v49
	v_mul_f32_e32 v41, v41, v41
	v_fmac_f32_e32 v35, v34, v34
	v_mul_f32_e32 v34, v51, v51
	v_fmac_f32_e32 v47, v48, v48
	v_fmac_f32_e32 v41, v40, v40
	v_fmac_f32_e32 v34, v50, v50
	v_add_f32_e32 v40, v47, v41
	v_add_f32_e32 v34, v35, v34
	v_add_f32_e32 v34, v40, v34
	v_add_f32_e32 v34, v54, v34
	ds_bpermute_b32 v35, v150, v34
	v_and_b32_e32 v56, 0xffff0000, v39
	v_sub_f32_e32 v46, v51, v56
	v_mul_f32_e32 v41, 0x45800000, v46
	v_med3_f32 v40, v53, s3, v206
	s_waitcnt lgkmcnt(0)
	v_add_f32_e32 v34, v34, v35
	ds_bpermute_b32 v35, v151, v34
	v_med3_f32 v41, v41, s3, v206
	v_cvt_pk_fp8_f32 v45, v40, v41 op_sel:[0,0,1]
	s_mov_b64 s[30:31], 0x24000
	v_lshl_add_u64 v[40:41], v[174:175], 0, s[30:31]
	v_mov_b32_e32 v226, v36
	v_mov_b32_e32 v227, v37
	v_mov_b32_e32 v228, v38
	v_mov_b32_e32 v229, v39
	s_nop 1
	v_permlane16_swap_b32_e32 v222, v226
	v_permlane16_swap_b32_e32 v223, v227
	v_permlane16_swap_b32_e32 v224, v228
	v_permlane16_swap_b32_e32 v225, v229
	v_permlane32_swap_b32_e32 v222, v226
	v_permlane32_swap_b32_e32 v223, v227
	v_permlane32_swap_b32_e32 v224, v228
	v_permlane32_swap_b32_e32 v225, v229
	v_lshl_add_u64 v[230:231], v[146:147], 0, v[232:233]
	global_store_dwordx4 v[230:231], v[222:225], off
	global_store_dwordx4 v[230:231], v[226:229], off offset:64
	global_store_dwordx4 v[40:41], v[42:45], off
	s_and_saveexec_b64 s[36:37], s[40:41]
	s_cbranch_execz .LBB0_92
	s_waitcnt lgkmcnt(0)
	v_add_f32_e32 v36, v34, v35
	v_add_u32_e32 v34, 0x90, v172
	v_ashrrev_i32_e32 v35, 31, v34
	v_lshlrev_b64 v[34:35], 6, v[34:35]
	v_lshl_add_u64 v[34:35], s[46:47], 0, v[34:35]
	v_lshl_add_u64 v[34:35], s[62:63], 2, v[34:35]
	s_lshl_b32 s24, s72, 2
	v_lshl_add_u64 v[34:35], v[34:35], 0, s[24:25]
	global_store_dword v[34:35], v36, off
; __device__ __forceinline__ u32x4 pack8(f32x4 a, f32x4 b) { u32x4 w; w.x = cvt_pk_bf16(a[0], a[1]); w.y = cvt_pk_bf16(a[2], a[3]); w.z = cvt_pk_bf16(b[0], b[1]); w.w = cvt_pk_bf16(b[2], b[3]); return w; }
; __device__ __forceinline__ void unpack8(u32x4 w, f32x4& a, f32x4& b) { a = (f32x4){bf_lo(w.x), bf_hi(w.x), bf_lo(w.y), bf_hi(w.y)}; b = (f32x4){bf_lo(w.z), bf_hi(w.z), bf_lo(w.w), bf_hi(w.w)}; }
; __device__ __forceinline__ float lo_dec(unsigned w, int i) { return (i == 0 ? __builtin_amdgcn_cvt_f32_fp8(w, 0) : i == 1 ? __builtin_amdgcn_cvt_f32_fp8(w, 1) : i == 2 ? __builtin_amdgcn_cvt_f32_fp8(w, 2) : __builtin_amdgcn_cvt_f32_fp8(w, 3)) * (1.0f / 4096.0f); }
;     __device__ __forceinline__ void operator()(const f32x4 (&acc)[2][2][4][2], const Unit& u, int wr, int wc, int fr_, int fq_) const {
;     ...
;                     u32x4 lo_out; float ss = 0.f;
; #pragma unroll
;                     for (int bj = 0; bj < 2; ++bj) {
;                         f32x4 a, b; unpack8(bj ? h1[k & 1][j] : h0[k & 1][j], a, b);
; #pragma unroll
;                         for (int i = 0; i < 4; ++i) { a[i] += lo_dec(lw[k & 1][j][2 * bj], i); b[i] += lo_dec(lw[k & 1][j][2 * bj + 1], i); }
;                         a = a + acc[ai][bj][m][0]; b = b + acc[ai][bj][m][1];
;                         const u32x4 hw = pack8(a, b);
;                         *(u32x4*)(XH + off + 8 * bj) = hw;
;                         f32x4 ra, rb; unpack8(hw, ra, rb);
;                         lo_out[2 * bj] = lo_enc(a - ra); lo_out[2 * bj + 1] = lo_enc(b - rb);
;                         ss += ((a[0] * a[0] + a[1] * a[1]) + (a[2] * a[2] + a[3] * a[3])) + ((b[0] * b[0] + b[1] * b[1]) + (b[2] * b[2] + b[3] * b[3]));
;                     }
;                     *(u32x4*)(XL + off) = lo_out;
;                     ss += __shfl_xor(ss, 16); ss += __shfl_xor(ss, 32);
;                     if (fq == 0) SSo[(size_t)(u.pm * 256 + ai * 128 + wr * 64 + m * 16 + fr) * 16 + 4 * u.pn + wc] = ss;
.LBB0_92:
	s_or_b64 exec, exec, s[36:37]
	s_waitcnt vmcnt(10)
	v_cvt_f32_fp8_e32 v34, v78
	s_waitcnt lgkmcnt(0)
	v_cvt_f32_fp8_sdwa v35, v78 src0_sel:BYTE_1
	v_cvt_f32_fp8_e32 v36, v79
	v_cvt_f32_fp8_sdwa v37, v79 src0_sel:BYTE_1
	v_lshlrev_b32_e32 v38, 16, v86
	v_and_b32_e32 v39, 0xffff0000, v86
	v_pk_fma_f32 v[34:35], v[34:35], s[22:23], v[38:39] op_sel_hi:[1,0,1]
	v_lshlrev_b32_e32 v38, 16, v88
	v_and_b32_e32 v39, 0xffff0000, v88
	v_pk_fma_f32 v[36:37], v[36:37], s[22:23], v[38:39] op_sel_hi:[1,0,1]
	v_cvt_f32_fp8_sdwa v38, v78 src0_sel:BYTE_2
	v_cvt_f32_fp8_sdwa v39, v78 src0_sel:BYTE_3
	v_cvt_f32_fp8_sdwa v40, v79 src0_sel:BYTE_2
	v_cvt_f32_fp8_sdwa v41, v79 src0_sel:BYTE_3
	v_lshlrev_b32_e32 v42, 16, v87
	v_and_b32_e32 v43, 0xffff0000, v87
	v_pk_fma_f32 v[38:39], v[38:39], s[22:23], v[42:43] op_sel_hi:[1,0,1]
	v_lshlrev_b32_e32 v42, 16, v89
	v_and_b32_e32 v43, 0xffff0000, v89
	v_pk_fma_f32 v[40:41], v[40:41], s[22:23], v[42:43] op_sel_hi:[1,0,1]
	v_pk_add_f32 v[30:31], v[30:31], v[34:35]
	v_pk_add_f32 v[36:37], v[26:27], v[36:37]
	v_cvt_pk_bf16_f32 v26, v30, v31
	v_pk_add_f32 v[32:33], v[32:33], v[38:39]
	v_pk_add_f32 v[34:35], v[28:29], v[40:41]
	v_cvt_pk_bf16_f32 v27, v32, v33
	v_cvt_pk_bf16_f32 v28, v36, v37
	v_lshlrev_b32_e32 v38, 16, v26
	v_cvt_pk_bf16_f32 v29, v34, v35
	v_mov_b32_e32 v222, v26
	v_mov_b32_e32 v223, v27
	v_mov_b32_e32 v224, v28
	v_mov_b32_e32 v225, v29
	v_sub_f32_e32 v38, v30, v38
	v_mul_f32_e32 v38, 0x45800000, v38
	v_and_b32_e32 v26, 0xffff0000, v26
	v_sub_f32_e32 v26, v31, v26
	v_mul_f32_e32 v26, 0x45800000, v26
	v_med3_f32 v38, v38, s3, v206
	v_med3_f32 v42, v26, s3, v206
	v_mov_b32_e32 v26, v1
	v_lshlrev_b32_e32 v39, 16, v27
	v_and_b32_e32 v27, 0xffff0000, v27
	v_cvt_pk_fp8_f32 v26, v38, v42
	v_sub_f32_e32 v27, v33, v27
	v_sub_f32_e32 v39, v32, v39
	v_mul_f32_e32 v39, 0x45800000, v39
	v_mul_f32_e32 v27, 0x45800000, v27
	v_lshlrev_b32_e32 v40, 16, v28
	v_and_b32_e32 v28, 0xffff0000, v28
	v_med3_f32 v38, v39, s3, v206
	v_med3_f32 v27, v27, s3, v206
	v_lshlrev_b32_e32 v41, 16, v29
	v_cvt_pk_fp8_f32 v26, v38, v27 op_sel:[0,0,1]
	v_sub_f32_e32 v28, v37, v28
	v_sub_f32_e32 v38, v36, v40
	v_sub_f32_e32 v27, v34, v41
	v_mul_f32_e32 v38, 0x45800000, v38
	v_mul_f32_e32 v28, 0x45800000, v28
	v_med3_f32 v38, v38, s3, v206
	v_med3_f32 v28, v28, s3, v206
	v_mul_f32_e32 v39, 0x45800000, v27
	v_mov_b32_e32 v27, v1
	v_and_b32_e32 v29, 0xffff0000, v29
	v_cvt_pk_fp8_f32 v27, v38, v28
	v_sub_f32_e32 v29, v35, v29
	v_mul_f32_e32 v29, 0x45800000, v29
	v_med3_f32 v28, v39, s3, v206
	v_med3_f32 v29, v29, s3, v206
	v_cvt_pk_fp8_f32 v27, v28, v29 op_sel:[0,0,1]
	v_mul_f32_e32 v28, v31, v31
	v_mul_f32_e32 v29, v33, v33
	v_fmac_f32_e32 v28, v30, v30
	v_fmac_f32_e32 v29, v32, v32
	v_add_f32_e32 v28, v28, v29
	v_mul_f32_e32 v29, v37, v37
	v_mul_f32_e32 v30, v35, v35
	v_fmac_f32_e32 v29, v36, v36
	v_fmac_f32_e32 v30, v34, v34
	v_add_f32_e32 v29, v29, v30
	v_add_f32_e32 v38, v28, v29
	v_cvt_f32_fp8_e32 v28, v80
	v_cvt_f32_fp8_sdwa v29, v80 src0_sel:BYTE_1
	v_cvt_f32_fp8_e32 v30, v81
	v_cvt_f32_fp8_sdwa v31, v81 src0_sel:BYTE_1
	s_waitcnt vmcnt(9)
	v_lshlrev_b32_e32 v32, 16, v82
	v_and_b32_e32 v33, 0xffff0000, v82
	v_pk_fma_f32 v[28:29], v[28:29], s[22:23], v[32:33] op_sel_hi:[1,0,1]
	v_lshlrev_b32_e32 v32, 16, v84
	v_and_b32_e32 v33, 0xffff0000, v84
	v_pk_fma_f32 v[30:31], v[30:31], s[22:23], v[32:33] op_sel_hi:[1,0,1]
	v_cvt_f32_fp8_sdwa v32, v80 src0_sel:BYTE_2
	v_cvt_f32_fp8_sdwa v33, v80 src0_sel:BYTE_3
	v_cvt_f32_fp8_sdwa v34, v81 src0_sel:BYTE_2
	v_cvt_f32_fp8_sdwa v35, v81 src0_sel:BYTE_3
	v_lshlrev_b32_e32 v36, 16, v83
	v_and_b32_e32 v37, 0xffff0000, v83
	v_pk_fma_f32 v[32:33], v[32:33], s[22:23], v[36:37] op_sel_hi:[1,0,1]
	v_lshlrev_b32_e32 v36, 16, v85
	v_and_b32_e32 v37, 0xffff0000, v85
	v_pk_fma_f32 v[34:35], v[34:35], s[22:23], v[36:37] op_sel_hi:[1,0,1]
	v_pk_add_f32 v[24:25], v[24:25], v[32:33]
	v_pk_add_f32 v[32:33], v[22:23], v[28:29]
	v_pk_add_f32 v[34:35], v[20:21], v[34:35]
	v_cvt_pk_bf16_f32 v20, v32, v33
	v_pk_add_f32 v[18:19], v[18:19], v[30:31]
	v_lshlrev_b32_e32 v28, 16, v20
	v_and_b32_e32 v29, 0xffff0000, v20
	v_sub_f32_e32 v28, v32, v28
	v_sub_f32_e32 v29, v33, v29
	v_mul_f32_e32 v28, 0x45800000, v28
	v_med3_f32 v41, v28, s3, v206
	v_mul_f32_e32 v28, 0x45800000, v29
	v_cvt_pk_bf16_f32 v21, v24, v25
	v_med3_f32 v29, v28, s3, v206
	v_lshlrev_b32_e32 v30, 16, v21
	v_mov_b32_e32 v28, v1
	v_and_b32_e32 v31, 0xffff0000, v21
	v_sub_f32_e32 v30, v24, v30
	v_cvt_pk_fp8_f32 v28, v41, v29
	v_sub_f32_e32 v31, v25, v31
	v_mul_f32_e32 v30, 0x45800000, v30
	v_cvt_pk_bf16_f32 v22, v18, v19
	v_med3_f32 v29, v30, s3, v206
	v_lshlrev_b32_e32 v36, 16, v22
	v_and_b32_e32 v37, 0xffff0000, v22
	v_mul_f32_e32 v30, 0x45800000, v31
	v_cvt_pk_bf16_f32 v23, v34, v35
	v_med3_f32 v30, v30, s3, v206
	v_lshlrev_b32_e32 v39, 16, v23
	v_sub_f32_e32 v31, v19, v37
	v_sub_f32_e32 v36, v18, v36
	v_cvt_pk_fp8_f32 v28, v29, v30 op_sel:[0,0,1]
	v_sub_f32_e32 v29, v34, v39
	v_mul_f32_e32 v36, 0x45800000, v36
	v_mul_f32_e32 v31, 0x45800000, v31
	v_med3_f32 v36, v36, s3, v206
	v_med3_f32 v31, v31, s3, v206
	v_mul_f32_e32 v37, 0x45800000, v29
	v_mov_b32_e32 v29, v1
	v_mul_f32_e32 v19, v19, v19
	v_cvt_pk_fp8_f32 v29, v36, v31
	v_mul_f32_e32 v31, v33, v33
	v_mul_f32_e32 v25, v25, v25
	v_fmac_f32_e32 v19, v18, v18
	v_mul_f32_e32 v18, v35, v35
	v_fmac_f32_e32 v31, v32, v32
	v_fmac_f32_e32 v25, v24, v24
	v_fmac_f32_e32 v18, v34, v34
	v_add_f32_e32 v24, v31, v25
	v_add_f32_e32 v18, v19, v18
	v_add_f32_e32 v18, v24, v18
	v_add_f32_e32 v18, v38, v18
	ds_bpermute_b32 v19, v150, v18
	v_and_b32_e32 v40, 0xffff0000, v23
	v_sub_f32_e32 v30, v35, v40
	v_mul_f32_e32 v25, 0x45800000, v30
	v_med3_f32 v24, v37, s3, v206
	s_waitcnt lgkmcnt(0)
	v_add_f32_e32 v18, v18, v19
	ds_bpermute_b32 v19, v151, v18
	v_med3_f32 v25, v25, s3, v206
	v_cvt_pk_fp8_f32 v29, v24, v25 op_sel:[0,0,1]
	s_mov_b64 s[30:31], 0x28000
	v_lshl_add_u64 v[24:25], v[174:175], 0, s[30:31]
	v_mov_b32_e32 v226, v20
	v_mov_b32_e32 v227, v21
	v_mov_b32_e32 v228, v22
	v_mov_b32_e32 v229, v23
	s_nop 1
	v_permlane16_swap_b32_e32 v222, v226
	v_permlane16_swap_b32_e32 v223, v227
	v_permlane16_swap_b32_e32 v224, v228
	v_permlane16_swap_b32_e32 v225, v229
	v_permlane32_swap_b32_e32 v222, v226
	v_permlane32_swap_b32_e32 v223, v227
	v_permlane32_swap_b32_e32 v224, v228
	v_permlane32_swap_b32_e32 v225, v229
	v_lshl_add_u64 v[230:231], v[92:93], 0, v[232:233]
	global_store_dwordx4 v[230:231], v[222:225], off
	global_store_dwordx4 v[230:231], v[226:229], off offset:64
	global_store_dwordx4 v[24:25], v[26:29], off
	s_and_saveexec_b64 s[36:37], s[40:41]
	s_cbranch_execz .LBB0_94
	s_waitcnt lgkmcnt(0)
	v_add_f32_e32 v20, v18, v19
	v_add_u32_e32 v18, 0xa0, v172
	v_ashrrev_i32_e32 v19, 31, v18
	v_lshlrev_b64 v[18:19], 6, v[18:19]
	v_lshl_add_u64 v[18:19], s[46:47], 0, v[18:19]
	v_lshl_add_u64 v[18:19], s[62:63], 2, v[18:19]
	s_lshl_b32 s24, s72, 2
	v_lshl_add_u64 v[18:19], v[18:19], 0, s[24:25]
	global_store_dword v[18:19], v20, off
; __device__ __forceinline__ u32x4 pack8(f32x4 a, f32x4 b) { u32x4 w; w.x = cvt_pk_bf16(a[0], a[1]); w.y = cvt_pk_bf16(a[2], a[3]); w.z = cvt_pk_bf16(b[0], b[1]); w.w = cvt_pk_bf16(b[2], b[3]); return w; }
; __device__ __forceinline__ void unpack8(u32x4 w, f32x4& a, f32x4& b) { a = (f32x4){bf_lo(w.x), bf_hi(w.x), bf_lo(w.y), bf_hi(w.y)}; b = (f32x4){bf_lo(w.z), bf_hi(w.z), bf_lo(w.w), bf_hi(w.w)}; }
; __device__ __forceinline__ float lo_dec(unsigned w, int i) { return (i == 0 ? __builtin_amdgcn_cvt_f32_fp8(w, 0) : i == 1 ? __builtin_amdgcn_cvt_f32_fp8(w, 1) : i == 2 ? __builtin_amdgcn_cvt_f32_fp8(w, 2) : __builtin_amdgcn_cvt_f32_fp8(w, 3)) * (1.0f / 4096.0f); }
;     __device__ __forceinline__ void operator()(const f32x4 (&acc)[2][2][4][2], const Unit& u, int wr, int wc, int fr_, int fq_) const {
;     ...
;                     u32x4 lo_out; float ss = 0.f;
; #pragma unroll
;                     for (int bj = 0; bj < 2; ++bj) {
;                         f32x4 a, b; unpack8(bj ? h1[k & 1][j] : h0[k & 1][j], a, b);
; #pragma unroll
;                         for (int i = 0; i < 4; ++i) { a[i] += lo_dec(lw[k & 1][j][2 * bj], i); b[i] += lo_dec(lw[k & 1][j][2 * bj + 1], i); }
;                         a = a + acc[ai][bj][m][0]; b = b + acc[ai][bj][m][1];
;                         const u32x4 hw = pack8(a, b);
;                         *(u32x4*)(XH + off + 8 * bj) = hw;
;                         f32x4 ra, rb; unpack8(hw, ra, rb);
;                         lo_out[2 * bj] = lo_enc(a - ra); lo_out[2 * bj + 1] = lo_enc(b - rb);
;                         ss += ((a[0] * a[0] + a[1] * a[1]) + (a[2] * a[2] + a[3] * a[3])) + ((b[0] * b[0] + b[1] * b[1]) + (b[2] * b[2] + b[3] * b[3]));
;                     }
;                     *(u32x4*)(XL + off) = lo_out;
;                     ss += __shfl_xor(ss, 16); ss += __shfl_xor(ss, 32);
;                     if (fq == 0) SSo[(size_t)(u.pm * 256 + ai * 128 + wr * 64 + m * 16 + fr) * 16 + 4 * u.pn + wc] = ss;
.LBB0_94:
	s_or_b64 exec, exec, s[36:37]
	s_waitcnt vmcnt(9)
	v_cvt_f32_fp8_e32 v18, v70
	s_waitcnt lgkmcnt(0)
	v_cvt_f32_fp8_sdwa v19, v70 src0_sel:BYTE_1
	v_cvt_f32_fp8_e32 v20, v71
	v_cvt_f32_fp8_sdwa v21, v71 src0_sel:BYTE_1
	v_lshlrev_b32_e32 v22, 16, v74
	v_and_b32_e32 v23, 0xffff0000, v74
	v_pk_fma_f32 v[18:19], v[18:19], s[22:23], v[22:23] op_sel_hi:[1,0,1]
	v_lshlrev_b32_e32 v22, 16, v76
	v_and_b32_e32 v23, 0xffff0000, v76
	v_pk_fma_f32 v[20:21], v[20:21], s[22:23], v[22:23] op_sel_hi:[1,0,1]
	v_cvt_f32_fp8_sdwa v22, v70 src0_sel:BYTE_2
	v_cvt_f32_fp8_sdwa v23, v70 src0_sel:BYTE_3
	v_cvt_f32_fp8_sdwa v24, v71 src0_sel:BYTE_2
	v_cvt_f32_fp8_sdwa v25, v71 src0_sel:BYTE_3
	v_lshlrev_b32_e32 v26, 16, v75
	v_and_b32_e32 v27, 0xffff0000, v75
	v_pk_fma_f32 v[22:23], v[22:23], s[22:23], v[26:27] op_sel_hi:[1,0,1]
	v_lshlrev_b32_e32 v26, 16, v77
	v_and_b32_e32 v27, 0xffff0000, v77
	v_pk_fma_f32 v[24:25], v[24:25], s[22:23], v[26:27] op_sel_hi:[1,0,1]
	v_pk_add_f32 v[14:15], v[14:15], v[18:19]
	v_pk_add_f32 v[20:21], v[10:11], v[20:21]
	v_cvt_pk_bf16_f32 v10, v14, v15
	v_pk_add_f32 v[16:17], v[16:17], v[22:23]
	v_pk_add_f32 v[18:19], v[12:13], v[24:25]
	v_cvt_pk_bf16_f32 v11, v16, v17
	v_cvt_pk_bf16_f32 v12, v20, v21
	v_lshlrev_b32_e32 v22, 16, v10
	v_cvt_pk_bf16_f32 v13, v18, v19
	v_mov_b32_e32 v222, v10
	v_mov_b32_e32 v223, v11
	v_mov_b32_e32 v224, v12
	v_mov_b32_e32 v225, v13
	v_sub_f32_e32 v22, v14, v22
	v_mul_f32_e32 v22, 0x45800000, v22
	v_and_b32_e32 v10, 0xffff0000, v10
	v_sub_f32_e32 v10, v15, v10
	v_mul_f32_e32 v10, 0x45800000, v10
	v_med3_f32 v22, v22, s3, v206
	v_med3_f32 v26, v10, s3, v206
	v_mov_b32_e32 v10, v1
	v_lshlrev_b32_e32 v23, 16, v11
	v_and_b32_e32 v11, 0xffff0000, v11
	v_cvt_pk_fp8_f32 v10, v22, v26
	v_sub_f32_e32 v11, v17, v11
	v_sub_f32_e32 v23, v16, v23
	v_mul_f32_e32 v23, 0x45800000, v23
	v_mul_f32_e32 v11, 0x45800000, v11
	v_lshlrev_b32_e32 v24, 16, v12
	v_and_b32_e32 v12, 0xffff0000, v12
	v_med3_f32 v22, v23, s3, v206
	v_med3_f32 v11, v11, s3, v206
	v_lshlrev_b32_e32 v25, 16, v13
	v_cvt_pk_fp8_f32 v10, v22, v11 op_sel:[0,0,1]
	v_sub_f32_e32 v12, v21, v12
	v_sub_f32_e32 v22, v20, v24
	v_sub_f32_e32 v11, v18, v25
	v_mul_f32_e32 v22, 0x45800000, v22
	v_mul_f32_e32 v12, 0x45800000, v12
	v_med3_f32 v22, v22, s3, v206
	v_med3_f32 v12, v12, s3, v206
	v_mul_f32_e32 v23, 0x45800000, v11
	v_mov_b32_e32 v11, v1
	v_and_b32_e32 v13, 0xffff0000, v13
	v_cvt_pk_fp8_f32 v11, v22, v12
	v_sub_f32_e32 v13, v19, v13
	v_mul_f32_e32 v13, 0x45800000, v13
	v_med3_f32 v12, v23, s3, v206
	v_med3_f32 v13, v13, s3, v206
	v_cvt_pk_fp8_f32 v11, v12, v13 op_sel:[0,0,1]
	v_mul_f32_e32 v12, v15, v15
	v_mul_f32_e32 v13, v17, v17
	v_fmac_f32_e32 v12, v14, v14
	v_fmac_f32_e32 v13, v16, v16
	v_add_f32_e32 v12, v12, v13
	v_mul_f32_e32 v13, v21, v21
	v_mul_f32_e32 v14, v19, v19
	v_fmac_f32_e32 v13, v20, v20
	v_fmac_f32_e32 v14, v18, v18
	v_add_f32_e32 v13, v13, v14
	v_add_f32_e32 v22, v12, v13
	v_cvt_f32_fp8_e32 v12, v72
	v_cvt_f32_fp8_sdwa v13, v72 src0_sel:BYTE_1
	v_cvt_f32_fp8_e32 v14, v73
	v_cvt_f32_fp8_sdwa v15, v73 src0_sel:BYTE_1
	v_lshlrev_b32_e32 v16, 16, v66
	v_and_b32_e32 v17, 0xffff0000, v66
	v_pk_fma_f32 v[12:13], v[12:13], s[22:23], v[16:17] op_sel_hi:[1,0,1]
	v_lshlrev_b32_e32 v16, 16, v68
	v_and_b32_e32 v17, 0xffff0000, v68
	v_pk_fma_f32 v[14:15], v[14:15], s[22:23], v[16:17] op_sel_hi:[1,0,1]
	v_cvt_f32_fp8_sdwa v16, v72 src0_sel:BYTE_2
	v_cvt_f32_fp8_sdwa v17, v72 src0_sel:BYTE_3
	v_cvt_f32_fp8_sdwa v18, v73 src0_sel:BYTE_2
	v_cvt_f32_fp8_sdwa v19, v73 src0_sel:BYTE_3
	v_lshlrev_b32_e32 v20, 16, v67
	v_and_b32_e32 v21, 0xffff0000, v67
	v_pk_fma_f32 v[16:17], v[16:17], s[22:23], v[20:21] op_sel_hi:[1,0,1]
	v_lshlrev_b32_e32 v20, 16, v69
	v_and_b32_e32 v21, 0xffff0000, v69
	v_pk_fma_f32 v[18:19], v[18:19], s[22:23], v[20:21] op_sel_hi:[1,0,1]
	v_pk_add_f32 v[8:9], v[8:9], v[16:17]
	v_pk_add_f32 v[16:17], v[6:7], v[12:13]
	v_pk_add_f32 v[18:19], v[4:5], v[18:19]
	v_cvt_pk_bf16_f32 v4, v16, v17
	v_pk_add_f32 v[2:3], v[2:3], v[14:15]
	v_lshlrev_b32_e32 v12, 16, v4
	v_and_b32_e32 v13, 0xffff0000, v4
	v_sub_f32_e32 v12, v16, v12
	v_sub_f32_e32 v13, v17, v13
	v_mul_f32_e32 v12, 0x45800000, v12
	v_med3_f32 v25, v12, s3, v206
	v_mul_f32_e32 v12, 0x45800000, v13
	v_cvt_pk_bf16_f32 v5, v8, v9
	v_med3_f32 v13, v12, s3, v206
	v_lshlrev_b32_e32 v14, 16, v5
	v_mov_b32_e32 v12, v1
	v_and_b32_e32 v15, 0xffff0000, v5
	v_sub_f32_e32 v14, v8, v14
	v_cvt_pk_fp8_f32 v12, v25, v13
	v_sub_f32_e32 v15, v9, v15
	v_mul_f32_e32 v14, 0x45800000, v14
	v_cvt_pk_bf16_f32 v6, v2, v3
	v_med3_f32 v13, v14, s3, v206
	v_lshlrev_b32_e32 v20, 16, v6
	v_and_b32_e32 v21, 0xffff0000, v6
	v_mul_f32_e32 v14, 0x45800000, v15
	v_cvt_pk_bf16_f32 v7, v18, v19
	v_med3_f32 v14, v14, s3, v206
	v_lshlrev_b32_e32 v23, 16, v7
	v_sub_f32_e32 v15, v3, v21
	v_sub_f32_e32 v20, v2, v20
	v_cvt_pk_fp8_f32 v12, v13, v14 op_sel:[0,0,1]
	v_sub_f32_e32 v13, v18, v23
	v_mul_f32_e32 v20, 0x45800000, v20
	v_mul_f32_e32 v15, 0x45800000, v15
	v_med3_f32 v20, v20, s3, v206
	v_med3_f32 v15, v15, s3, v206
	v_mul_f32_e32 v21, 0x45800000, v13
	v_mov_b32_e32 v13, v1
	v_mul_f32_e32 v3, v3, v3
	v_cvt_pk_fp8_f32 v13, v20, v15
	v_mul_f32_e32 v15, v17, v17
	v_mul_f32_e32 v9, v9, v9
	v_fmac_f32_e32 v3, v2, v2
	v_mul_f32_e32 v2, v19, v19
	v_fmac_f32_e32 v15, v16, v16
	v_fmac_f32_e32 v9, v8, v8
	v_fmac_f32_e32 v2, v18, v18
	v_add_f32_e32 v8, v15, v9
	v_add_f32_e32 v2, v3, v2
	v_add_f32_e32 v2, v8, v2
	v_add_f32_e32 v2, v22, v2
	ds_bpermute_b32 v3, v150, v2
	v_and_b32_e32 v24, 0xffff0000, v7
	v_sub_f32_e32 v14, v19, v24
	v_mul_f32_e32 v9, 0x45800000, v14
	v_med3_f32 v8, v21, s3, v206
	s_waitcnt lgkmcnt(0)
	v_add_f32_e32 v2, v2, v3
	ds_bpermute_b32 v3, v151, v2
	v_med3_f32 v9, v9, s3, v206
	v_cvt_pk_fp8_f32 v13, v8, v9 op_sel:[0,0,1]
	s_mov_b64 s[30:31], 0x2c000
	v_lshl_add_u64 v[8:9], v[174:175], 0, s[30:31]
	v_mov_b32_e32 v226, v4
	v_mov_b32_e32 v227, v5
	v_mov_b32_e32 v228, v6
	v_mov_b32_e32 v229, v7
	s_nop 1
	v_permlane16_swap_b32_e32 v222, v226
	v_permlane16_swap_b32_e32 v223, v227
	v_permlane16_swap_b32_e32 v224, v228
	v_permlane16_swap_b32_e32 v225, v229
	v_permlane32_swap_b32_e32 v222, v226
	v_permlane32_swap_b32_e32 v223, v227
	v_permlane32_swap_b32_e32 v224, v228
	v_permlane32_swap_b32_e32 v225, v229
	v_lshl_add_u64 v[230:231], v[90:91], 0, v[232:233]
	global_store_dwordx4 v[230:231], v[222:225], off
	global_store_dwordx4 v[230:231], v[226:229], off offset:64
	global_store_dwordx4 v[8:9], v[10:13], off
	s_and_saveexec_b64 s[36:37], s[40:41]
	s_cbranch_execz .LBB0_96
	s_waitcnt lgkmcnt(0)
	v_add_f32_e32 v4, v2, v3
	v_add_u32_e32 v2, 0xb0, v172
	v_ashrrev_i32_e32 v3, 31, v2
	v_lshlrev_b64 v[2:3], 6, v[2:3]
	v_lshl_add_u64 v[2:3], s[46:47], 0, v[2:3]
	v_lshl_add_u64 v[2:3], s[62:63], 2, v[2:3]
	s_lshl_b32 s24, s72, 2
	v_lshl_add_u64 v[2:3], v[2:3], 0, s[24:25]
	global_store_dword v[2:3], v4, off

; __device__ __forceinline__ u32x4 pack8(f32x4 a, f32x4 b) { u32x4 w; w.x = cvt_pk_bf16(a[0], a[1]); w.y = cvt_pk_bf16(a[2], a[3]); w.z = cvt_pk_bf16(b[0], b[1]); w.w = cvt_pk_bf16(b[2], b[3]); return w; }
;     __device__ __forceinline__ void operator()(const f32x4 (&acc)[2][2][4][2], const Unit& u, int wr, int wc, int fr_, int fq_) const {
;     ...
;         const size_t off0 = (size_t)(u.pm * 256 + wr * 64 + fr) * 1024 + 256 * u.pn + 64 * wc + 16 * fq;
;         u32x4 h0[2][2], h1[2][2], lw[2][2];
; #pragma unroll
;         for (int k = 0; k < 6; ++k) {
;             if (k >= 2) {
; #pragma unroll
;                 for (int j = 0; j < 2; ++j) {
;                     const int kb = k - 2, ai = kb >> 1, m = (kb & 1) * 2 + j;
;                     const size_t off = off0 + (size_t)(ai * 128 + m * 16) * 1024;
;                     u32x4 lo_out; float ss = 0.f;
; #pragma unroll
;                     for (int bj = 0; bj < 2; ++bj) {
;                         f32x4 a, b; unpack8(bj ? h1[k & 1][j] : h0[k & 1][j], a, b);
; #pragma unroll
;                         for (int i = 0; i < 4; ++i) { a[i] += lo_dec(lw[k & 1][j][2 * bj], i); b[i] += lo_dec(lw[k & 1][j][2 * bj + 1], i); }
;                         a = a + acc[ai][bj][m][0]; b = b + acc[ai][bj][m][1];
;                         const u32x4 hw = pack8(a, b);
;                         *(u32x4*)(XH + off + 8 * bj) = hw;
;                         f32x4 ra, rb; unpack8(hw, ra, rb);
;                         lo_out[2 * bj] = lo_enc(a - ra); lo_out[2 * bj + 1] = lo_enc(b - rb);
;                         ss += ((a[0] * a[0] + a[1] * a[1]) + (a[2] * a[2] + a[3] * a[3])) + ((b[0] * b[0] + b[1] * b[1]) + (b[2] * b[2] + b[3] * b[3]));
;                     }
;                     *(u32x4*)(XL + off) = lo_out;
;                     ss += __shfl_xor(ss, 16); ss += __shfl_xor(ss, 32);
;                     if (fq == 0) SSo[(size_t)(u.pm * 256 + ai * 128 + wr * 64 + m * 16 + fr) * 16 + 4 * u.pn + wc] = ss;
;                 }
;             }
;             if (k < 4) {
; #pragma unroll
;                 for (int j = 0; j < 2; ++j) {
;                     const int ai = k >> 1, m = (k & 1) * 2 + j;
;                     const size_t off = off0 + (size_t)(ai * 128 + m * 16) * 1024;
;                     h0[k & 1][j] = *(const u32x4*)(XH + off); h1[k & 1][j] = *(const u32x4*)(XH + off + 8); lw[k & 1][j] = *(const u32x4*)(XL + off);
.LBB0_374:
	v_lshlrev_b32_e32 v232, 4, v185
	v_sub_u32_e32 v232, 0, v232
	v_ashrrev_i32_e32 v233, 31, v232
	s_lshl_b32 s23, s68, 8
	v_mov_b32_e32 v98, v184
	v_mov_b32_e32 v106, v185
	s_add_i32 s23, s23, s59
	s_lshl_b32 s30, s24, 8
	s_ashr_i32 s31, s30, 31
	v_add_u32_e32 v172, s23, v98
	v_lshlrev_b32_e32 v100, 4, v106
	v_ashrrev_i32_e32 v173, 31, v172
	v_ashrrev_i32_e32 v101, 31, v100
	s_or_b64 s[30:31], s[30:31], s[48:49]
	v_lshlrev_b64 v[98:99], 10, v[172:173]
	v_lshl_add_u64 v[100:101], s[30:31], 0, v[100:101]
	v_readlane_b32 s30, v253, 11
	v_lshl_add_u64 v[98:99], v[100:101], 0, v[98:99]
	v_readlane_b32 s31, v253, 12
	s_movk_i32 s23, 0x4000
	v_cmp_eq_u32_e64 s[40:41], 0, v106
	v_lshl_add_u64 v[174:175], s[30:31], 0, v[98:99]
	v_readlane_b32 s30, v253, 9
	v_readlane_b32 s31, v253, 10
	global_load_dwordx4 v[188:191], v[174:175], off
	s_lshl_b32 s52, s24, 2
	v_lshl_add_u64 v[176:177], v[98:99], 1, s[30:31]
	global_load_dwordx4 v[192:195], v[176:177], off
	global_load_dwordx4 v[196:199], v[176:177], off offset:16
	s_mov_b64 s[30:31], 0x8000
	v_lshl_add_u64 v[182:183], v[176:177], 0, s[30:31]
	s_mov_b32 s30, 0x8000
	v_add_co_u32_e32 v98, vcc, s30, v176
	v_lshl_add_u64 v[180:181], v[176:177], 0, s[28:29]
	s_nop 0
	v_addc_co_u32_e32 v99, vcc, 0, v177, vcc
	v_add_co_u32_e32 v100, vcc, s23, v174
	s_mov_b32 s23, 0x10000
	s_nop 0
	v_addc_co_u32_e32 v101, vcc, 0, v175, vcc
	v_add_co_u32_e32 v106, vcc, s23, v176
	s_mov_b32 s23, 0x18000
	s_nop 0
	v_addc_co_u32_e32 v107, vcc, 0, v177, vcc
	v_add_co_u32_e32 v108, vcc, s30, v174
	s_mov_b64 s[30:31], 0x18000
	s_nop 0
	v_addc_co_u32_e32 v109, vcc, 0, v175, vcc
	v_add_co_u32_e32 v114, vcc, s23, v176
	s_mov_b32 s23, 0xc000
	s_nop 0
	v_addc_co_u32_e32 v115, vcc, 0, v177, vcc
	v_add_co_u32_e32 v200, vcc, s23, v174
	v_lshl_add_u64 v[178:179], v[176:177], 0, s[30:31]
	s_nop 0
	v_addc_co_u32_e32 v201, vcc, 0, v175, vcc
	global_load_dwordx4 v[154:157], v[182:183], off offset:16
	global_load_dwordx4 v[162:165], v[98:99], off
	global_load_dwordx4 v[158:161], v[100:101], off
	global_load_dwordx4 v[142:145], v[106:107], off
	global_load_dwordx4 v[126:129], v[108:109], off
	global_load_dwordx4 v[130:133], v[180:181], off offset:16
	s_nop 0
	global_load_dwordx4 v[98:101], v[178:179], off offset:16
	s_nop 0
	global_load_dwordx4 v[114:117], v[114:115], off
	s_nop 0
	global_load_dwordx4 v[106:109], v[200:201], off
	s_ashr_i32 s53, s52, 31
	s_waitcnt vmcnt(0)
	v_cvt_f32_fp8_e32 v200, v188
	v_cvt_f32_fp8_e32 v204, v189
	v_cvt_f32_fp8_sdwa v201, v188 src0_sel:BYTE_1
	v_cvt_f32_fp8_sdwa v205, v189 src0_sel:BYTE_1
	v_lshlrev_b32_e32 v208, 16, v192
	v_and_b32_e32 v209, 0xffff0000, v192
	v_cvt_f32_fp8_sdwa v212, v188 src0_sel:BYTE_2
	v_cvt_f32_fp8_sdwa v192, v189 src0_sel:BYTE_2
	v_cvt_f32_fp8_sdwa v213, v188 src0_sel:BYTE_3
	v_lshlrev_b32_e32 v214, 16, v193
	v_and_b32_e32 v215, 0xffff0000, v193
	v_cvt_f32_fp8_sdwa v193, v189 src0_sel:BYTE_3
	v_lshlrev_b32_e32 v210, 16, v194
	v_and_b32_e32 v211, 0xffff0000, v194
	v_lshlrev_b32_e32 v188, 16, v195
	v_and_b32_e32 v189, 0xffff0000, v195
	v_pk_fma_f32 v[194:195], v[200:201], s[22:23], v[208:209] op_sel_hi:[1,0,1]
	v_pk_fma_f32 v[200:201], v[204:205], s[22:23], v[210:211] op_sel_hi:[1,0,1]
	v_pk_fma_f32 v[204:205], v[212:213], s[22:23], v[214:215] op_sel_hi:[1,0,1]
	v_pk_fma_f32 v[188:189], v[192:193], s[22:23], v[188:189] op_sel_hi:[1,0,1]
	v_pk_add_f32 v[150:151], v[150:151], v[194:195]
	v_pk_add_f32 v[192:193], v[146:147], v[200:201]
	v_cvt_pk_bf16_f32 v146, v150, v151
	v_pk_add_f32 v[152:153], v[152:153], v[204:205]
	v_pk_add_f32 v[188:189], v[148:149], v[188:189]
	v_cvt_pk_bf16_f32 v147, v152, v153
	v_cvt_pk_bf16_f32 v148, v192, v193
	v_lshlrev_b32_e32 v194, 16, v146
	v_cvt_pk_bf16_f32 v149, v188, v189
	v_mov_b32_e32 v222, v146
	v_mov_b32_e32 v223, v147
	v_mov_b32_e32 v224, v148
	v_mov_b32_e32 v225, v149
	v_sub_f32_e32 v194, v150, v194
	v_mul_f32_e32 v194, 0x45800000, v194
	v_and_b32_e32 v146, 0xffff0000, v146
	v_sub_f32_e32 v146, v151, v146
	v_mul_f32_e32 v146, 0x45800000, v146
	v_med3_f32 v194, v194, s3, v206
	v_med3_f32 v204, v146, s3, v206
	v_mov_b32_e32 v146, v1
	v_lshlrev_b32_e32 v195, 16, v147
	v_and_b32_e32 v147, 0xffff0000, v147
	v_cvt_pk_fp8_f32 v146, v194, v204
	v_sub_f32_e32 v147, v153, v147
	v_sub_f32_e32 v195, v152, v195
	v_mul_f32_e32 v195, 0x45800000, v195
	v_mul_f32_e32 v147, 0x45800000, v147
	v_lshlrev_b32_e32 v200, 16, v148
	v_and_b32_e32 v148, 0xffff0000, v148
	v_med3_f32 v194, v195, s3, v206
	v_med3_f32 v147, v147, s3, v206
	v_lshlrev_b32_e32 v201, 16, v149
	v_cvt_pk_fp8_f32 v146, v194, v147 op_sel:[0,0,1]
	v_sub_f32_e32 v148, v193, v148
	v_sub_f32_e32 v194, v192, v200
	v_sub_f32_e32 v147, v188, v201
	v_mul_f32_e32 v194, 0x45800000, v194
	v_mul_f32_e32 v148, 0x45800000, v148
	v_med3_f32 v194, v194, s3, v206
	v_med3_f32 v148, v148, s3, v206
	v_mul_f32_e32 v195, 0x45800000, v147
	v_mov_b32_e32 v147, v1
	v_and_b32_e32 v149, 0xffff0000, v149
	v_cvt_pk_fp8_f32 v147, v194, v148
	v_sub_f32_e32 v149, v189, v149
	v_mul_f32_e32 v149, 0x45800000, v149
	v_med3_f32 v148, v195, s3, v206
	v_med3_f32 v149, v149, s3, v206
	v_cvt_pk_fp8_f32 v147, v148, v149 op_sel:[0,0,1]
	v_mul_f32_e32 v148, v151, v151
	v_mul_f32_e32 v149, v153, v153
	v_fmac_f32_e32 v148, v150, v150
	v_fmac_f32_e32 v149, v152, v152
	v_add_f32_e32 v148, v148, v149
	v_mul_f32_e32 v149, v193, v193
	v_mul_f32_e32 v150, v189, v189
	v_fmac_f32_e32 v149, v192, v192
	v_fmac_f32_e32 v150, v188, v188
	v_add_f32_e32 v149, v149, v150
	v_add_f32_e32 v194, v148, v149
	v_cvt_f32_fp8_e32 v148, v190
	v_cvt_f32_fp8_sdwa v149, v190 src0_sel:BYTE_1
	v_cvt_f32_fp8_e32 v150, v191
	v_cvt_f32_fp8_sdwa v151, v191 src0_sel:BYTE_1
; __device__ __forceinline__ u32x4 pack8(f32x4 a, f32x4 b) { u32x4 w; w.x = cvt_pk_bf16(a[0], a[1]); w.y = cvt_pk_bf16(a[2], a[3]); w.z = cvt_pk_bf16(b[0], b[1]); w.w = cvt_pk_bf16(b[2], b[3]); return w; }
; __device__ __forceinline__ void unpack8(u32x4 w, f32x4& a, f32x4& b) { a = (f32x4){bf_lo(w.x), bf_hi(w.x), bf_lo(w.y), bf_hi(w.y)}; b = (f32x4){bf_lo(w.z), bf_hi(w.z), bf_lo(w.w), bf_hi(w.w)}; }
; __device__ __forceinline__ float lo_dec(unsigned w, int i) { return (i == 0 ? __builtin_amdgcn_cvt_f32_fp8(w, 0) : i == 1 ? __builtin_amdgcn_cvt_f32_fp8(w, 1) : i == 2 ? __builtin_amdgcn_cvt_f32_fp8(w, 2) : __builtin_amdgcn_cvt_f32_fp8(w, 3)) * (1.0f / 4096.0f); }
;     __device__ __forceinline__ void operator()(const f32x4 (&acc)[2][2][4][2], const Unit& u, int wr, int wc, int fr_, int fq_) const {
;     ...
;                     u32x4 lo_out; float ss = 0.f;
; #pragma unroll
;                     for (int bj = 0; bj < 2; ++bj) {
;                         f32x4 a, b; unpack8(bj ? h1[k & 1][j] : h0[k & 1][j], a, b);
; #pragma unroll
;                         for (int i = 0; i < 4; ++i) { a[i] += lo_dec(lw[k & 1][j][2 * bj], i); b[i] += lo_dec(lw[k & 1][j][2 * bj + 1], i); }
;                         a = a + acc[ai][bj][m][0]; b = b + acc[ai][bj][m][1];
;                         const u32x4 hw = pack8(a, b);
;                         *(u32x4*)(XH + off + 8 * bj) = hw;
;                         f32x4 ra, rb; unpack8(hw, ra, rb);
;                         lo_out[2 * bj] = lo_enc(a - ra); lo_out[2 * bj + 1] = lo_enc(b - rb);
;                         ss += ((a[0] * a[0] + a[1] * a[1]) + (a[2] * a[2] + a[3] * a[3])) + ((b[0] * b[0] + b[1] * b[1]) + (b[2] * b[2] + b[3] * b[3]));
;                     }
;                     *(u32x4*)(XL + off) = lo_out;
;                     ss += __shfl_xor(ss, 16); ss += __shfl_xor(ss, 32);
;                     if (fq == 0) SSo[(size_t)(u.pm * 256 + ai * 128 + wr * 64 + m * 16 + fr) * 16 + 4 * u.pn + wc] = ss;
	v_lshlrev_b32_e32 v152, 16, v196
	v_and_b32_e32 v153, 0xffff0000, v196
	v_pk_fma_f32 v[148:149], v[148:149], s[22:23], v[152:153] op_sel_hi:[1,0,1]
	v_lshlrev_b32_e32 v152, 16, v198
	v_and_b32_e32 v153, 0xffff0000, v198
	v_pk_fma_f32 v[150:151], v[150:151], s[22:23], v[152:153] op_sel_hi:[1,0,1]
	v_cvt_f32_fp8_sdwa v152, v190 src0_sel:BYTE_2
	v_cvt_f32_fp8_sdwa v188, v191 src0_sel:BYTE_2
	v_cvt_f32_fp8_sdwa v153, v190 src0_sel:BYTE_3
	v_cvt_f32_fp8_sdwa v189, v191 src0_sel:BYTE_3
	v_lshlrev_b32_e32 v192, 16, v197
	v_and_b32_e32 v193, 0xffff0000, v197
	v_lshlrev_b32_e32 v190, 16, v199
	v_and_b32_e32 v191, 0xffff0000, v199
	v_pk_fma_f32 v[152:153], v[152:153], s[22:23], v[192:193] op_sel_hi:[1,0,1]
	v_pk_fma_f32 v[188:189], v[188:189], s[22:23], v[190:191] op_sel_hi:[1,0,1]
	v_pk_add_f32 v[140:141], v[140:141], v[152:153]
	v_pk_add_f32 v[152:153], v[138:139], v[148:149]
	v_pk_add_f32 v[188:189], v[136:137], v[188:189]
	v_cvt_pk_bf16_f32 v136, v152, v153
	v_pk_add_f32 v[134:135], v[134:135], v[150:151]
	v_lshlrev_b32_e32 v148, 16, v136
	v_and_b32_e32 v149, 0xffff0000, v136
	v_sub_f32_e32 v148, v152, v148
	v_sub_f32_e32 v149, v153, v149
	v_mul_f32_e32 v148, 0x45800000, v148
	v_med3_f32 v195, v148, s3, v206
	v_mul_f32_e32 v148, 0x45800000, v149
	v_cvt_pk_bf16_f32 v137, v140, v141
	v_med3_f32 v149, v148, s3, v206
	v_lshlrev_b32_e32 v150, 16, v137
	v_mov_b32_e32 v148, v1
	v_and_b32_e32 v151, 0xffff0000, v137
	v_sub_f32_e32 v150, v140, v150
	v_cvt_pk_fp8_f32 v148, v195, v149
	v_sub_f32_e32 v151, v141, v151
	v_mul_f32_e32 v150, 0x45800000, v150
	v_med3_f32 v149, v150, s3, v206
	v_mul_f32_e32 v150, 0x45800000, v151
	v_cvt_pk_bf16_f32 v138, v134, v135
	v_med3_f32 v150, v150, s3, v206
	v_lshlrev_b32_e32 v190, 16, v138
	v_and_b32_e32 v191, 0xffff0000, v138
	v_cvt_pk_bf16_f32 v139, v188, v189
	v_cvt_pk_fp8_f32 v148, v149, v150 op_sel:[0,0,1]
	v_lshlrev_b32_e32 v192, 16, v139
	v_sub_f32_e32 v150, v135, v191
	v_sub_f32_e32 v190, v134, v190
	v_sub_f32_e32 v149, v188, v192
	v_mul_f32_e32 v190, 0x45800000, v190
	v_mul_f32_e32 v150, 0x45800000, v150
	v_med3_f32 v190, v190, s3, v206
	v_med3_f32 v150, v150, s3, v206
	v_mul_f32_e32 v191, 0x45800000, v149
	v_mov_b32_e32 v149, v1
	v_mul_f32_e32 v135, v135, v135
	v_cvt_pk_fp8_f32 v149, v190, v150
	v_mul_f32_e32 v150, v153, v153
	v_mul_f32_e32 v141, v141, v141
	v_fmac_f32_e32 v135, v134, v134
	v_mul_f32_e32 v134, v189, v189
	v_fmac_f32_e32 v150, v152, v152
	v_fmac_f32_e32 v141, v140, v140
	v_fmac_f32_e32 v134, v188, v188
	v_add_f32_e32 v140, v150, v141
	v_add_f32_e32 v134, v135, v134
	v_add_f32_e32 v134, v140, v134
	v_and_b32_e32 v140, 64, v203
	v_xor_b32_e32 v135, 16, v203
	v_add_u32_e32 v140, 64, v140
	v_cmp_lt_i32_e32 vcc, v135, v140
	v_add_f32_e32 v134, v194, v134
	v_and_b32_e32 v193, 0xffff0000, v139
	v_cndmask_b32_e32 v135, v203, v135, vcc
	v_lshlrev_b32_e32 v150, 2, v135
	ds_bpermute_b32 v135, v150, v134
	v_sub_f32_e32 v151, v189, v193
	v_mul_f32_e32 v151, 0x45800000, v151
	v_med3_f32 v141, v191, s3, v206
	v_med3_f32 v151, v151, s3, v206
	s_waitcnt lgkmcnt(0)
	v_add_f32_e32 v134, v134, v135
	v_xor_b32_e32 v135, 32, v203
	v_cmp_lt_i32_e32 vcc, v135, v140
	v_cvt_pk_fp8_f32 v149, v141, v151 op_sel:[0,0,1]
	v_mov_b32_e32 v226, v136
	v_mov_b32_e32 v227, v137
	v_mov_b32_e32 v228, v138
	v_mov_b32_e32 v229, v139
	s_nop 1
	v_permlane16_swap_b32_e32 v222, v226
	v_permlane16_swap_b32_e32 v223, v227
	v_permlane16_swap_b32_e32 v224, v228
	v_permlane16_swap_b32_e32 v225, v229
	v_permlane32_swap_b32_e32 v222, v226
	v_permlane32_swap_b32_e32 v223, v227
	v_permlane32_swap_b32_e32 v224, v228
	v_permlane32_swap_b32_e32 v225, v229
	v_lshl_add_u64 v[230:231], v[176:177], 0, v[232:233]
	global_store_dwordx4 v[230:231], v[222:225], off
	global_store_dwordx4 v[230:231], v[226:229], off offset:64
	global_store_dwordx4 v[174:175], v[146:149], off
	v_cndmask_b32_e32 v135, v203, v135, vcc
	v_lshlrev_b32_e32 v151, 2, v135
	ds_bpermute_b32 v135, v151, v134
	s_and_saveexec_b64 s[36:37], s[40:41]
	s_cbranch_execz .LBB0_376
	v_readlane_b32 s30, v255, 23
	v_lshlrev_b64 v[136:137], 6, v[172:173]
	v_readlane_b32 s31, v255, 24
	s_lshl_b32 s24, s58, 2
	s_waitcnt lgkmcnt(0)
	v_add_f32_e32 v134, v134, v135
	v_lshl_add_u64 v[136:137], s[30:31], 0, v[136:137]
	v_lshl_add_u64 v[136:137], s[52:53], 2, v[136:137]
	v_lshl_add_u64 v[136:137], v[136:137], 0, s[24:25]
	global_store_dword v[136:137], v134, off
; __device__ __forceinline__ u32x4 pack8(f32x4 a, f32x4 b) { u32x4 w; w.x = cvt_pk_bf16(a[0], a[1]); w.y = cvt_pk_bf16(a[2], a[3]); w.z = cvt_pk_bf16(b[0], b[1]); w.w = cvt_pk_bf16(b[2], b[3]); return w; }
; __device__ __forceinline__ void unpack8(u32x4 w, f32x4& a, f32x4& b) { a = (f32x4){bf_lo(w.x), bf_hi(w.x), bf_lo(w.y), bf_hi(w.y)}; b = (f32x4){bf_lo(w.z), bf_hi(w.z), bf_lo(w.w), bf_hi(w.w)}; }
; __device__ __forceinline__ float lo_dec(unsigned w, int i) { return (i == 0 ? __builtin_amdgcn_cvt_f32_fp8(w, 0) : i == 1 ? __builtin_amdgcn_cvt_f32_fp8(w, 1) : i == 2 ? __builtin_amdgcn_cvt_f32_fp8(w, 2) : __builtin_amdgcn_cvt_f32_fp8(w, 3)) * (1.0f / 4096.0f); }
;     __device__ __forceinline__ void operator()(const f32x4 (&acc)[2][2][4][2], const Unit& u, int wr, int wc, int fr_, int fq_) const {
;     ...
;                     u32x4 lo_out; float ss = 0.f;
; #pragma unroll
;                     for (int bj = 0; bj < 2; ++bj) {
;                         f32x4 a, b; unpack8(bj ? h1[k & 1][j] : h0[k & 1][j], a, b);
; #pragma unroll
;                         for (int i = 0; i < 4; ++i) { a[i] += lo_dec(lw[k & 1][j][2 * bj], i); b[i] += lo_dec(lw[k & 1][j][2 * bj + 1], i); }
;                         a = a + acc[ai][bj][m][0]; b = b + acc[ai][bj][m][1];
;                         const u32x4 hw = pack8(a, b);
;                         *(u32x4*)(XH + off + 8 * bj) = hw;
;                         f32x4 ra, rb; unpack8(hw, ra, rb);
;                         lo_out[2 * bj] = lo_enc(a - ra); lo_out[2 * bj + 1] = lo_enc(b - rb);
;                         ss += ((a[0] * a[0] + a[1] * a[1]) + (a[2] * a[2] + a[3] * a[3])) + ((b[0] * b[0] + b[1] * b[1]) + (b[2] * b[2] + b[3] * b[3]));
;                     }
;                     *(u32x4*)(XL + off) = lo_out;
;                     ss += __shfl_xor(ss, 16); ss += __shfl_xor(ss, 32);
;                     if (fq == 0) SSo[(size_t)(u.pm * 256 + ai * 128 + wr * 64 + m * 16 + fr) * 16 + 4 * u.pn + wc] = ss;
.LBB0_376:
	s_or_b64 exec, exec, s[36:37]
	v_cvt_f32_fp8_e32 v134, v158
	s_waitcnt lgkmcnt(0)
	v_cvt_f32_fp8_sdwa v135, v158 src0_sel:BYTE_1
	v_cvt_f32_fp8_e32 v136, v159
	v_cvt_f32_fp8_sdwa v137, v159 src0_sel:BYTE_1
	v_lshlrev_b32_e32 v138, 16, v162
	v_and_b32_e32 v139, 0xffff0000, v162
	v_pk_fma_f32 v[134:135], v[134:135], s[22:23], v[138:139] op_sel_hi:[1,0,1]
	v_lshlrev_b32_e32 v138, 16, v164
	v_and_b32_e32 v139, 0xffff0000, v164
	v_pk_fma_f32 v[136:137], v[136:137], s[22:23], v[138:139] op_sel_hi:[1,0,1]
	v_cvt_f32_fp8_sdwa v138, v158 src0_sel:BYTE_2
	v_cvt_f32_fp8_sdwa v139, v158 src0_sel:BYTE_3
	v_cvt_f32_fp8_sdwa v140, v159 src0_sel:BYTE_2
	v_cvt_f32_fp8_sdwa v141, v159 src0_sel:BYTE_3
	v_lshlrev_b32_e32 v146, 16, v163
	v_and_b32_e32 v147, 0xffff0000, v163
	v_pk_fma_f32 v[138:139], v[138:139], s[22:23], v[146:147] op_sel_hi:[1,0,1]
	v_lshlrev_b32_e32 v146, 16, v165
	v_and_b32_e32 v147, 0xffff0000, v165
	v_pk_fma_f32 v[140:141], v[140:141], s[22:23], v[146:147] op_sel_hi:[1,0,1]
	v_pk_add_f32 v[122:123], v[122:123], v[134:135]
	v_pk_add_f32 v[136:137], v[118:119], v[136:137]
	v_cvt_pk_bf16_f32 v118, v122, v123
	v_pk_add_f32 v[124:125], v[124:125], v[138:139]
	v_pk_add_f32 v[134:135], v[120:121], v[140:141]
	v_cvt_pk_bf16_f32 v119, v124, v125
	v_cvt_pk_bf16_f32 v120, v136, v137
	v_lshlrev_b32_e32 v138, 16, v118
	v_cvt_pk_bf16_f32 v121, v134, v135
	v_mov_b32_e32 v222, v118
	v_mov_b32_e32 v223, v119
	v_mov_b32_e32 v224, v120
	v_mov_b32_e32 v225, v121
	v_sub_f32_e32 v138, v122, v138
	v_mul_f32_e32 v138, 0x45800000, v138
	v_and_b32_e32 v118, 0xffff0000, v118
	v_sub_f32_e32 v118, v123, v118
	v_mul_f32_e32 v118, 0x45800000, v118
	v_med3_f32 v138, v138, s3, v206
	v_med3_f32 v146, v118, s3, v206
	v_mov_b32_e32 v118, v1
	v_lshlrev_b32_e32 v139, 16, v119
	v_and_b32_e32 v119, 0xffff0000, v119
	v_cvt_pk_fp8_f32 v118, v138, v146
	v_sub_f32_e32 v119, v125, v119
	v_sub_f32_e32 v139, v124, v139
	v_mul_f32_e32 v139, 0x45800000, v139
	v_mul_f32_e32 v119, 0x45800000, v119
	v_lshlrev_b32_e32 v140, 16, v120
	v_and_b32_e32 v120, 0xffff0000, v120
	v_med3_f32 v138, v139, s3, v206
	v_med3_f32 v119, v119, s3, v206
	v_lshlrev_b32_e32 v141, 16, v121
	v_cvt_pk_fp8_f32 v118, v138, v119 op_sel:[0,0,1]
	v_sub_f32_e32 v120, v137, v120
	v_sub_f32_e32 v138, v136, v140
	v_sub_f32_e32 v119, v134, v141
	v_mul_f32_e32 v138, 0x45800000, v138
	v_mul_f32_e32 v120, 0x45800000, v120
	v_med3_f32 v138, v138, s3, v206
	v_med3_f32 v120, v120, s3, v206
	v_mul_f32_e32 v139, 0x45800000, v119
	v_mov_b32_e32 v119, v1
	v_and_b32_e32 v121, 0xffff0000, v121
	v_cvt_pk_fp8_f32 v119, v138, v120
	v_sub_f32_e32 v121, v135, v121
	v_mul_f32_e32 v121, 0x45800000, v121
	v_med3_f32 v120, v139, s3, v206
	v_med3_f32 v121, v121, s3, v206
	v_cvt_pk_fp8_f32 v119, v120, v121 op_sel:[0,0,1]
	v_mul_f32_e32 v120, v123, v123
	v_mul_f32_e32 v121, v125, v125
	v_fmac_f32_e32 v120, v122, v122
	v_fmac_f32_e32 v121, v124, v124
	v_add_f32_e32 v120, v120, v121
	v_mul_f32_e32 v121, v137, v137
	v_mul_f32_e32 v122, v135, v135
	v_fmac_f32_e32 v121, v136, v136
	v_fmac_f32_e32 v122, v134, v134
	v_add_f32_e32 v121, v121, v122
	v_add_f32_e32 v138, v120, v121
	v_cvt_f32_fp8_e32 v120, v160
	v_cvt_f32_fp8_sdwa v121, v160 src0_sel:BYTE_1
	v_cvt_f32_fp8_e32 v122, v161
	v_cvt_f32_fp8_sdwa v123, v161 src0_sel:BYTE_1
	v_lshlrev_b32_e32 v124, 16, v154
	v_and_b32_e32 v125, 0xffff0000, v154
	v_pk_fma_f32 v[120:121], v[120:121], s[22:23], v[124:125] op_sel_hi:[1,0,1]
	v_lshlrev_b32_e32 v124, 16, v156
	v_and_b32_e32 v125, 0xffff0000, v156
	v_pk_fma_f32 v[122:123], v[122:123], s[22:23], v[124:125] op_sel_hi:[1,0,1]
	v_cvt_f32_fp8_sdwa v124, v160 src0_sel:BYTE_2
	v_cvt_f32_fp8_sdwa v125, v160 src0_sel:BYTE_3
	v_cvt_f32_fp8_sdwa v134, v161 src0_sel:BYTE_2
	v_cvt_f32_fp8_sdwa v135, v161 src0_sel:BYTE_3
	v_lshlrev_b32_e32 v136, 16, v155
	v_and_b32_e32 v137, 0xffff0000, v155
	v_pk_fma_f32 v[124:125], v[124:125], s[22:23], v[136:137] op_sel_hi:[1,0,1]
	v_lshlrev_b32_e32 v136, 16, v157
	v_and_b32_e32 v137, 0xffff0000, v157
	v_pk_fma_f32 v[134:135], v[134:135], s[22:23], v[136:137] op_sel_hi:[1,0,1]
	v_pk_add_f32 v[136:137], v[110:111], v[120:121]
	v_pk_add_f32 v[124:125], v[112:113], v[124:125]
	v_cvt_pk_bf16_f32 v110, v136, v137
	v_pk_add_f32 v[102:103], v[102:103], v[122:123]
	v_lshlrev_b32_e32 v120, 16, v110
	v_and_b32_e32 v121, 0xffff0000, v110
	v_sub_f32_e32 v120, v136, v120
	v_sub_f32_e32 v121, v137, v121
	v_mul_f32_e32 v120, 0x45800000, v120
	v_med3_f32 v141, v120, s3, v206
	v_mul_f32_e32 v120, 0x45800000, v121
	v_cvt_pk_bf16_f32 v111, v124, v125
	v_med3_f32 v121, v120, s3, v206
	v_lshlrev_b32_e32 v122, 16, v111
	v_mov_b32_e32 v120, v1
	v_and_b32_e32 v123, 0xffff0000, v111
	v_sub_f32_e32 v122, v124, v122
	v_cvt_pk_fp8_f32 v120, v141, v121
	v_sub_f32_e32 v123, v125, v123
	v_mul_f32_e32 v122, 0x45800000, v122
	v_pk_add_f32 v[104:105], v[104:105], v[134:135]
	v_cvt_pk_bf16_f32 v112, v102, v103
	v_med3_f32 v121, v122, s3, v206
	v_lshlrev_b32_e32 v134, 16, v112
	v_and_b32_e32 v135, 0xffff0000, v112
	v_mul_f32_e32 v122, 0x45800000, v123
	v_cvt_pk_bf16_f32 v113, v104, v105
	v_med3_f32 v122, v122, s3, v206
	v_lshlrev_b32_e32 v139, 16, v113
	v_sub_f32_e32 v123, v103, v135
	v_sub_f32_e32 v134, v102, v134
	v_cvt_pk_fp8_f32 v120, v121, v122 op_sel:[0,0,1]
	v_sub_f32_e32 v121, v104, v139
	v_mul_f32_e32 v134, 0x45800000, v134
	v_mul_f32_e32 v123, 0x45800000, v123
	v_med3_f32 v134, v134, s3, v206
	v_med3_f32 v123, v123, s3, v206
	v_mul_f32_e32 v135, 0x45800000, v121
	v_mov_b32_e32 v121, v1
	v_mul_f32_e32 v103, v103, v103
	v_cvt_pk_fp8_f32 v121, v134, v123
	v_mul_f32_e32 v123, v137, v137
	v_mul_f32_e32 v125, v125, v125
	v_fmac_f32_e32 v103, v102, v102
	v_mul_f32_e32 v102, v105, v105
	v_fmac_f32_e32 v123, v136, v136
	v_fmac_f32_e32 v125, v124, v124
	v_fmac_f32_e32 v102, v104, v104
	v_add_f32_e32 v123, v123, v125
	v_add_f32_e32 v102, v103, v102
	v_add_f32_e32 v102, v123, v102
	v_add_f32_e32 v102, v138, v102
	ds_bpermute_b32 v103, v150, v102
	v_and_b32_e32 v140, 0xffff0000, v113
	v_sub_f32_e32 v122, v105, v140
	v_mul_f32_e32 v105, 0x45800000, v122
	v_med3_f32 v104, v135, s3, v206
	s_waitcnt lgkmcnt(0)
	v_add_f32_e32 v102, v102, v103
	ds_bpermute_b32 v103, v151, v102
	v_med3_f32 v105, v105, s3, v206
	v_cvt_pk_fp8_f32 v121, v104, v105 op_sel:[0,0,1]
	s_mov_b64 s[30:31], 0x4000
	v_lshl_add_u64 v[104:105], v[174:175], 0, s[30:31]
	v_mov_b32_e32 v226, v110
	v_mov_b32_e32 v227, v111
	v_mov_b32_e32 v228, v112
	v_mov_b32_e32 v229, v113
	s_nop 1
	v_permlane16_swap_b32_e32 v222, v226
	v_permlane16_swap_b32_e32 v223, v227
	v_permlane16_swap_b32_e32 v224, v228
	v_permlane16_swap_b32_e32 v225, v229
	v_permlane32_swap_b32_e32 v222, v226
	v_permlane32_swap_b32_e32 v223, v227
	v_permlane32_swap_b32_e32 v224, v228
	v_permlane32_swap_b32_e32 v225, v229
	v_lshl_add_u64 v[230:231], v[182:183], 0, v[232:233]
	global_store_dwordx4 v[230:231], v[222:225], off
	global_store_dwordx4 v[230:231], v[226:229], off offset:64
	global_store_dwordx4 v[104:105], v[118:121], off
	s_and_saveexec_b64 s[36:37], s[40:41]
	s_cbranch_execz .LBB0_378
; __device__ __forceinline__ u32x4 pack8(f32x4 a, f32x4 b) { u32x4 w; w.x = cvt_pk_bf16(a[0], a[1]); w.y = cvt_pk_bf16(a[2], a[3]); w.z = cvt_pk_bf16(b[0], b[1]); w.w = cvt_pk_bf16(b[2], b[3]); return w; }
; __device__ __forceinline__ void unpack8(u32x4 w, f32x4& a, f32x4& b) { a = (f32x4){bf_lo(w.x), bf_hi(w.x), bf_lo(w.y), bf_hi(w.y)}; b = (f32x4){bf_lo(w.z), bf_hi(w.z), bf_lo(w.w), bf_hi(w.w)}; }
; __device__ __forceinline__ float lo_dec(unsigned w, int i) { return (i == 0 ? __builtin_amdgcn_cvt_f32_fp8(w, 0) : i == 1 ? __builtin_amdgcn_cvt_f32_fp8(w, 1) : i == 2 ? __builtin_amdgcn_cvt_f32_fp8(w, 2) : __builtin_amdgcn_cvt_f32_fp8(w, 3)) * (1.0f / 4096.0f); }
;     __device__ __forceinline__ void operator()(const f32x4 (&acc)[2][2][4][2], const Unit& u, int wr, int wc, int fr_, int fq_) const {
;     ...
;                     u32x4 lo_out; float ss = 0.f;
; #pragma unroll
;                     for (int bj = 0; bj < 2; ++bj) {
;                         f32x4 a, b; unpack8(bj ? h1[k & 1][j] : h0[k & 1][j], a, b);
; #pragma unroll
;                         for (int i = 0; i < 4; ++i) { a[i] += lo_dec(lw[k & 1][j][2 * bj], i); b[i] += lo_dec(lw[k & 1][j][2 * bj + 1], i); }
;                         a = a + acc[ai][bj][m][0]; b = b + acc[ai][bj][m][1];
;                         const u32x4 hw = pack8(a, b);
;                         *(u32x4*)(XH + off + 8 * bj) = hw;
;                         f32x4 ra, rb; unpack8(hw, ra, rb);
;                         lo_out[2 * bj] = lo_enc(a - ra); lo_out[2 * bj + 1] = lo_enc(b - rb);
;                         ss += ((a[0] * a[0] + a[1] * a[1]) + (a[2] * a[2] + a[3] * a[3])) + ((b[0] * b[0] + b[1] * b[1]) + (b[2] * b[2] + b[3] * b[3]));
;                     }
;                     *(u32x4*)(XL + off) = lo_out;
;                     ss += __shfl_xor(ss, 16); ss += __shfl_xor(ss, 32);
;                     if (fq == 0) SSo[(size_t)(u.pm * 256 + ai * 128 + wr * 64 + m * 16 + fr) * 16 + 4 * u.pn + wc] = ss;
;                 }
;             }
;             if (k < 4) {
; #pragma unroll
;                 for (int j = 0; j < 2; ++j) {
;                     const int ai = k >> 1, m = (k & 1) * 2 + j;
;                     const size_t off = off0 + (size_t)(ai * 128 + m * 16) * 1024;
;                     h0[k & 1][j] = *(const u32x4*)(XH + off); h1[k & 1][j] = *(const u32x4*)(XH + off + 8); lw[k & 1][j] = *(const u32x4*)(XL + off);
	s_waitcnt lgkmcnt(0)
	v_add_f32_e32 v104, v102, v103
	v_add_u32_e32 v102, 16, v172
	v_ashrrev_i32_e32 v103, 31, v102
	v_readlane_b32 s30, v255, 23
	v_lshlrev_b64 v[102:103], 6, v[102:103]
	v_readlane_b32 s31, v255, 24
	s_lshl_b32 s24, s58, 2
	s_nop 0
	v_lshl_add_u64 v[102:103], s[30:31], 0, v[102:103]
	v_lshl_add_u64 v[102:103], s[52:53], 2, v[102:103]
	v_lshl_add_u64 v[102:103], v[102:103], 0, s[24:25]
	global_store_dword v[102:103], v104, off
.LBB0_378:
	s_or_b64 exec, exec, s[36:37]
	v_add_co_u32_e32 v102, vcc, 0x40000, v176
	s_mov_b64 s[30:31], 0x40000
	s_waitcnt lgkmcnt(0)
	v_addc_co_u32_e32 v103, vcc, 0, v177, vcc
	v_add_co_u32_e32 v104, vcc, 0x20000, v174
	v_lshl_add_u64 v[148:149], v[176:177], 0, s[30:31]
	s_nop 0
	v_addc_co_u32_e32 v105, vcc, 0, v175, vcc
	v_add_co_u32_e32 v110, vcc, 0x48000, v176
	s_mov_b64 s[30:31], 0x48000
	s_nop 0
	v_addc_co_u32_e32 v111, vcc, 0, v177, vcc
	v_add_co_u32_e32 v112, vcc, 0x24000, v174
	global_load_dwordx4 v[138:141], v[102:103], off
	global_load_dwordx4 v[122:125], v[104:105], off
	v_addc_co_u32_e32 v113, vcc, 0, v175, vcc
	v_lshl_add_u64 v[146:147], v[176:177], 0, s[30:31]
	global_load_dwordx4 v[134:137], v[148:149], off offset:16
	global_load_dwordx4 v[102:105], v[146:147], off offset:16
	global_load_dwordx4 v[118:121], v[110:111], off
	s_nop 0
	global_load_dwordx4 v[110:113], v[112:113], off
	v_cvt_f32_fp8_e32 v152, v126
	v_cvt_f32_fp8_sdwa v153, v126 src0_sel:BYTE_1
	v_cvt_f32_fp8_e32 v154, v127
	v_cvt_f32_fp8_sdwa v155, v127 src0_sel:BYTE_1
	v_lshlrev_b32_e32 v156, 16, v142
	v_and_b32_e32 v157, 0xffff0000, v142
	v_pk_fma_f32 v[152:153], v[152:153], s[22:23], v[156:157] op_sel_hi:[1,0,1]
	v_lshlrev_b32_e32 v156, 16, v144
	v_and_b32_e32 v157, 0xffff0000, v144
	v_pk_fma_f32 v[154:155], v[154:155], s[22:23], v[156:157] op_sel_hi:[1,0,1]
	v_cvt_f32_fp8_sdwa v156, v126 src0_sel:BYTE_2
	v_cvt_f32_fp8_sdwa v142, v127 src0_sel:BYTE_2
	v_cvt_f32_fp8_sdwa v157, v126 src0_sel:BYTE_3
	v_lshlrev_b32_e32 v158, 16, v143
	v_and_b32_e32 v159, 0xffff0000, v143
	v_cvt_f32_fp8_sdwa v143, v127 src0_sel:BYTE_3
	v_lshlrev_b32_e32 v144, 16, v145
	v_and_b32_e32 v145, 0xffff0000, v145
	v_pk_fma_f32 v[126:127], v[156:157], s[22:23], v[158:159] op_sel_hi:[1,0,1]
	v_pk_fma_f32 v[142:143], v[142:143], s[22:23], v[144:145] op_sel_hi:[1,0,1]
	v_pk_add_f32 v[96:97], v[96:97], v[126:127]
	v_pk_add_f32 v[94:95], v[94:95], v[152:153]
	v_pk_add_f32 v[126:127], v[92:93], v[142:143]
	v_pk_add_f32 v[142:143], v[90:91], v[154:155]
	v_cvt_pk_bf16_f32 v90, v94, v95
	v_cvt_pk_bf16_f32 v91, v96, v97
	s_mov_b64 s[30:31], 0x8000
	v_cvt_pk_bf16_f32 v92, v142, v143
	v_cvt_pk_bf16_f32 v93, v126, v127
	v_mov_b32_e32 v222, v90
	v_mov_b32_e32 v223, v91
	v_mov_b32_e32 v224, v92
	v_mov_b32_e32 v225, v93
	v_lshlrev_b32_e32 v144, 16, v90
	v_sub_f32_e32 v144, v94, v144
	v_and_b32_e32 v90, 0xffff0000, v90
	v_sub_f32_e32 v90, v95, v90
	v_mul_f32_e32 v144, 0x45800000, v144
	v_mul_f32_e32 v90, 0x45800000, v90
	v_med3_f32 v144, v144, s3, v206
	v_med3_f32 v154, v90, s3, v206
	v_mov_b32_e32 v90, v1
	v_lshlrev_b32_e32 v145, 16, v91
	v_and_b32_e32 v91, 0xffff0000, v91
	v_cvt_pk_fp8_f32 v90, v144, v154
	v_sub_f32_e32 v91, v97, v91
	v_sub_f32_e32 v145, v96, v145
	v_mul_f32_e32 v145, 0x45800000, v145
	v_mul_f32_e32 v91, 0x45800000, v91
	v_lshlrev_b32_e32 v152, 16, v92
	v_and_b32_e32 v92, 0xffff0000, v92
	v_med3_f32 v144, v145, s3, v206
	v_med3_f32 v91, v91, s3, v206
	v_lshlrev_b32_e32 v153, 16, v93
	v_cvt_pk_fp8_f32 v90, v144, v91 op_sel:[0,0,1]
	v_sub_f32_e32 v92, v143, v92
	v_sub_f32_e32 v144, v142, v152
	v_sub_f32_e32 v91, v126, v153
	v_mul_f32_e32 v144, 0x45800000, v144
	v_mul_f32_e32 v92, 0x45800000, v92
	v_med3_f32 v144, v144, s3, v206
	v_med3_f32 v92, v92, s3, v206
	v_mul_f32_e32 v145, 0x45800000, v91
	v_mov_b32_e32 v91, v1
	v_and_b32_e32 v93, 0xffff0000, v93
	v_cvt_pk_fp8_f32 v91, v144, v92
	v_sub_f32_e32 v93, v127, v93
	v_mul_f32_e32 v93, 0x45800000, v93
	v_med3_f32 v92, v145, s3, v206
	v_med3_f32 v93, v93, s3, v206
	v_cvt_pk_fp8_f32 v91, v92, v93 op_sel:[0,0,1]
	v_mul_f32_e32 v92, v95, v95
	v_mul_f32_e32 v93, v97, v97
	v_fmac_f32_e32 v92, v94, v94
	v_fmac_f32_e32 v93, v96, v96
	v_add_f32_e32 v92, v92, v93
	v_mul_f32_e32 v93, v143, v143
	v_mul_f32_e32 v94, v127, v127
	v_fmac_f32_e32 v93, v142, v142
	v_fmac_f32_e32 v94, v126, v126
	v_add_f32_e32 v93, v93, v94
	v_add_f32_e32 v142, v92, v93
	v_cvt_f32_fp8_e32 v92, v128
	v_cvt_f32_fp8_sdwa v93, v128 src0_sel:BYTE_1
	v_cvt_f32_fp8_e32 v94, v129
	v_cvt_f32_fp8_sdwa v95, v129 src0_sel:BYTE_1
	v_lshlrev_b32_e32 v96, 16, v130
	v_and_b32_e32 v97, 0xffff0000, v130
	v_pk_fma_f32 v[92:93], v[92:93], s[22:23], v[96:97] op_sel_hi:[1,0,1]
	v_lshlrev_b32_e32 v96, 16, v132
	v_and_b32_e32 v97, 0xffff0000, v132
	v_pk_fma_f32 v[94:95], v[94:95], s[22:23], v[96:97] op_sel_hi:[1,0,1]
	v_cvt_f32_fp8_sdwa v96, v128 src0_sel:BYTE_2
	v_cvt_f32_fp8_sdwa v126, v129 src0_sel:BYTE_2
	v_cvt_f32_fp8_sdwa v97, v128 src0_sel:BYTE_3
	v_cvt_f32_fp8_sdwa v127, v129 src0_sel:BYTE_3
	v_lshlrev_b32_e32 v130, 16, v131
	v_and_b32_e32 v131, 0xffff0000, v131
	v_lshlrev_b32_e32 v128, 16, v133
	v_and_b32_e32 v129, 0xffff0000, v133
	v_pk_fma_f32 v[96:97], v[96:97], s[22:23], v[130:131] op_sel_hi:[1,0,1]
	v_pk_fma_f32 v[126:127], v[126:127], s[22:23], v[128:129] op_sel_hi:[1,0,1]
	v_pk_add_f32 v[88:89], v[88:89], v[96:97]
	v_pk_add_f32 v[96:97], v[86:87], v[92:93]
	v_pk_add_f32 v[126:127], v[84:85], v[126:127]
	v_cvt_pk_bf16_f32 v84, v96, v97
	v_pk_add_f32 v[82:83], v[82:83], v[94:95]
	v_lshlrev_b32_e32 v92, 16, v84
	v_and_b32_e32 v93, 0xffff0000, v84
	v_sub_f32_e32 v92, v96, v92
	v_sub_f32_e32 v93, v97, v93
	v_mul_f32_e32 v92, 0x45800000, v92
; __device__ __forceinline__ u32x4 pack8(f32x4 a, f32x4 b) { u32x4 w; w.x = cvt_pk_bf16(a[0], a[1]); w.y = cvt_pk_bf16(a[2], a[3]); w.z = cvt_pk_bf16(b[0], b[1]); w.w = cvt_pk_bf16(b[2], b[3]); return w; }
; __device__ __forceinline__ void unpack8(u32x4 w, f32x4& a, f32x4& b) { a = (f32x4){bf_lo(w.x), bf_hi(w.x), bf_lo(w.y), bf_hi(w.y)}; b = (f32x4){bf_lo(w.z), bf_hi(w.z), bf_lo(w.w), bf_hi(w.w)}; }
; __device__ __forceinline__ float lo_dec(unsigned w, int i) { return (i == 0 ? __builtin_amdgcn_cvt_f32_fp8(w, 0) : i == 1 ? __builtin_amdgcn_cvt_f32_fp8(w, 1) : i == 2 ? __builtin_amdgcn_cvt_f32_fp8(w, 2) : __builtin_amdgcn_cvt_f32_fp8(w, 3)) * (1.0f / 4096.0f); }
;     __device__ __forceinline__ void operator()(const f32x4 (&acc)[2][2][4][2], const Unit& u, int wr, int wc, int fr_, int fq_) const {
;     ...
;                     u32x4 lo_out; float ss = 0.f;
; #pragma unroll
;                     for (int bj = 0; bj < 2; ++bj) {
;                         f32x4 a, b; unpack8(bj ? h1[k & 1][j] : h0[k & 1][j], a, b);
; #pragma unroll
;                         for (int i = 0; i < 4; ++i) { a[i] += lo_dec(lw[k & 1][j][2 * bj], i); b[i] += lo_dec(lw[k & 1][j][2 * bj + 1], i); }
;                         a = a + acc[ai][bj][m][0]; b = b + acc[ai][bj][m][1];
;                         const u32x4 hw = pack8(a, b);
;                         *(u32x4*)(XH + off + 8 * bj) = hw;
;                         f32x4 ra, rb; unpack8(hw, ra, rb);
;                         lo_out[2 * bj] = lo_enc(a - ra); lo_out[2 * bj + 1] = lo_enc(b - rb);
;                         ss += ((a[0] * a[0] + a[1] * a[1]) + (a[2] * a[2] + a[3] * a[3])) + ((b[0] * b[0] + b[1] * b[1]) + (b[2] * b[2] + b[3] * b[3]));
;                     }
;                     *(u32x4*)(XL + off) = lo_out;
;                     ss += __shfl_xor(ss, 16); ss += __shfl_xor(ss, 32);
;                     if (fq == 0) SSo[(size_t)(u.pm * 256 + ai * 128 + wr * 64 + m * 16 + fr) * 16 + 4 * u.pn + wc] = ss;
	v_med3_f32 v132, v92, s3, v206
	v_mul_f32_e32 v92, 0x45800000, v93
	v_cvt_pk_bf16_f32 v85, v88, v89
	v_med3_f32 v93, v92, s3, v206
	v_lshlrev_b32_e32 v94, 16, v85
	v_mov_b32_e32 v92, v1
	v_and_b32_e32 v95, 0xffff0000, v85
	v_sub_f32_e32 v94, v88, v94
	v_cvt_pk_fp8_f32 v92, v132, v93
	v_sub_f32_e32 v95, v89, v95
	v_mul_f32_e32 v94, 0x45800000, v94
	v_cvt_pk_bf16_f32 v86, v82, v83
	v_med3_f32 v93, v94, s3, v206
	v_lshlrev_b32_e32 v128, 16, v86
	v_and_b32_e32 v129, 0xffff0000, v86
	v_mul_f32_e32 v94, 0x45800000, v95
	v_cvt_pk_bf16_f32 v87, v126, v127
	v_med3_f32 v94, v94, s3, v206
	v_lshlrev_b32_e32 v130, 16, v87
	v_sub_f32_e32 v95, v83, v129
	v_sub_f32_e32 v128, v82, v128
	v_cvt_pk_fp8_f32 v92, v93, v94 op_sel:[0,0,1]
	v_sub_f32_e32 v93, v126, v130
	v_mul_f32_e32 v128, 0x45800000, v128
	v_mul_f32_e32 v95, 0x45800000, v95
	v_med3_f32 v128, v128, s3, v206
	v_med3_f32 v95, v95, s3, v206
	v_mul_f32_e32 v129, 0x45800000, v93
	v_mov_b32_e32 v93, v1
	v_mul_f32_e32 v83, v83, v83
	v_cvt_pk_fp8_f32 v93, v128, v95
	v_mul_f32_e32 v95, v97, v97
	v_mul_f32_e32 v89, v89, v89
	v_fmac_f32_e32 v83, v82, v82
	v_mul_f32_e32 v82, v127, v127
	v_fmac_f32_e32 v95, v96, v96
	v_fmac_f32_e32 v89, v88, v88
	v_fmac_f32_e32 v82, v126, v126
	v_add_f32_e32 v88, v95, v89
	v_add_f32_e32 v82, v83, v82
	v_add_f32_e32 v82, v88, v82
	v_add_f32_e32 v82, v142, v82
	ds_bpermute_b32 v83, v150, v82
	v_and_b32_e32 v131, 0xffff0000, v87
	v_sub_f32_e32 v94, v127, v131
	v_mul_f32_e32 v89, 0x45800000, v94
	v_med3_f32 v88, v129, s3, v206
	s_waitcnt lgkmcnt(0)
	v_add_f32_e32 v82, v82, v83
	ds_bpermute_b32 v83, v151, v82
	v_med3_f32 v89, v89, s3, v206
	v_cvt_pk_fp8_f32 v93, v88, v89 op_sel:[0,0,1]
	v_lshl_add_u64 v[88:89], v[174:175], 0, s[30:31]
	v_mov_b32_e32 v226, v84
	v_mov_b32_e32 v227, v85
	v_mov_b32_e32 v228, v86
	v_mov_b32_e32 v229, v87
	s_nop 1
	v_permlane16_swap_b32_e32 v222, v226
	v_permlane16_swap_b32_e32 v223, v227
	v_permlane16_swap_b32_e32 v224, v228
	v_permlane16_swap_b32_e32 v225, v229
	v_permlane32_swap_b32_e32 v222, v226
	v_permlane32_swap_b32_e32 v223, v227
	v_permlane32_swap_b32_e32 v224, v228
	v_permlane32_swap_b32_e32 v225, v229
	v_lshl_add_u64 v[230:231], v[180:181], 0, v[232:233]
	global_store_dwordx4 v[230:231], v[222:225], off
	global_store_dwordx4 v[230:231], v[226:229], off offset:64
	global_store_dwordx4 v[88:89], v[90:93], off
	s_and_saveexec_b64 s[36:37], s[40:41]
	s_cbranch_execz .LBB0_380
	s_waitcnt lgkmcnt(0)
	v_add_f32_e32 v84, v82, v83
	v_add_u32_e32 v82, 32, v172
	v_ashrrev_i32_e32 v83, 31, v82
	v_readlane_b32 s30, v255, 23
	v_lshlrev_b64 v[82:83], 6, v[82:83]
	v_readlane_b32 s31, v255, 24
	s_lshl_b32 s24, s58, 2
	s_nop 0
	v_lshl_add_u64 v[82:83], s[30:31], 0, v[82:83]
	v_lshl_add_u64 v[82:83], s[52:53], 2, v[82:83]
	v_lshl_add_u64 v[82:83], v[82:83], 0, s[24:25]
	global_store_dword v[82:83], v84, off
.LBB0_380:
	s_or_b64 exec, exec, s[36:37]
	v_cvt_f32_fp8_e32 v82, v106
	s_waitcnt lgkmcnt(0)
	v_cvt_f32_fp8_sdwa v83, v106 src0_sel:BYTE_1
	v_cvt_f32_fp8_e32 v84, v107
	v_cvt_f32_fp8_sdwa v85, v107 src0_sel:BYTE_1
	v_lshlrev_b32_e32 v86, 16, v114
	v_and_b32_e32 v87, 0xffff0000, v114
	v_pk_fma_f32 v[82:83], v[82:83], s[22:23], v[86:87] op_sel_hi:[1,0,1]
	v_lshlrev_b32_e32 v86, 16, v116
	v_and_b32_e32 v87, 0xffff0000, v116
	v_pk_fma_f32 v[84:85], v[84:85], s[22:23], v[86:87] op_sel_hi:[1,0,1]
	v_cvt_f32_fp8_sdwa v86, v106 src0_sel:BYTE_2
	v_cvt_f32_fp8_sdwa v87, v106 src0_sel:BYTE_3
	v_cvt_f32_fp8_sdwa v88, v107 src0_sel:BYTE_2
	v_cvt_f32_fp8_sdwa v89, v107 src0_sel:BYTE_3
	v_lshlrev_b32_e32 v90, 16, v115
	v_and_b32_e32 v91, 0xffff0000, v115
	v_pk_fma_f32 v[86:87], v[86:87], s[22:23], v[90:91] op_sel_hi:[1,0,1]
	v_lshlrev_b32_e32 v90, 16, v117
	v_and_b32_e32 v91, 0xffff0000, v117
	v_pk_fma_f32 v[88:89], v[88:89], s[22:23], v[90:91] op_sel_hi:[1,0,1]
	v_pk_add_f32 v[78:79], v[78:79], v[82:83]
	v_pk_add_f32 v[84:85], v[74:75], v[84:85]
	v_cvt_pk_bf16_f32 v74, v78, v79
	v_pk_add_f32 v[80:81], v[80:81], v[86:87]
	v_pk_add_f32 v[82:83], v[76:77], v[88:89]
	v_cvt_pk_bf16_f32 v75, v80, v81
	v_cvt_pk_bf16_f32 v76, v84, v85
	v_lshlrev_b32_e32 v86, 16, v74
	v_cvt_pk_bf16_f32 v77, v82, v83
	v_mov_b32_e32 v222, v74
	v_mov_b32_e32 v223, v75
	v_mov_b32_e32 v224, v76
	v_mov_b32_e32 v225, v77
	v_sub_f32_e32 v86, v78, v86
	v_mul_f32_e32 v86, 0x45800000, v86
	v_and_b32_e32 v74, 0xffff0000, v74
	v_sub_f32_e32 v74, v79, v74
	v_mul_f32_e32 v74, 0x45800000, v74
	v_med3_f32 v86, v86, s3, v206
	v_med3_f32 v90, v74, s3, v206
	v_mov_b32_e32 v74, v1
	v_lshlrev_b32_e32 v87, 16, v75
	v_and_b32_e32 v75, 0xffff0000, v75
	v_cvt_pk_fp8_f32 v74, v86, v90
	v_sub_f32_e32 v75, v81, v75
	v_sub_f32_e32 v87, v80, v87
	v_mul_f32_e32 v87, 0x45800000, v87
	v_mul_f32_e32 v75, 0x45800000, v75
	v_lshlrev_b32_e32 v88, 16, v76
	v_and_b32_e32 v76, 0xffff0000, v76
	v_med3_f32 v86, v87, s3, v206
	v_med3_f32 v75, v75, s3, v206
	v_lshlrev_b32_e32 v89, 16, v77
	v_cvt_pk_fp8_f32 v74, v86, v75 op_sel:[0,0,1]
	v_sub_f32_e32 v76, v85, v76
	v_sub_f32_e32 v86, v84, v88
	v_sub_f32_e32 v75, v82, v89
	v_mul_f32_e32 v86, 0x45800000, v86
	v_mul_f32_e32 v76, 0x45800000, v76
	v_med3_f32 v86, v86, s3, v206
	v_med3_f32 v76, v76, s3, v206
	v_mul_f32_e32 v87, 0x45800000, v75
	v_mov_b32_e32 v75, v1
	v_and_b32_e32 v77, 0xffff0000, v77
	v_cvt_pk_fp8_f32 v75, v86, v76
	v_sub_f32_e32 v77, v83, v77
	v_mul_f32_e32 v77, 0x45800000, v77
	v_med3_f32 v76, v87, s3, v206
	v_med3_f32 v77, v77, s3, v206
	v_cvt_pk_fp8_f32 v75, v76, v77 op_sel:[0,0,1]
	v_mul_f32_e32 v76, v79, v79
	v_mul_f32_e32 v77, v81, v81
	v_fmac_f32_e32 v76, v78, v78
	v_fmac_f32_e32 v77, v80, v80
	v_add_f32_e32 v76, v76, v77
	v_mul_f32_e32 v77, v85, v85
	v_mul_f32_e32 v78, v83, v83
; __device__ __forceinline__ u32x4 pack8(f32x4 a, f32x4 b) { u32x4 w; w.x = cvt_pk_bf16(a[0], a[1]); w.y = cvt_pk_bf16(a[2], a[3]); w.z = cvt_pk_bf16(b[0], b[1]); w.w = cvt_pk_bf16(b[2], b[3]); return w; }
; __device__ __forceinline__ void unpack8(u32x4 w, f32x4& a, f32x4& b) { a = (f32x4){bf_lo(w.x), bf_hi(w.x), bf_lo(w.y), bf_hi(w.y)}; b = (f32x4){bf_lo(w.z), bf_hi(w.z), bf_lo(w.w), bf_hi(w.w)}; }
; __device__ __forceinline__ float lo_dec(unsigned w, int i) { return (i == 0 ? __builtin_amdgcn_cvt_f32_fp8(w, 0) : i == 1 ? __builtin_amdgcn_cvt_f32_fp8(w, 1) : i == 2 ? __builtin_amdgcn_cvt_f32_fp8(w, 2) : __builtin_amdgcn_cvt_f32_fp8(w, 3)) * (1.0f / 4096.0f); }
;     __device__ __forceinline__ void operator()(const f32x4 (&acc)[2][2][4][2], const Unit& u, int wr, int wc, int fr_, int fq_) const {
;     ...
;                     u32x4 lo_out; float ss = 0.f;
; #pragma unroll
;                     for (int bj = 0; bj < 2; ++bj) {
;                         f32x4 a, b; unpack8(bj ? h1[k & 1][j] : h0[k & 1][j], a, b);
; #pragma unroll
;                         for (int i = 0; i < 4; ++i) { a[i] += lo_dec(lw[k & 1][j][2 * bj], i); b[i] += lo_dec(lw[k & 1][j][2 * bj + 1], i); }
;                         a = a + acc[ai][bj][m][0]; b = b + acc[ai][bj][m][1];
;                         const u32x4 hw = pack8(a, b);
;                         *(u32x4*)(XH + off + 8 * bj) = hw;
;                         f32x4 ra, rb; unpack8(hw, ra, rb);
;                         lo_out[2 * bj] = lo_enc(a - ra); lo_out[2 * bj + 1] = lo_enc(b - rb);
;                         ss += ((a[0] * a[0] + a[1] * a[1]) + (a[2] * a[2] + a[3] * a[3])) + ((b[0] * b[0] + b[1] * b[1]) + (b[2] * b[2] + b[3] * b[3]));
;                     }
;                     *(u32x4*)(XL + off) = lo_out;
;                     ss += __shfl_xor(ss, 16); ss += __shfl_xor(ss, 32);
;                     if (fq == 0) SSo[(size_t)(u.pm * 256 + ai * 128 + wr * 64 + m * 16 + fr) * 16 + 4 * u.pn + wc] = ss;
;                 }
;             }
;             if (k < 4) {
; #pragma unroll
;                 for (int j = 0; j < 2; ++j) {
;                     const int ai = k >> 1, m = (k & 1) * 2 + j;
;                     const size_t off = off0 + (size_t)(ai * 128 + m * 16) * 1024;
;                     h0[k & 1][j] = *(const u32x4*)(XH + off); h1[k & 1][j] = *(const u32x4*)(XH + off + 8); lw[k & 1][j] = *(const u32x4*)(XL + off);
	v_fmac_f32_e32 v77, v84, v84
	v_fmac_f32_e32 v78, v82, v82
	v_add_f32_e32 v77, v77, v78
	v_add_f32_e32 v86, v76, v77
	v_cvt_f32_fp8_e32 v76, v108
	v_cvt_f32_fp8_sdwa v77, v108 src0_sel:BYTE_1
	v_cvt_f32_fp8_e32 v78, v109
	v_cvt_f32_fp8_sdwa v79, v109 src0_sel:BYTE_1
	v_lshlrev_b32_e32 v80, 16, v98
	v_and_b32_e32 v81, 0xffff0000, v98
	v_pk_fma_f32 v[76:77], v[76:77], s[22:23], v[80:81] op_sel_hi:[1,0,1]
	v_lshlrev_b32_e32 v80, 16, v100
	v_and_b32_e32 v81, 0xffff0000, v100
	v_pk_fma_f32 v[78:79], v[78:79], s[22:23], v[80:81] op_sel_hi:[1,0,1]
	v_cvt_f32_fp8_sdwa v80, v108 src0_sel:BYTE_2
	v_cvt_f32_fp8_sdwa v81, v108 src0_sel:BYTE_3
	v_cvt_f32_fp8_sdwa v82, v109 src0_sel:BYTE_2
	v_cvt_f32_fp8_sdwa v83, v109 src0_sel:BYTE_3
	v_lshlrev_b32_e32 v84, 16, v99
	v_and_b32_e32 v85, 0xffff0000, v99
	v_pk_fma_f32 v[80:81], v[80:81], s[22:23], v[84:85] op_sel_hi:[1,0,1]
	v_lshlrev_b32_e32 v84, 16, v101
	v_and_b32_e32 v85, 0xffff0000, v101
	v_pk_fma_f32 v[82:83], v[82:83], s[22:23], v[84:85] op_sel_hi:[1,0,1]
	v_pk_add_f32 v[72:73], v[72:73], v[80:81]
	v_pk_add_f32 v[80:81], v[70:71], v[76:77]
	v_pk_add_f32 v[82:83], v[68:69], v[82:83]
	v_cvt_pk_bf16_f32 v68, v80, v81
	v_pk_add_f32 v[66:67], v[66:67], v[78:79]
	v_lshlrev_b32_e32 v76, 16, v68
	v_and_b32_e32 v77, 0xffff0000, v68
	v_sub_f32_e32 v76, v80, v76
	v_sub_f32_e32 v77, v81, v77
	v_mul_f32_e32 v76, 0x45800000, v76
	v_med3_f32 v89, v76, s3, v206
	v_mul_f32_e32 v76, 0x45800000, v77
	v_cvt_pk_bf16_f32 v69, v72, v73
	v_med3_f32 v77, v76, s3, v206
	v_lshlrev_b32_e32 v78, 16, v69
	v_mov_b32_e32 v76, v1
	v_and_b32_e32 v79, 0xffff0000, v69
	v_sub_f32_e32 v78, v72, v78
	v_cvt_pk_fp8_f32 v76, v89, v77
	v_sub_f32_e32 v79, v73, v79
	v_mul_f32_e32 v78, 0x45800000, v78
	v_cvt_pk_bf16_f32 v70, v66, v67
	v_med3_f32 v77, v78, s3, v206
	v_lshlrev_b32_e32 v84, 16, v70
	v_and_b32_e32 v85, 0xffff0000, v70
	v_mul_f32_e32 v78, 0x45800000, v79
	v_cvt_pk_bf16_f32 v71, v82, v83
	v_med3_f32 v78, v78, s3, v206
	v_lshlrev_b32_e32 v87, 16, v71
	v_sub_f32_e32 v79, v67, v85
	v_sub_f32_e32 v84, v66, v84
	v_cvt_pk_fp8_f32 v76, v77, v78 op_sel:[0,0,1]
	v_sub_f32_e32 v77, v82, v87
	v_mul_f32_e32 v84, 0x45800000, v84
	v_mul_f32_e32 v79, 0x45800000, v79
	v_med3_f32 v84, v84, s3, v206
	v_med3_f32 v79, v79, s3, v206
	v_mul_f32_e32 v85, 0x45800000, v77
	v_mov_b32_e32 v77, v1
	v_mul_f32_e32 v67, v67, v67
	v_cvt_pk_fp8_f32 v77, v84, v79
	v_mul_f32_e32 v79, v81, v81
	v_mul_f32_e32 v73, v73, v73
	v_fmac_f32_e32 v67, v66, v66
	v_mul_f32_e32 v66, v83, v83
	v_fmac_f32_e32 v79, v80, v80
	v_fmac_f32_e32 v73, v72, v72
	v_fmac_f32_e32 v66, v82, v82
	v_add_f32_e32 v72, v79, v73
	v_add_f32_e32 v66, v67, v66
	v_add_f32_e32 v66, v72, v66
	v_add_f32_e32 v66, v86, v66
	ds_bpermute_b32 v67, v150, v66
	v_and_b32_e32 v88, 0xffff0000, v71
	v_sub_f32_e32 v78, v83, v88
	v_mul_f32_e32 v73, 0x45800000, v78
	v_med3_f32 v72, v85, s3, v206
	s_waitcnt lgkmcnt(0)
	v_add_f32_e32 v66, v66, v67
	ds_bpermute_b32 v67, v151, v66
	v_med3_f32 v73, v73, s3, v206
	v_cvt_pk_fp8_f32 v77, v72, v73 op_sel:[0,0,1]
	s_mov_b64 s[30:31], 0xc000
	v_lshl_add_u64 v[72:73], v[174:175], 0, s[30:31]
	v_mov_b32_e32 v226, v68
	v_mov_b32_e32 v227, v69
	v_mov_b32_e32 v228, v70
	v_mov_b32_e32 v229, v71
	s_nop 1
	v_permlane16_swap_b32_e32 v222, v226
	v_permlane16_swap_b32_e32 v223, v227
	v_permlane16_swap_b32_e32 v224, v228
	v_permlane16_swap_b32_e32 v225, v229
	v_permlane32_swap_b32_e32 v222, v226
	v_permlane32_swap_b32_e32 v223, v227
	v_permlane32_swap_b32_e32 v224, v228
	v_permlane32_swap_b32_e32 v225, v229
	v_lshl_add_u64 v[230:231], v[178:179], 0, v[232:233]
	global_store_dwordx4 v[230:231], v[222:225], off
	global_store_dwordx4 v[230:231], v[226:229], off offset:64
	global_store_dwordx4 v[72:73], v[74:77], off
	s_and_saveexec_b64 s[36:37], s[40:41]
	s_cbranch_execz .LBB0_382
	s_waitcnt lgkmcnt(0)
	v_add_f32_e32 v68, v66, v67
	v_add_u32_e32 v66, 48, v172
	v_ashrrev_i32_e32 v67, 31, v66
	v_readlane_b32 s30, v255, 23
	v_lshlrev_b64 v[66:67], 6, v[66:67]
	v_readlane_b32 s31, v255, 24
	s_lshl_b32 s24, s58, 2
	s_nop 0
	v_lshl_add_u64 v[66:67], s[30:31], 0, v[66:67]
	v_lshl_add_u64 v[66:67], s[52:53], 2, v[66:67]
	v_lshl_add_u64 v[66:67], v[66:67], 0, s[24:25]
	global_store_dword v[66:67], v68, off
.LBB0_382:
	s_or_b64 exec, exec, s[36:37]
	v_add_co_u32_e32 v66, vcc, 0x50000, v176
	s_mov_b64 s[30:31], 0x50000
	s_waitcnt lgkmcnt(0)
	v_addc_co_u32_e32 v67, vcc, 0, v177, vcc
	v_add_co_u32_e32 v68, vcc, 0x28000, v174
	v_lshl_add_u64 v[92:93], v[176:177], 0, s[30:31]
	s_nop 0
	v_addc_co_u32_e32 v69, vcc, 0, v175, vcc
	v_add_co_u32_e32 v70, vcc, 0x58000, v176
	s_mov_b64 s[30:31], 0x58000
	s_nop 0
	v_addc_co_u32_e32 v71, vcc, 0, v177, vcc
	v_add_co_u32_e32 v72, vcc, 0x2c000, v174
	global_load_dwordx4 v[86:89], v[66:67], off
	global_load_dwordx4 v[78:81], v[68:69], off
	v_addc_co_u32_e32 v73, vcc, 0, v175, vcc
	v_lshl_add_u64 v[90:91], v[176:177], 0, s[30:31]
	global_load_dwordx4 v[82:85], v[92:93], off offset:16
	global_load_dwordx4 v[66:69], v[90:91], off offset:16
	global_load_dwordx4 v[74:77], v[70:71], off
	s_nop 0
	global_load_dwordx4 v[70:73], v[72:73], off
	s_waitcnt vmcnt(16)
; __device__ __forceinline__ u32x4 pack8(f32x4 a, f32x4 b) { u32x4 w; w.x = cvt_pk_bf16(a[0], a[1]); w.y = cvt_pk_bf16(a[2], a[3]); w.z = cvt_pk_bf16(b[0], b[1]); w.w = cvt_pk_bf16(b[2], b[3]); return w; }
; __device__ __forceinline__ void unpack8(u32x4 w, f32x4& a, f32x4& b) { a = (f32x4){bf_lo(w.x), bf_hi(w.x), bf_lo(w.y), bf_hi(w.y)}; b = (f32x4){bf_lo(w.z), bf_hi(w.z), bf_lo(w.w), bf_hi(w.w)}; }
; __device__ __forceinline__ float lo_dec(unsigned w, int i) { return (i == 0 ? __builtin_amdgcn_cvt_f32_fp8(w, 0) : i == 1 ? __builtin_amdgcn_cvt_f32_fp8(w, 1) : i == 2 ? __builtin_amdgcn_cvt_f32_fp8(w, 2) : __builtin_amdgcn_cvt_f32_fp8(w, 3)) * (1.0f / 4096.0f); }
;     __device__ __forceinline__ void operator()(const f32x4 (&acc)[2][2][4][2], const Unit& u, int wr, int wc, int fr_, int fq_) const {
;     ...
;                     u32x4 lo_out; float ss = 0.f;
; #pragma unroll
;                     for (int bj = 0; bj < 2; ++bj) {
;                         f32x4 a, b; unpack8(bj ? h1[k & 1][j] : h0[k & 1][j], a, b);
; #pragma unroll
;                         for (int i = 0; i < 4; ++i) { a[i] += lo_dec(lw[k & 1][j][2 * bj], i); b[i] += lo_dec(lw[k & 1][j][2 * bj + 1], i); }
;                         a = a + acc[ai][bj][m][0]; b = b + acc[ai][bj][m][1];
;                         const u32x4 hw = pack8(a, b);
;                         *(u32x4*)(XH + off + 8 * bj) = hw;
;                         f32x4 ra, rb; unpack8(hw, ra, rb);
;                         lo_out[2 * bj] = lo_enc(a - ra); lo_out[2 * bj + 1] = lo_enc(b - rb);
;                         ss += ((a[0] * a[0] + a[1] * a[1]) + (a[2] * a[2] + a[3] * a[3])) + ((b[0] * b[0] + b[1] * b[1]) + (b[2] * b[2] + b[3] * b[3]));
;                     }
;                     *(u32x4*)(XL + off) = lo_out;
;                     ss += __shfl_xor(ss, 16); ss += __shfl_xor(ss, 32);
;                     if (fq == 0) SSo[(size_t)(u.pm * 256 + ai * 128 + wr * 64 + m * 16 + fr) * 16 + 4 * u.pn + wc] = ss;
	v_cvt_f32_fp8_e32 v94, v122
	v_cvt_f32_fp8_sdwa v95, v122 src0_sel:BYTE_1
	v_cvt_f32_fp8_e32 v96, v123
	v_cvt_f32_fp8_sdwa v97, v123 src0_sel:BYTE_1
	v_lshlrev_b32_e32 v98, 16, v138
	v_and_b32_e32 v99, 0xffff0000, v138
	v_pk_fma_f32 v[94:95], v[94:95], s[22:23], v[98:99] op_sel_hi:[1,0,1]
	v_lshlrev_b32_e32 v98, 16, v140
	v_and_b32_e32 v99, 0xffff0000, v140
	v_pk_fma_f32 v[96:97], v[96:97], s[22:23], v[98:99] op_sel_hi:[1,0,1]
	v_cvt_f32_fp8_sdwa v98, v122 src0_sel:BYTE_2
	v_cvt_f32_fp8_sdwa v99, v122 src0_sel:BYTE_3
	v_cvt_f32_fp8_sdwa v100, v123 src0_sel:BYTE_2
	v_cvt_f32_fp8_sdwa v101, v123 src0_sel:BYTE_3
	v_lshlrev_b32_e32 v106, 16, v139
	v_and_b32_e32 v107, 0xffff0000, v139
	v_pk_fma_f32 v[98:99], v[98:99], s[22:23], v[106:107] op_sel_hi:[1,0,1]
	v_lshlrev_b32_e32 v106, 16, v141
	v_and_b32_e32 v107, 0xffff0000, v141
	v_pk_fma_f32 v[100:101], v[100:101], s[22:23], v[106:107] op_sel_hi:[1,0,1]
	v_pk_add_f32 v[62:63], v[62:63], v[94:95]
	v_pk_add_f32 v[96:97], v[58:59], v[96:97]
	v_cvt_pk_bf16_f32 v58, v62, v63
	v_pk_add_f32 v[64:65], v[64:65], v[98:99]
	v_pk_add_f32 v[94:95], v[60:61], v[100:101]
	v_cvt_pk_bf16_f32 v59, v64, v65
	v_cvt_pk_bf16_f32 v60, v96, v97
	v_lshlrev_b32_e32 v98, 16, v58
	v_cvt_pk_bf16_f32 v61, v94, v95
	v_mov_b32_e32 v222, v58
	v_mov_b32_e32 v223, v59
	v_mov_b32_e32 v224, v60
	v_mov_b32_e32 v225, v61
	v_sub_f32_e32 v98, v62, v98
	v_mul_f32_e32 v98, 0x45800000, v98
	v_and_b32_e32 v58, 0xffff0000, v58
	v_sub_f32_e32 v58, v63, v58
	v_mul_f32_e32 v58, 0x45800000, v58
	v_med3_f32 v98, v98, s3, v206
	v_med3_f32 v106, v58, s3, v206
	v_mov_b32_e32 v58, v1
	v_lshlrev_b32_e32 v99, 16, v59
	v_and_b32_e32 v59, 0xffff0000, v59
	v_cvt_pk_fp8_f32 v58, v98, v106
	v_sub_f32_e32 v59, v65, v59
	v_sub_f32_e32 v99, v64, v99
	v_mul_f32_e32 v99, 0x45800000, v99
	v_mul_f32_e32 v59, 0x45800000, v59
	v_lshlrev_b32_e32 v100, 16, v60
	v_and_b32_e32 v60, 0xffff0000, v60
	v_med3_f32 v98, v99, s3, v206
	v_med3_f32 v59, v59, s3, v206
	v_lshlrev_b32_e32 v101, 16, v61
	v_cvt_pk_fp8_f32 v58, v98, v59 op_sel:[0,0,1]
	v_sub_f32_e32 v60, v97, v60
	v_sub_f32_e32 v98, v96, v100
	v_sub_f32_e32 v59, v94, v101
	v_mul_f32_e32 v98, 0x45800000, v98
	v_mul_f32_e32 v60, 0x45800000, v60
	v_med3_f32 v98, v98, s3, v206
	v_med3_f32 v60, v60, s3, v206
	v_mul_f32_e32 v99, 0x45800000, v59
	v_mov_b32_e32 v59, v1
	v_and_b32_e32 v61, 0xffff0000, v61
	v_cvt_pk_fp8_f32 v59, v98, v60
	v_sub_f32_e32 v61, v95, v61
	v_mul_f32_e32 v61, 0x45800000, v61
	v_med3_f32 v60, v99, s3, v206
	v_med3_f32 v61, v61, s3, v206
	v_cvt_pk_fp8_f32 v59, v60, v61 op_sel:[0,0,1]
	v_mul_f32_e32 v60, v63, v63
	v_mul_f32_e32 v61, v65, v65
	v_fmac_f32_e32 v60, v62, v62
	v_fmac_f32_e32 v61, v64, v64
	v_add_f32_e32 v60, v60, v61
	v_mul_f32_e32 v61, v97, v97
	v_mul_f32_e32 v62, v95, v95
	v_fmac_f32_e32 v61, v96, v96
	v_fmac_f32_e32 v62, v94, v94
	v_add_f32_e32 v61, v61, v62
	v_add_f32_e32 v98, v60, v61
	v_cvt_f32_fp8_e32 v60, v124
	v_cvt_f32_fp8_sdwa v61, v124 src0_sel:BYTE_1
	v_cvt_f32_fp8_e32 v62, v125
	v_cvt_f32_fp8_sdwa v63, v125 src0_sel:BYTE_1
	s_waitcnt vmcnt(15)
	v_lshlrev_b32_e32 v64, 16, v134
	v_and_b32_e32 v65, 0xffff0000, v134
	v_pk_fma_f32 v[60:61], v[60:61], s[22:23], v[64:65] op_sel_hi:[1,0,1]
	v_lshlrev_b32_e32 v64, 16, v136
	v_and_b32_e32 v65, 0xffff0000, v136
	v_pk_fma_f32 v[62:63], v[62:63], s[22:23], v[64:65] op_sel_hi:[1,0,1]
	v_cvt_f32_fp8_sdwa v64, v124 src0_sel:BYTE_2
	v_cvt_f32_fp8_sdwa v65, v124 src0_sel:BYTE_3
	v_cvt_f32_fp8_sdwa v94, v125 src0_sel:BYTE_2
	v_cvt_f32_fp8_sdwa v95, v125 src0_sel:BYTE_3
	v_lshlrev_b32_e32 v96, 16, v135
	v_and_b32_e32 v97, 0xffff0000, v135
	v_pk_fma_f32 v[64:65], v[64:65], s[22:23], v[96:97] op_sel_hi:[1,0,1]
	v_lshlrev_b32_e32 v96, 16, v137
	v_and_b32_e32 v97, 0xffff0000, v137
	v_pk_fma_f32 v[94:95], v[94:95], s[22:23], v[96:97] op_sel_hi:[1,0,1]
	v_pk_add_f32 v[56:57], v[56:57], v[64:65]
	v_pk_add_f32 v[64:65], v[54:55], v[60:61]
	v_pk_add_f32 v[94:95], v[52:53], v[94:95]
	v_cvt_pk_bf16_f32 v52, v64, v65
	v_pk_add_f32 v[50:51], v[50:51], v[62:63]
	v_lshlrev_b32_e32 v60, 16, v52
	v_and_b32_e32 v61, 0xffff0000, v52
	v_sub_f32_e32 v60, v64, v60
	v_sub_f32_e32 v61, v65, v61
	v_mul_f32_e32 v60, 0x45800000, v60
	v_med3_f32 v101, v60, s3, v206
	v_mul_f32_e32 v60, 0x45800000, v61
	v_cvt_pk_bf16_f32 v53, v56, v57
	v_med3_f32 v61, v60, s3, v206
	v_lshlrev_b32_e32 v62, 16, v53
	v_mov_b32_e32 v60, v1
	v_and_b32_e32 v63, 0xffff0000, v53
	v_sub_f32_e32 v62, v56, v62
	v_cvt_pk_fp8_f32 v60, v101, v61
	v_sub_f32_e32 v63, v57, v63
	v_mul_f32_e32 v62, 0x45800000, v62
	v_cvt_pk_bf16_f32 v54, v50, v51
	v_med3_f32 v61, v62, s3, v206
	v_lshlrev_b32_e32 v96, 16, v54
	v_and_b32_e32 v97, 0xffff0000, v54
	v_mul_f32_e32 v62, 0x45800000, v63
	v_cvt_pk_bf16_f32 v55, v94, v95
	v_med3_f32 v62, v62, s3, v206
	v_lshlrev_b32_e32 v99, 16, v55
	v_sub_f32_e32 v63, v51, v97
	v_sub_f32_e32 v96, v50, v96
	v_cvt_pk_fp8_f32 v60, v61, v62 op_sel:[0,0,1]
	v_sub_f32_e32 v61, v94, v99
	v_mul_f32_e32 v96, 0x45800000, v96
	v_mul_f32_e32 v63, 0x45800000, v63
	v_med3_f32 v96, v96, s3, v206
	v_med3_f32 v63, v63, s3, v206
	v_mul_f32_e32 v97, 0x45800000, v61
	v_mov_b32_e32 v61, v1
	v_mul_f32_e32 v51, v51, v51
	v_cvt_pk_fp8_f32 v61, v96, v63
	v_mul_f32_e32 v63, v65, v65
	v_mul_f32_e32 v57, v57, v57
	v_fmac_f32_e32 v51, v50, v50
	v_mul_f32_e32 v50, v95, v95
	v_fmac_f32_e32 v63, v64, v64
	v_fmac_f32_e32 v57, v56, v56
	v_fmac_f32_e32 v50, v94, v94
	v_add_f32_e32 v56, v63, v57
	v_add_f32_e32 v50, v51, v50
	v_add_f32_e32 v50, v56, v50
	v_add_f32_e32 v50, v98, v50
	ds_bpermute_b32 v51, v150, v50
	v_and_b32_e32 v100, 0xffff0000, v55
	v_sub_f32_e32 v62, v95, v100
	v_mul_f32_e32 v57, 0x45800000, v62
	v_med3_f32 v56, v97, s3, v206
	s_waitcnt lgkmcnt(0)
	v_add_f32_e32 v50, v50, v51
	ds_bpermute_b32 v51, v151, v50
	v_med3_f32 v57, v57, s3, v206
	v_cvt_pk_fp8_f32 v61, v56, v57 op_sel:[0,0,1]
	s_mov_b64 s[30:31], 0x20000
	v_lshl_add_u64 v[56:57], v[174:175], 0, s[30:31]
	v_mov_b32_e32 v226, v52
	v_mov_b32_e32 v227, v53
	v_mov_b32_e32 v228, v54
	v_mov_b32_e32 v229, v55
	s_nop 1
	v_permlane16_swap_b32_e32 v222, v226
	v_permlane16_swap_b32_e32 v223, v227
	v_permlane16_swap_b32_e32 v224, v228
	v_permlane16_swap_b32_e32 v225, v229
	v_permlane32_swap_b32_e32 v222, v226
	v_permlane32_swap_b32_e32 v223, v227
	v_permlane32_swap_b32_e32 v224, v228
	v_permlane32_swap_b32_e32 v225, v229
	v_lshl_add_u64 v[230:231], v[148:149], 0, v[232:233]
	global_store_dwordx4 v[230:231], v[222:225], off
	global_store_dwordx4 v[230:231], v[226:229], off offset:64
	global_store_dwordx4 v[56:57], v[58:61], off
	s_and_saveexec_b64 s[36:37], s[40:41]
	s_cbranch_execz .LBB0_384
	v_add_u32_e32 v52, 0x80, v172
	v_ashrrev_i32_e32 v53, 31, v52
	v_readlane_b32 s30, v255, 23
	s_waitcnt lgkmcnt(0)
	v_add_f32_e32 v54, v50, v51
	v_lshlrev_b64 v[50:51], 6, v[52:53]
	v_readlane_b32 s31, v255, 24
	s_lshl_b32 s24, s58, 2
	s_nop 0
	v_lshl_add_u64 v[50:51], s[30:31], 0, v[50:51]
	v_lshl_add_u64 v[50:51], s[52:53], 2, v[50:51]
	v_lshl_add_u64 v[50:51], v[50:51], 0, s[24:25]
	global_store_dword v[50:51], v54, off
; __device__ __forceinline__ u32x4 pack8(f32x4 a, f32x4 b) { u32x4 w; w.x = cvt_pk_bf16(a[0], a[1]); w.y = cvt_pk_bf16(a[2], a[3]); w.z = cvt_pk_bf16(b[0], b[1]); w.w = cvt_pk_bf16(b[2], b[3]); return w; }
; __device__ __forceinline__ void unpack8(u32x4 w, f32x4& a, f32x4& b) { a = (f32x4){bf_lo(w.x), bf_hi(w.x), bf_lo(w.y), bf_hi(w.y)}; b = (f32x4){bf_lo(w.z), bf_hi(w.z), bf_lo(w.w), bf_hi(w.w)}; }
; __device__ __forceinline__ float lo_dec(unsigned w, int i) { return (i == 0 ? __builtin_amdgcn_cvt_f32_fp8(w, 0) : i == 1 ? __builtin_amdgcn_cvt_f32_fp8(w, 1) : i == 2 ? __builtin_amdgcn_cvt_f32_fp8(w, 2) : __builtin_amdgcn_cvt_f32_fp8(w, 3)) * (1.0f / 4096.0f); }
;     __device__ __forceinline__ void operator()(const f32x4 (&acc)[2][2][4][2], const Unit& u, int wr, int wc, int fr_, int fq_) const {
;     ...
;         for (int k = 0; k < 6; ++k) {
;             if (k >= 2) {
; #pragma unroll
;                 for (int j = 0; j < 2; ++j) {
;                     const int kb = k - 2, ai = kb >> 1, m = (kb & 1) * 2 + j;
;                     const size_t off = off0 + (size_t)(ai * 128 + m * 16) * 1024;
;                     u32x4 lo_out; float ss = 0.f;
; #pragma unroll
;                     for (int bj = 0; bj < 2; ++bj) {
;                         f32x4 a, b; unpack8(bj ? h1[k & 1][j] : h0[k & 1][j], a, b);
; #pragma unroll
;                         for (int i = 0; i < 4; ++i) { a[i] += lo_dec(lw[k & 1][j][2 * bj], i); b[i] += lo_dec(lw[k & 1][j][2 * bj + 1], i); }
;                         a = a + acc[ai][bj][m][0]; b = b + acc[ai][bj][m][1];
;                         const u32x4 hw = pack8(a, b);
;                         *(u32x4*)(XH + off + 8 * bj) = hw;
;                         f32x4 ra, rb; unpack8(hw, ra, rb);
;                         lo_out[2 * bj] = lo_enc(a - ra); lo_out[2 * bj + 1] = lo_enc(b - rb);
;                         ss += ((a[0] * a[0] + a[1] * a[1]) + (a[2] * a[2] + a[3] * a[3])) + ((b[0] * b[0] + b[1] * b[1]) + (b[2] * b[2] + b[3] * b[3]));
;                     }
;                     *(u32x4*)(XL + off) = lo_out;
;                     ss += __shfl_xor(ss, 16); ss += __shfl_xor(ss, 32);
;                     if (fq == 0) SSo[(size_t)(u.pm * 256 + ai * 128 + wr * 64 + m * 16 + fr) * 16 + 4 * u.pn + wc] = ss;
;                 }
.LBB0_384:
	s_or_b64 exec, exec, s[36:37]
	s_waitcnt vmcnt(15)
	v_cvt_f32_fp8_e32 v50, v110
	s_waitcnt lgkmcnt(0)
	v_cvt_f32_fp8_sdwa v51, v110 src0_sel:BYTE_1
	v_cvt_f32_fp8_e32 v52, v111
	v_cvt_f32_fp8_sdwa v53, v111 src0_sel:BYTE_1
	v_lshlrev_b32_e32 v54, 16, v118
	v_and_b32_e32 v55, 0xffff0000, v118
	v_pk_fma_f32 v[50:51], v[50:51], s[22:23], v[54:55] op_sel_hi:[1,0,1]
	v_lshlrev_b32_e32 v54, 16, v120
	v_and_b32_e32 v55, 0xffff0000, v120
	v_pk_fma_f32 v[52:53], v[52:53], s[22:23], v[54:55] op_sel_hi:[1,0,1]
	v_cvt_f32_fp8_sdwa v54, v110 src0_sel:BYTE_2
	v_cvt_f32_fp8_sdwa v55, v110 src0_sel:BYTE_3
	v_cvt_f32_fp8_sdwa v56, v111 src0_sel:BYTE_2
	v_cvt_f32_fp8_sdwa v57, v111 src0_sel:BYTE_3
	v_lshlrev_b32_e32 v58, 16, v119
	v_and_b32_e32 v59, 0xffff0000, v119
	v_pk_fma_f32 v[54:55], v[54:55], s[22:23], v[58:59] op_sel_hi:[1,0,1]
	v_lshlrev_b32_e32 v58, 16, v121
	v_and_b32_e32 v59, 0xffff0000, v121
	v_pk_fma_f32 v[56:57], v[56:57], s[22:23], v[58:59] op_sel_hi:[1,0,1]
	v_pk_add_f32 v[46:47], v[46:47], v[50:51]
	v_pk_add_f32 v[52:53], v[42:43], v[52:53]
	v_cvt_pk_bf16_f32 v42, v46, v47
	v_pk_add_f32 v[48:49], v[48:49], v[54:55]
	v_pk_add_f32 v[50:51], v[44:45], v[56:57]
	v_cvt_pk_bf16_f32 v43, v48, v49
	v_cvt_pk_bf16_f32 v44, v52, v53
	v_lshlrev_b32_e32 v54, 16, v42
	v_cvt_pk_bf16_f32 v45, v50, v51
	v_mov_b32_e32 v222, v42
	v_mov_b32_e32 v223, v43
	v_mov_b32_e32 v224, v44
	v_mov_b32_e32 v225, v45
	v_sub_f32_e32 v54, v46, v54
	v_mul_f32_e32 v54, 0x45800000, v54
	v_and_b32_e32 v42, 0xffff0000, v42
	v_sub_f32_e32 v42, v47, v42
	v_mul_f32_e32 v42, 0x45800000, v42
	v_med3_f32 v54, v54, s3, v206
	v_med3_f32 v58, v42, s3, v206
	v_mov_b32_e32 v42, v1
	v_lshlrev_b32_e32 v55, 16, v43
	v_and_b32_e32 v43, 0xffff0000, v43
	v_cvt_pk_fp8_f32 v42, v54, v58
	v_sub_f32_e32 v43, v49, v43
	v_sub_f32_e32 v55, v48, v55
	v_mul_f32_e32 v55, 0x45800000, v55
	v_mul_f32_e32 v43, 0x45800000, v43
	v_lshlrev_b32_e32 v56, 16, v44
	v_and_b32_e32 v44, 0xffff0000, v44
	v_med3_f32 v54, v55, s3, v206
	v_med3_f32 v43, v43, s3, v206
	v_lshlrev_b32_e32 v57, 16, v45
	v_cvt_pk_fp8_f32 v42, v54, v43 op_sel:[0,0,1]
	v_sub_f32_e32 v44, v53, v44
	v_sub_f32_e32 v54, v52, v56
	v_sub_f32_e32 v43, v50, v57
	v_mul_f32_e32 v54, 0x45800000, v54
	v_mul_f32_e32 v44, 0x45800000, v44
	v_med3_f32 v54, v54, s3, v206
	v_med3_f32 v44, v44, s3, v206
	v_mul_f32_e32 v55, 0x45800000, v43
	v_mov_b32_e32 v43, v1
	v_and_b32_e32 v45, 0xffff0000, v45
	v_cvt_pk_fp8_f32 v43, v54, v44
	v_sub_f32_e32 v45, v51, v45
	v_mul_f32_e32 v45, 0x45800000, v45
	v_med3_f32 v44, v55, s3, v206
	v_med3_f32 v45, v45, s3, v206
	v_cvt_pk_fp8_f32 v43, v44, v45 op_sel:[0,0,1]
	v_mul_f32_e32 v44, v47, v47
	v_mul_f32_e32 v45, v49, v49
	v_fmac_f32_e32 v44, v46, v46
	v_fmac_f32_e32 v45, v48, v48
	v_add_f32_e32 v44, v44, v45
	v_mul_f32_e32 v45, v53, v53
	v_mul_f32_e32 v46, v51, v51
	v_fmac_f32_e32 v45, v52, v52
	v_fmac_f32_e32 v46, v50, v50
	v_add_f32_e32 v45, v45, v46
	v_add_f32_e32 v54, v44, v45
	v_cvt_f32_fp8_e32 v44, v112
	v_cvt_f32_fp8_sdwa v45, v112 src0_sel:BYTE_1
	v_cvt_f32_fp8_e32 v46, v113
	v_cvt_f32_fp8_sdwa v47, v113 src0_sel:BYTE_1
	v_lshlrev_b32_e32 v48, 16, v102
	v_and_b32_e32 v49, 0xffff0000, v102
	v_pk_fma_f32 v[44:45], v[44:45], s[22:23], v[48:49] op_sel_hi:[1,0,1]
	v_lshlrev_b32_e32 v48, 16, v104
	v_and_b32_e32 v49, 0xffff0000, v104
	v_pk_fma_f32 v[46:47], v[46:47], s[22:23], v[48:49] op_sel_hi:[1,0,1]
	v_cvt_f32_fp8_sdwa v48, v112 src0_sel:BYTE_2
	v_cvt_f32_fp8_sdwa v49, v112 src0_sel:BYTE_3
	v_cvt_f32_fp8_sdwa v50, v113 src0_sel:BYTE_2
	v_cvt_f32_fp8_sdwa v51, v113 src0_sel:BYTE_3
	v_lshlrev_b32_e32 v52, 16, v103
	v_and_b32_e32 v53, 0xffff0000, v103
	v_pk_fma_f32 v[48:49], v[48:49], s[22:23], v[52:53] op_sel_hi:[1,0,1]
	v_lshlrev_b32_e32 v52, 16, v105
	v_and_b32_e32 v53, 0xffff0000, v105
	v_pk_fma_f32 v[50:51], v[50:51], s[22:23], v[52:53] op_sel_hi:[1,0,1]
	v_pk_add_f32 v[40:41], v[40:41], v[48:49]
	v_pk_add_f32 v[48:49], v[38:39], v[44:45]
	v_pk_add_f32 v[50:51], v[36:37], v[50:51]
	v_cvt_pk_bf16_f32 v36, v48, v49
	v_pk_add_f32 v[34:35], v[34:35], v[46:47]
	v_lshlrev_b32_e32 v44, 16, v36
	v_and_b32_e32 v45, 0xffff0000, v36
	v_sub_f32_e32 v44, v48, v44
	v_sub_f32_e32 v45, v49, v45
	v_mul_f32_e32 v44, 0x45800000, v44
	v_med3_f32 v57, v44, s3, v206
	v_mul_f32_e32 v44, 0x45800000, v45
	v_cvt_pk_bf16_f32 v37, v40, v41
	v_med3_f32 v45, v44, s3, v206
	v_lshlrev_b32_e32 v46, 16, v37
	v_mov_b32_e32 v44, v1
	v_and_b32_e32 v47, 0xffff0000, v37
	v_sub_f32_e32 v46, v40, v46
	v_cvt_pk_fp8_f32 v44, v57, v45
	v_sub_f32_e32 v47, v41, v47
	v_mul_f32_e32 v46, 0x45800000, v46
	v_cvt_pk_bf16_f32 v38, v34, v35
	v_med3_f32 v45, v46, s3, v206
	v_lshlrev_b32_e32 v52, 16, v38
	v_and_b32_e32 v53, 0xffff0000, v38
	v_mul_f32_e32 v46, 0x45800000, v47
	v_cvt_pk_bf16_f32 v39, v50, v51
	v_med3_f32 v46, v46, s3, v206
	v_lshlrev_b32_e32 v55, 16, v39
	v_sub_f32_e32 v47, v35, v53
	v_sub_f32_e32 v52, v34, v52
	v_cvt_pk_fp8_f32 v44, v45, v46 op_sel:[0,0,1]
	v_sub_f32_e32 v45, v50, v55
	v_mul_f32_e32 v52, 0x45800000, v52
	v_mul_f32_e32 v47, 0x45800000, v47
	v_med3_f32 v52, v52, s3, v206
	v_med3_f32 v47, v47, s3, v206
	v_mul_f32_e32 v53, 0x45800000, v45
	v_mov_b32_e32 v45, v1
	v_mul_f32_e32 v35, v35, v35
	v_cvt_pk_fp8_f32 v45, v52, v47
	v_mul_f32_e32 v47, v49, v49
	v_mul_f32_e32 v41, v41, v41
	v_fmac_f32_e32 v35, v34, v34
	v_mul_f32_e32 v34, v51, v51
	v_fmac_f32_e32 v47, v48, v48
	v_fmac_f32_e32 v41, v40, v40
	v_fmac_f32_e32 v34, v50, v50
	v_add_f32_e32 v40, v47, v41
	v_add_f32_e32 v34, v35, v34
	v_add_f32_e32 v34, v40, v34
	v_add_f32_e32 v34, v54, v34
	ds_bpermute_b32 v35, v150, v34
	v_and_b32_e32 v56, 0xffff0000, v39
	v_sub_f32_e32 v46, v51, v56
	v_mul_f32_e32 v41, 0x45800000, v46
	v_med3_f32 v40, v53, s3, v206
	s_waitcnt lgkmcnt(0)
	v_add_f32_e32 v34, v34, v35
	ds_bpermute_b32 v35, v151, v34
	v_med3_f32 v41, v41, s3, v206
	v_cvt_pk_fp8_f32 v45, v40, v41 op_sel:[0,0,1]
	s_mov_b64 s[30:31], 0x24000
	v_lshl_add_u64 v[40:41], v[174:175], 0, s[30:31]
	v_mov_b32_e32 v226, v36
	v_mov_b32_e32 v227, v37
	v_mov_b32_e32 v228, v38
	v_mov_b32_e32 v229, v39
	s_nop 1
	v_permlane16_swap_b32_e32 v222, v226
	v_permlane16_swap_b32_e32 v223, v227
	v_permlane16_swap_b32_e32 v224, v228
	v_permlane16_swap_b32_e32 v225, v229
	v_permlane32_swap_b32_e32 v222, v226
	v_permlane32_swap_b32_e32 v223, v227
	v_permlane32_swap_b32_e32 v224, v228
	v_permlane32_swap_b32_e32 v225, v229
	v_lshl_add_u64 v[230:231], v[146:147], 0, v[232:233]
	global_store_dwordx4 v[230:231], v[222:225], off
	global_store_dwordx4 v[230:231], v[226:229], off offset:64
	global_store_dwordx4 v[40:41], v[42:45], off
	s_and_saveexec_b64 s[36:37], s[40:41]
	s_cbranch_execz .LBB0_386
; __device__ __forceinline__ u32x4 pack8(f32x4 a, f32x4 b) { u32x4 w; w.x = cvt_pk_bf16(a[0], a[1]); w.y = cvt_pk_bf16(a[2], a[3]); w.z = cvt_pk_bf16(b[0], b[1]); w.w = cvt_pk_bf16(b[2], b[3]); return w; }
; __device__ __forceinline__ void unpack8(u32x4 w, f32x4& a, f32x4& b) { a = (f32x4){bf_lo(w.x), bf_hi(w.x), bf_lo(w.y), bf_hi(w.y)}; b = (f32x4){bf_lo(w.z), bf_hi(w.z), bf_lo(w.w), bf_hi(w.w)}; }
; __device__ __forceinline__ float lo_dec(unsigned w, int i) { return (i == 0 ? __builtin_amdgcn_cvt_f32_fp8(w, 0) : i == 1 ? __builtin_amdgcn_cvt_f32_fp8(w, 1) : i == 2 ? __builtin_amdgcn_cvt_f32_fp8(w, 2) : __builtin_amdgcn_cvt_f32_fp8(w, 3)) * (1.0f / 4096.0f); }
;     __device__ __forceinline__ void operator()(const f32x4 (&acc)[2][2][4][2], const Unit& u, int wr, int wc, int fr_, int fq_) const {
;     ...
;                     u32x4 lo_out; float ss = 0.f;
; #pragma unroll
;                     for (int bj = 0; bj < 2; ++bj) {
;                         f32x4 a, b; unpack8(bj ? h1[k & 1][j] : h0[k & 1][j], a, b);
; #pragma unroll
;                         for (int i = 0; i < 4; ++i) { a[i] += lo_dec(lw[k & 1][j][2 * bj], i); b[i] += lo_dec(lw[k & 1][j][2 * bj + 1], i); }
;                         a = a + acc[ai][bj][m][0]; b = b + acc[ai][bj][m][1];
;                         const u32x4 hw = pack8(a, b);
;                         *(u32x4*)(XH + off + 8 * bj) = hw;
;                         f32x4 ra, rb; unpack8(hw, ra, rb);
;                         lo_out[2 * bj] = lo_enc(a - ra); lo_out[2 * bj + 1] = lo_enc(b - rb);
;                         ss += ((a[0] * a[0] + a[1] * a[1]) + (a[2] * a[2] + a[3] * a[3])) + ((b[0] * b[0] + b[1] * b[1]) + (b[2] * b[2] + b[3] * b[3]));
;                     }
;                     *(u32x4*)(XL + off) = lo_out;
;                     ss += __shfl_xor(ss, 16); ss += __shfl_xor(ss, 32);
;                     if (fq == 0) SSo[(size_t)(u.pm * 256 + ai * 128 + wr * 64 + m * 16 + fr) * 16 + 4 * u.pn + wc] = ss;
	s_waitcnt lgkmcnt(0)
	v_add_f32_e32 v36, v34, v35
	v_add_u32_e32 v34, 0x90, v172
	v_ashrrev_i32_e32 v35, 31, v34
	v_readlane_b32 s30, v255, 23
	v_lshlrev_b64 v[34:35], 6, v[34:35]
	v_readlane_b32 s31, v255, 24
	s_lshl_b32 s24, s58, 2
	s_nop 0
	v_lshl_add_u64 v[34:35], s[30:31], 0, v[34:35]
	v_lshl_add_u64 v[34:35], s[52:53], 2, v[34:35]
	v_lshl_add_u64 v[34:35], v[34:35], 0, s[24:25]
	global_store_dword v[34:35], v36, off
.LBB0_386:
	s_or_b64 exec, exec, s[36:37]
	s_waitcnt vmcnt(10)
	v_cvt_f32_fp8_e32 v34, v78
	s_waitcnt lgkmcnt(0)
	v_cvt_f32_fp8_sdwa v35, v78 src0_sel:BYTE_1
	v_cvt_f32_fp8_e32 v36, v79
	v_cvt_f32_fp8_sdwa v37, v79 src0_sel:BYTE_1
	v_lshlrev_b32_e32 v38, 16, v86
	v_and_b32_e32 v39, 0xffff0000, v86
	v_pk_fma_f32 v[34:35], v[34:35], s[22:23], v[38:39] op_sel_hi:[1,0,1]
	v_lshlrev_b32_e32 v38, 16, v88
	v_and_b32_e32 v39, 0xffff0000, v88
	v_pk_fma_f32 v[36:37], v[36:37], s[22:23], v[38:39] op_sel_hi:[1,0,1]
	v_cvt_f32_fp8_sdwa v38, v78 src0_sel:BYTE_2
	v_cvt_f32_fp8_sdwa v39, v78 src0_sel:BYTE_3
	v_cvt_f32_fp8_sdwa v40, v79 src0_sel:BYTE_2
	v_cvt_f32_fp8_sdwa v41, v79 src0_sel:BYTE_3
	v_lshlrev_b32_e32 v42, 16, v87
	v_and_b32_e32 v43, 0xffff0000, v87
	v_pk_fma_f32 v[38:39], v[38:39], s[22:23], v[42:43] op_sel_hi:[1,0,1]
	v_lshlrev_b32_e32 v42, 16, v89
	v_and_b32_e32 v43, 0xffff0000, v89
	v_pk_fma_f32 v[40:41], v[40:41], s[22:23], v[42:43] op_sel_hi:[1,0,1]
	v_pk_add_f32 v[30:31], v[30:31], v[34:35]
	v_pk_add_f32 v[36:37], v[26:27], v[36:37]
	v_cvt_pk_bf16_f32 v26, v30, v31
	v_pk_add_f32 v[32:33], v[32:33], v[38:39]
	v_pk_add_f32 v[34:35], v[28:29], v[40:41]
	v_cvt_pk_bf16_f32 v27, v32, v33
	v_cvt_pk_bf16_f32 v28, v36, v37
	v_lshlrev_b32_e32 v38, 16, v26
	v_cvt_pk_bf16_f32 v29, v34, v35
	v_mov_b32_e32 v222, v26
	v_mov_b32_e32 v223, v27
	v_mov_b32_e32 v224, v28
	v_mov_b32_e32 v225, v29
	v_sub_f32_e32 v38, v30, v38
	v_mul_f32_e32 v38, 0x45800000, v38
	v_and_b32_e32 v26, 0xffff0000, v26
	v_sub_f32_e32 v26, v31, v26
	v_mul_f32_e32 v26, 0x45800000, v26
	v_med3_f32 v38, v38, s3, v206
	v_med3_f32 v42, v26, s3, v206
	v_mov_b32_e32 v26, v1
	v_lshlrev_b32_e32 v39, 16, v27
	v_and_b32_e32 v27, 0xffff0000, v27
	v_cvt_pk_fp8_f32 v26, v38, v42
	v_sub_f32_e32 v27, v33, v27
	v_sub_f32_e32 v39, v32, v39
	v_mul_f32_e32 v39, 0x45800000, v39
	v_mul_f32_e32 v27, 0x45800000, v27
	v_lshlrev_b32_e32 v40, 16, v28
	v_and_b32_e32 v28, 0xffff0000, v28
	v_med3_f32 v38, v39, s3, v206
	v_med3_f32 v27, v27, s3, v206
	v_lshlrev_b32_e32 v41, 16, v29
	v_cvt_pk_fp8_f32 v26, v38, v27 op_sel:[0,0,1]
	v_sub_f32_e32 v28, v37, v28
	v_sub_f32_e32 v38, v36, v40
	v_sub_f32_e32 v27, v34, v41
	v_mul_f32_e32 v38, 0x45800000, v38
	v_mul_f32_e32 v28, 0x45800000, v28
	v_med3_f32 v38, v38, s3, v206
	v_med3_f32 v28, v28, s3, v206
	v_mul_f32_e32 v39, 0x45800000, v27
	v_mov_b32_e32 v27, v1
	v_and_b32_e32 v29, 0xffff0000, v29
	v_cvt_pk_fp8_f32 v27, v38, v28
	v_sub_f32_e32 v29, v35, v29
	v_mul_f32_e32 v29, 0x45800000, v29
	v_med3_f32 v28, v39, s3, v206
	v_med3_f32 v29, v29, s3, v206
	v_cvt_pk_fp8_f32 v27, v28, v29 op_sel:[0,0,1]
	v_mul_f32_e32 v28, v31, v31
	v_mul_f32_e32 v29, v33, v33
	v_fmac_f32_e32 v28, v30, v30
	v_fmac_f32_e32 v29, v32, v32
	v_add_f32_e32 v28, v28, v29
	v_mul_f32_e32 v29, v37, v37
	v_mul_f32_e32 v30, v35, v35
	v_fmac_f32_e32 v29, v36, v36
	v_fmac_f32_e32 v30, v34, v34
	v_add_f32_e32 v29, v29, v30
	v_add_f32_e32 v38, v28, v29
	v_cvt_f32_fp8_e32 v28, v80
	v_cvt_f32_fp8_sdwa v29, v80 src0_sel:BYTE_1
	v_cvt_f32_fp8_e32 v30, v81
	v_cvt_f32_fp8_sdwa v31, v81 src0_sel:BYTE_1
	s_waitcnt vmcnt(9)
	v_lshlrev_b32_e32 v32, 16, v82
	v_and_b32_e32 v33, 0xffff0000, v82
	v_pk_fma_f32 v[28:29], v[28:29], s[22:23], v[32:33] op_sel_hi:[1,0,1]
	v_lshlrev_b32_e32 v32, 16, v84
	v_and_b32_e32 v33, 0xffff0000, v84
	v_pk_fma_f32 v[30:31], v[30:31], s[22:23], v[32:33] op_sel_hi:[1,0,1]
	v_cvt_f32_fp8_sdwa v32, v80 src0_sel:BYTE_2
	v_cvt_f32_fp8_sdwa v33, v80 src0_sel:BYTE_3
	v_cvt_f32_fp8_sdwa v34, v81 src0_sel:BYTE_2
	v_cvt_f32_fp8_sdwa v35, v81 src0_sel:BYTE_3
	v_lshlrev_b32_e32 v36, 16, v83
	v_and_b32_e32 v37, 0xffff0000, v83
	v_pk_fma_f32 v[32:33], v[32:33], s[22:23], v[36:37] op_sel_hi:[1,0,1]
	v_lshlrev_b32_e32 v36, 16, v85
	v_and_b32_e32 v37, 0xffff0000, v85
	v_pk_fma_f32 v[34:35], v[34:35], s[22:23], v[36:37] op_sel_hi:[1,0,1]
	v_pk_add_f32 v[24:25], v[24:25], v[32:33]
	v_pk_add_f32 v[32:33], v[22:23], v[28:29]
	v_pk_add_f32 v[34:35], v[20:21], v[34:35]
	v_cvt_pk_bf16_f32 v20, v32, v33
	v_pk_add_f32 v[18:19], v[18:19], v[30:31]
	v_lshlrev_b32_e32 v28, 16, v20
	v_and_b32_e32 v29, 0xffff0000, v20
	v_sub_f32_e32 v28, v32, v28
	v_sub_f32_e32 v29, v33, v29
	v_mul_f32_e32 v28, 0x45800000, v28
	v_med3_f32 v41, v28, s3, v206
	v_mul_f32_e32 v28, 0x45800000, v29
	v_cvt_pk_bf16_f32 v21, v24, v25
	v_med3_f32 v29, v28, s3, v206
	v_lshlrev_b32_e32 v30, 16, v21
	v_mov_b32_e32 v28, v1
	v_and_b32_e32 v31, 0xffff0000, v21
	v_sub_f32_e32 v30, v24, v30
	v_cvt_pk_fp8_f32 v28, v41, v29
	v_sub_f32_e32 v31, v25, v31
	v_mul_f32_e32 v30, 0x45800000, v30
	v_cvt_pk_bf16_f32 v22, v18, v19
	v_med3_f32 v29, v30, s3, v206
	v_lshlrev_b32_e32 v36, 16, v22
	v_and_b32_e32 v37, 0xffff0000, v22
	v_mul_f32_e32 v30, 0x45800000, v31
	v_cvt_pk_bf16_f32 v23, v34, v35
	v_med3_f32 v30, v30, s3, v206
	v_lshlrev_b32_e32 v39, 16, v23
	v_sub_f32_e32 v31, v19, v37
	v_sub_f32_e32 v36, v18, v36
	v_cvt_pk_fp8_f32 v28, v29, v30 op_sel:[0,0,1]
	v_sub_f32_e32 v29, v34, v39
	v_mul_f32_e32 v36, 0x45800000, v36
	v_mul_f32_e32 v31, 0x45800000, v31
	v_med3_f32 v36, v36, s3, v206
	v_med3_f32 v31, v31, s3, v206
	v_mul_f32_e32 v37, 0x45800000, v29
	v_mov_b32_e32 v29, v1
	v_mul_f32_e32 v19, v19, v19
	v_cvt_pk_fp8_f32 v29, v36, v31
	v_mul_f32_e32 v31, v33, v33
	v_mul_f32_e32 v25, v25, v25
	v_fmac_f32_e32 v19, v18, v18
	v_mul_f32_e32 v18, v35, v35
	v_fmac_f32_e32 v31, v32, v32
	v_fmac_f32_e32 v25, v24, v24
	v_fmac_f32_e32 v18, v34, v34
	v_add_f32_e32 v24, v31, v25
	v_add_f32_e32 v18, v19, v18
	v_add_f32_e32 v18, v24, v18
	v_add_f32_e32 v18, v38, v18
	ds_bpermute_b32 v19, v150, v18
	v_and_b32_e32 v40, 0xffff0000, v23
	v_sub_f32_e32 v30, v35, v40
	v_mul_f32_e32 v25, 0x45800000, v30
	v_med3_f32 v24, v37, s3, v206
	s_waitcnt lgkmcnt(0)
	v_add_f32_e32 v18, v18, v19
	ds_bpermute_b32 v19, v151, v18
	v_med3_f32 v25, v25, s3, v206
	v_cvt_pk_fp8_f32 v29, v24, v25 op_sel:[0,0,1]
	s_mov_b64 s[30:31], 0x28000
	v_lshl_add_u64 v[24:25], v[174:175], 0, s[30:31]
	v_mov_b32_e32 v226, v20
	v_mov_b32_e32 v227, v21
	v_mov_b32_e32 v228, v22
	v_mov_b32_e32 v229, v23
	s_nop 1
	v_permlane16_swap_b32_e32 v222, v226
	v_permlane16_swap_b32_e32 v223, v227
	v_permlane16_swap_b32_e32 v224, v228
	v_permlane16_swap_b32_e32 v225, v229
	v_permlane32_swap_b32_e32 v222, v226
	v_permlane32_swap_b32_e32 v223, v227
	v_permlane32_swap_b32_e32 v224, v228
	v_permlane32_swap_b32_e32 v225, v229
	v_lshl_add_u64 v[230:231], v[92:93], 0, v[232:233]
	global_store_dwordx4 v[230:231], v[222:225], off
	global_store_dwordx4 v[230:231], v[226:229], off offset:64
	global_store_dwordx4 v[24:25], v[26:29], off
	s_and_saveexec_b64 s[36:37], s[40:41]
	s_cbranch_execz .LBB0_388
;     __device__ __forceinline__ void operator()(const f32x4 (&acc)[2][2][4][2], const Unit& u, int wr, int wc, int fr_, int fq_) const {
;     ...
;                     ss += __shfl_xor(ss, 16); ss += __shfl_xor(ss, 32);
;                     if (fq == 0) SSo[(size_t)(u.pm * 256 + ai * 128 + wr * 64 + m * 16 + fr) * 16 + 4 * u.pn + wc] = ss;
	s_waitcnt lgkmcnt(0)
	v_add_f32_e32 v20, v18, v19
	v_add_u32_e32 v18, 0xa0, v172
	v_ashrrev_i32_e32 v19, 31, v18
	v_readlane_b32 s30, v255, 23
	v_lshlrev_b64 v[18:19], 6, v[18:19]
	v_readlane_b32 s31, v255, 24
	s_lshl_b32 s24, s58, 2
	s_nop 0
	v_lshl_add_u64 v[18:19], s[30:31], 0, v[18:19]
	v_lshl_add_u64 v[18:19], s[52:53], 2, v[18:19]
	v_lshl_add_u64 v[18:19], v[18:19], 0, s[24:25]
	global_store_dword v[18:19], v20, off
; __device__ __forceinline__ u32x4 pack8(f32x4 a, f32x4 b) { u32x4 w; w.x = cvt_pk_bf16(a[0], a[1]); w.y = cvt_pk_bf16(a[2], a[3]); w.z = cvt_pk_bf16(b[0], b[1]); w.w = cvt_pk_bf16(b[2], b[3]); return w; }
; __device__ __forceinline__ void unpack8(u32x4 w, f32x4& a, f32x4& b) { a = (f32x4){bf_lo(w.x), bf_hi(w.x), bf_lo(w.y), bf_hi(w.y)}; b = (f32x4){bf_lo(w.z), bf_hi(w.z), bf_lo(w.w), bf_hi(w.w)}; }
; __device__ __forceinline__ float lo_dec(unsigned w, int i) { return (i == 0 ? __builtin_amdgcn_cvt_f32_fp8(w, 0) : i == 1 ? __builtin_amdgcn_cvt_f32_fp8(w, 1) : i == 2 ? __builtin_amdgcn_cvt_f32_fp8(w, 2) : __builtin_amdgcn_cvt_f32_fp8(w, 3)) * (1.0f / 4096.0f); }
;     __device__ __forceinline__ void operator()(const f32x4 (&acc)[2][2][4][2], const Unit& u, int wr, int wc, int fr_, int fq_) const {
;     ...
;                     u32x4 lo_out; float ss = 0.f;
; #pragma unroll
;                     for (int bj = 0; bj < 2; ++bj) {
;                         f32x4 a, b; unpack8(bj ? h1[k & 1][j] : h0[k & 1][j], a, b);
; #pragma unroll
;                         for (int i = 0; i < 4; ++i) { a[i] += lo_dec(lw[k & 1][j][2 * bj], i); b[i] += lo_dec(lw[k & 1][j][2 * bj + 1], i); }
;                         a = a + acc[ai][bj][m][0]; b = b + acc[ai][bj][m][1];
;                         const u32x4 hw = pack8(a, b);
;                         *(u32x4*)(XH + off + 8 * bj) = hw;
;                         f32x4 ra, rb; unpack8(hw, ra, rb);
;                         lo_out[2 * bj] = lo_enc(a - ra); lo_out[2 * bj + 1] = lo_enc(b - rb);
;                         ss += ((a[0] * a[0] + a[1] * a[1]) + (a[2] * a[2] + a[3] * a[3])) + ((b[0] * b[0] + b[1] * b[1]) + (b[2] * b[2] + b[3] * b[3]));
;                     }
;                     *(u32x4*)(XL + off) = lo_out;
;                     ss += __shfl_xor(ss, 16); ss += __shfl_xor(ss, 32);
;                     if (fq == 0) SSo[(size_t)(u.pm * 256 + ai * 128 + wr * 64 + m * 16 + fr) * 16 + 4 * u.pn + wc] = ss;
.LBB0_388:
	s_or_b64 exec, exec, s[36:37]
	s_waitcnt vmcnt(9)
	v_cvt_f32_fp8_e32 v18, v70
	s_waitcnt lgkmcnt(0)
	v_cvt_f32_fp8_sdwa v19, v70 src0_sel:BYTE_1
	v_cvt_f32_fp8_e32 v20, v71
	v_cvt_f32_fp8_sdwa v21, v71 src0_sel:BYTE_1
	v_lshlrev_b32_e32 v22, 16, v74
	v_and_b32_e32 v23, 0xffff0000, v74
	v_pk_fma_f32 v[18:19], v[18:19], s[22:23], v[22:23] op_sel_hi:[1,0,1]
	v_lshlrev_b32_e32 v22, 16, v76
	v_and_b32_e32 v23, 0xffff0000, v76
	v_pk_fma_f32 v[20:21], v[20:21], s[22:23], v[22:23] op_sel_hi:[1,0,1]
	v_cvt_f32_fp8_sdwa v22, v70 src0_sel:BYTE_2
	v_cvt_f32_fp8_sdwa v23, v70 src0_sel:BYTE_3
	v_cvt_f32_fp8_sdwa v24, v71 src0_sel:BYTE_2
	v_cvt_f32_fp8_sdwa v25, v71 src0_sel:BYTE_3
	v_lshlrev_b32_e32 v26, 16, v75
	v_and_b32_e32 v27, 0xffff0000, v75
	v_pk_fma_f32 v[22:23], v[22:23], s[22:23], v[26:27] op_sel_hi:[1,0,1]
	v_lshlrev_b32_e32 v26, 16, v77
	v_and_b32_e32 v27, 0xffff0000, v77
	v_pk_fma_f32 v[24:25], v[24:25], s[22:23], v[26:27] op_sel_hi:[1,0,1]
	v_pk_add_f32 v[14:15], v[14:15], v[18:19]
	v_pk_add_f32 v[20:21], v[10:11], v[20:21]
	v_cvt_pk_bf16_f32 v10, v14, v15
	v_pk_add_f32 v[16:17], v[16:17], v[22:23]
	v_pk_add_f32 v[18:19], v[12:13], v[24:25]
	v_cvt_pk_bf16_f32 v11, v16, v17
	v_cvt_pk_bf16_f32 v12, v20, v21
	v_lshlrev_b32_e32 v22, 16, v10
	v_cvt_pk_bf16_f32 v13, v18, v19
	v_mov_b32_e32 v222, v10
	v_mov_b32_e32 v223, v11
	v_mov_b32_e32 v224, v12
	v_mov_b32_e32 v225, v13
	v_sub_f32_e32 v22, v14, v22
	v_mul_f32_e32 v22, 0x45800000, v22
	v_and_b32_e32 v10, 0xffff0000, v10
	v_sub_f32_e32 v10, v15, v10
	v_mul_f32_e32 v10, 0x45800000, v10
	v_med3_f32 v22, v22, s3, v206
	v_med3_f32 v26, v10, s3, v206
	v_mov_b32_e32 v10, v1
	v_lshlrev_b32_e32 v23, 16, v11
	v_and_b32_e32 v11, 0xffff0000, v11
	v_cvt_pk_fp8_f32 v10, v22, v26
	v_sub_f32_e32 v11, v17, v11
	v_sub_f32_e32 v23, v16, v23
	v_mul_f32_e32 v23, 0x45800000, v23
	v_mul_f32_e32 v11, 0x45800000, v11
	v_lshlrev_b32_e32 v24, 16, v12
	v_and_b32_e32 v12, 0xffff0000, v12
	v_med3_f32 v22, v23, s3, v206
	v_med3_f32 v11, v11, s3, v206
	v_lshlrev_b32_e32 v25, 16, v13
	v_cvt_pk_fp8_f32 v10, v22, v11 op_sel:[0,0,1]
	v_sub_f32_e32 v12, v21, v12
	v_sub_f32_e32 v22, v20, v24
	v_sub_f32_e32 v11, v18, v25
	v_mul_f32_e32 v22, 0x45800000, v22
	v_mul_f32_e32 v12, 0x45800000, v12
	v_med3_f32 v22, v22, s3, v206
	v_med3_f32 v12, v12, s3, v206
	v_mul_f32_e32 v23, 0x45800000, v11
	v_mov_b32_e32 v11, v1
	v_and_b32_e32 v13, 0xffff0000, v13
	v_cvt_pk_fp8_f32 v11, v22, v12
	v_sub_f32_e32 v13, v19, v13
	v_mul_f32_e32 v13, 0x45800000, v13
	v_med3_f32 v12, v23, s3, v206
	v_med3_f32 v13, v13, s3, v206
	v_cvt_pk_fp8_f32 v11, v12, v13 op_sel:[0,0,1]
	v_mul_f32_e32 v12, v15, v15
	v_mul_f32_e32 v13, v17, v17
	v_fmac_f32_e32 v12, v14, v14
	v_fmac_f32_e32 v13, v16, v16
	v_add_f32_e32 v12, v12, v13
	v_mul_f32_e32 v13, v21, v21
	v_mul_f32_e32 v14, v19, v19
	v_fmac_f32_e32 v13, v20, v20
	v_fmac_f32_e32 v14, v18, v18
	v_add_f32_e32 v13, v13, v14
	v_add_f32_e32 v22, v12, v13
	v_cvt_f32_fp8_e32 v12, v72
	v_cvt_f32_fp8_sdwa v13, v72 src0_sel:BYTE_1
	v_cvt_f32_fp8_e32 v14, v73
	v_cvt_f32_fp8_sdwa v15, v73 src0_sel:BYTE_1
	v_lshlrev_b32_e32 v16, 16, v66
	v_and_b32_e32 v17, 0xffff0000, v66
	v_pk_fma_f32 v[12:13], v[12:13], s[22:23], v[16:17] op_sel_hi:[1,0,1]
	v_lshlrev_b32_e32 v16, 16, v68
	v_and_b32_e32 v17, 0xffff0000, v68
	v_pk_fma_f32 v[14:15], v[14:15], s[22:23], v[16:17] op_sel_hi:[1,0,1]
	v_cvt_f32_fp8_sdwa v16, v72 src0_sel:BYTE_2
	v_cvt_f32_fp8_sdwa v17, v72 src0_sel:BYTE_3
	v_cvt_f32_fp8_sdwa v18, v73 src0_sel:BYTE_2
	v_cvt_f32_fp8_sdwa v19, v73 src0_sel:BYTE_3
	v_lshlrev_b32_e32 v20, 16, v67
	v_and_b32_e32 v21, 0xffff0000, v67
	v_pk_fma_f32 v[16:17], v[16:17], s[22:23], v[20:21] op_sel_hi:[1,0,1]
	v_lshlrev_b32_e32 v20, 16, v69
	v_and_b32_e32 v21, 0xffff0000, v69
	v_pk_fma_f32 v[18:19], v[18:19], s[22:23], v[20:21] op_sel_hi:[1,0,1]
	v_pk_add_f32 v[8:9], v[8:9], v[16:17]
	v_pk_add_f32 v[16:17], v[6:7], v[12:13]
	v_pk_add_f32 v[18:19], v[4:5], v[18:19]
	v_cvt_pk_bf16_f32 v4, v16, v17
	v_pk_add_f32 v[2:3], v[2:3], v[14:15]
	v_lshlrev_b32_e32 v12, 16, v4
	v_and_b32_e32 v13, 0xffff0000, v4
	v_sub_f32_e32 v12, v16, v12
	v_sub_f32_e32 v13, v17, v13
	v_mul_f32_e32 v12, 0x45800000, v12
	v_med3_f32 v25, v12, s3, v206
	v_mul_f32_e32 v12, 0x45800000, v13
	v_cvt_pk_bf16_f32 v5, v8, v9
	v_med3_f32 v13, v12, s3, v206
	v_lshlrev_b32_e32 v14, 16, v5
	v_mov_b32_e32 v12, v1
	v_and_b32_e32 v15, 0xffff0000, v5
	v_sub_f32_e32 v14, v8, v14
	v_cvt_pk_fp8_f32 v12, v25, v13
	v_sub_f32_e32 v15, v9, v15
	v_mul_f32_e32 v14, 0x45800000, v14
	v_cvt_pk_bf16_f32 v6, v2, v3
	v_med3_f32 v13, v14, s3, v206
	v_lshlrev_b32_e32 v20, 16, v6
	v_and_b32_e32 v21, 0xffff0000, v6
	v_mul_f32_e32 v14, 0x45800000, v15
	v_cvt_pk_bf16_f32 v7, v18, v19
	v_med3_f32 v14, v14, s3, v206
	v_lshlrev_b32_e32 v23, 16, v7
	v_sub_f32_e32 v15, v3, v21
	v_sub_f32_e32 v20, v2, v20
	v_cvt_pk_fp8_f32 v12, v13, v14 op_sel:[0,0,1]
	v_sub_f32_e32 v13, v18, v23
	v_mul_f32_e32 v20, 0x45800000, v20
	v_mul_f32_e32 v15, 0x45800000, v15
	v_med3_f32 v20, v20, s3, v206
	v_med3_f32 v15, v15, s3, v206
	v_mul_f32_e32 v21, 0x45800000, v13
	v_mov_b32_e32 v13, v1
	v_mul_f32_e32 v3, v3, v3
	v_cvt_pk_fp8_f32 v13, v20, v15
	v_mul_f32_e32 v15, v17, v17
	v_mul_f32_e32 v9, v9, v9
	v_fmac_f32_e32 v3, v2, v2
	v_mul_f32_e32 v2, v19, v19
	v_fmac_f32_e32 v15, v16, v16
	v_fmac_f32_e32 v9, v8, v8
	v_fmac_f32_e32 v2, v18, v18
	v_add_f32_e32 v8, v15, v9
	v_add_f32_e32 v2, v3, v2
	v_add_f32_e32 v2, v8, v2
	v_add_f32_e32 v2, v22, v2
	ds_bpermute_b32 v3, v150, v2
	v_and_b32_e32 v24, 0xffff0000, v7
	v_sub_f32_e32 v14, v19, v24
	v_mul_f32_e32 v9, 0x45800000, v14
	v_med3_f32 v8, v21, s3, v206
	s_waitcnt lgkmcnt(0)
	v_add_f32_e32 v2, v2, v3
	ds_bpermute_b32 v3, v151, v2
	v_med3_f32 v9, v9, s3, v206
	v_cvt_pk_fp8_f32 v13, v8, v9 op_sel:[0,0,1]
	s_mov_b64 s[30:31], 0x2c000
	v_lshl_add_u64 v[8:9], v[174:175], 0, s[30:31]
	v_mov_b32_e32 v226, v4
	v_mov_b32_e32 v227, v5
	v_mov_b32_e32 v228, v6
	v_mov_b32_e32 v229, v7
	s_nop 1
	v_permlane16_swap_b32_e32 v222, v226
	v_permlane16_swap_b32_e32 v223, v227
	v_permlane16_swap_b32_e32 v224, v228
	v_permlane16_swap_b32_e32 v225, v229
	v_permlane32_swap_b32_e32 v222, v226
	v_permlane32_swap_b32_e32 v223, v227
	v_permlane32_swap_b32_e32 v224, v228
	v_permlane32_swap_b32_e32 v225, v229
	v_lshl_add_u64 v[230:231], v[90:91], 0, v[232:233]
	global_store_dwordx4 v[230:231], v[222:225], off
	global_store_dwordx4 v[230:231], v[226:229], off offset:64
	global_store_dwordx4 v[8:9], v[10:13], off
	s_and_saveexec_b64 s[36:37], s[40:41]
	s_cbranch_execz .LBB0_390
	s_waitcnt lgkmcnt(0)
	v_add_f32_e32 v4, v2, v3
	v_add_u32_e32 v2, 0xb0, v172
	v_ashrrev_i32_e32 v3, 31, v2
	v_readlane_b32 s30, v255, 23
	v_lshlrev_b64 v[2:3], 6, v[2:3]
	v_readlane_b32 s31, v255, 24
	s_lshl_b32 s24, s58, 2
	s_nop 0
	v_lshl_add_u64 v[2:3], s[30:31], 0, v[2:3]
	v_lshl_add_u64 v[2:3], s[52:53], 2, v[2:3]
	v_lshl_add_u64 v[2:3], v[2:3], 0, s[24:25]
	global_store_dword v[2:3], v4, off
